# deleted the 36 redundant s_waitcnt lgkmcnt(0) between s_setprio 1 and the first MFMA of each GEMM block (an lgkmcnt(0) already precedes the barrier)
# baseline (speedup 1.0000x reference)
; #define PG8_STAGE(bufoff, gbase, voff) do { _Pragma("unroll") for (int _i = 0; _i < 2; ++_i) \
;         __builtin_amdgcn_global_load_lds((const unsigned*)((const char*)(gbase) + (voff)[_i]), (PG8_LAS unsigned*)(lds + (bufoff) + ldsw + _i * 8192), 16, 0, 0); } while (0)
; #define PG8_LDA(dst, b, h) do { _Pragma("unroll") for (int m = 0; m < 4; ++m) _Pragma("unroll") for (int k = 0; k < 2; ++k) dst[m][k] = *(const PG8_LAS bf16x8*)(lds + PG8_SA(b, h) + aoff + m * 2048 + k * 1024); } while (0)
; #define PG8_LDB(dst, b, h) do { _Pragma("unroll") for (int n = 0; n < 2; ++n) _Pragma("unroll") for (int k = 0; k < 2; ++k) dst[n][k] = *(const PG8_LAS bf16x8*)(lds + PG8_SB(b, h) + boff + n * 2048 + k * 1024); } while (0)
; #define PG8_MMA(ai, bj, At, Bt) do { __builtin_amdgcn_s_setprio(1); _Pragma("unroll") for (int m = 0; m < 4; ++m) _Pragma("unroll") for (int n = 0; n < 2; ++n) _Pragma("unroll") for (int k = 0; k < 2; ++k) \
;         acc[ai][bj][m][n] = __builtin_amdgcn_mfma_f32_16x16x32_bf16(Bt[n][k], At[m][k], acc[ai][bj][m][n], 0, 0, 0); __builtin_amdgcn_s_setprio(0); } while (0)
; #define PG8_WAIT_V(n) asm volatile("s_waitcnt vmcnt(" #n ")" ::: "memory")
; #define PG8_WAIT_L(n) asm volatile("s_waitcnt lgkmcnt(" #n ")" ::: "memory")
; #define PG8_BAR __builtin_amdgcn_s_barrier()
; #define PG8_SCHED __builtin_amdgcn_sched_barrier(0)
; template <class Epi, class Sched, bool ALIGN_EPI = false, bool SP2 = false>
; __device__ __forceinline__ void gemm_phase(PG8_LAS unsigned char* lds, const Gemm g, const Sched& S, const Epi& E) {
;     ...
;         for (int t = 0; t < nt; t += 2) {
;             const bool last = (t == nt - 2);
;             const char* a1 = cA + (size_t)(t + 1) * kstep;
;             const char* a2 = last ? nA : cA + (size_t)(t + 2) * kstep; const char* b2 = last ? nB : cB + (size_t)(t + 2) * kstep;
;             const char* a3 = a2 + kstep; const char* b3 = b2 + kstep;
;             if (last && has_next) S.a_ready(nxt);
;             if constexpr (SP2) {
;             PG8_LDB(B0, 0, 0); PG8_LDB(B1, 0, 1); PG8_SCHED; PG8_LDA(At, 0, 0); PG8_STAGE(PG8_SA(1, 1), a1 + hstep, voffA);
;             PG8_WAIT_V(8); PG8_WAIT_L(0); PG8_BAR; PG8_MMA(0, 0, At, B0); PG8_MMA(0, 1, At, B1); PG8_BAR; PG8_SCHED;
;             PG8_LDA(At, 0, 1); PG8_STAGE(PG8_SB(0, 0), b2, voffB); PG8_STAGE(PG8_SB(0, 1), b2 + hstep, voffB); PG8_STAGE(PG8_SA(0, 0), a2, voffA);
.LBB0_116:
	ds_read_b128 v[150:153], v147
	ds_read_b128 v[154:157], v147 offset:1024
	ds_read_b128 v[158:161], v147 offset:2048
	ds_read_b128 v[174:177], v147 offset:3072
	ds_read_b128 v[178:181], v148
	ds_read_b128 v[182:185], v148 offset:1024
	ds_read_b128 v[186:189], v148 offset:2048
	ds_read_b128 v[190:193], v148 offset:3072
	s_add_i32 s55, s54, 2
	s_add_u32 s28, s0, 0xfff80080
	s_addc_u32 s29, s1, -1
	s_cmp_eq_u32 s50, s54
	s_cselect_b32 s31, s21, s29
	s_cselect_b32 s30, s48, s28
	s_cselect_b32 s29, s19, s53
	s_cselect_b32 s28, s49, s51
	v_lshl_add_u64 v[138:139], s[0:1], 0, v[130:131]
	s_add_i32 m0, s27, 0xc000
	ds_read_b128 v[194:197], v149
	ds_read_b128 v[198:201], v149 offset:1024
	ds_read_b128 v[202:205], v149 offset:2048
	ds_read_b128 v[206:209], v149 offset:3072
	ds_read_b128 v[210:213], v149 offset:4096
	ds_read_b128 v[224:227], v149 offset:5120
	ds_read_b128 v[232:235], v149 offset:6144
	ds_read_b128 v[236:239], v149 offset:7168
	global_load_lds_dwordx4 v[138:139], off
	v_lshl_add_u64 v[138:139], s[0:1], 0, v[132:133]
	s_add_i32 m0, s27, 0xe000
	s_nop 0
	global_load_lds_dwordx4 v[138:139], off
	s_waitcnt vmcnt(8)
	s_waitcnt lgkmcnt(0)
	s_barrier
	s_setprio 1
	v_mfma_f32_16x16x32_bf16 v[126:129], v[150:153], v[194:197], v[126:129]
	v_mfma_f32_16x16x32_bf16 v[122:125], v[158:161], v[194:197], v[122:125]
	v_mfma_f32_16x16x32_bf16 v[110:113], v[150:153], v[202:205], v[110:113]
	v_mfma_f32_16x16x32_bf16 v[106:109], v[158:161], v[202:205], v[106:109]
	v_mfma_f32_16x16x32_bf16 v[94:97], v[150:153], v[210:213], v[94:97]
	v_mfma_f32_16x16x32_bf16 v[90:93], v[158:161], v[210:213], v[90:93]
	v_mfma_f32_16x16x32_bf16 v[78:81], v[150:153], v[232:235], v[78:81]
	v_mfma_f32_16x16x32_bf16 v[74:77], v[158:161], v[232:235], v[74:77]
	v_mfma_f32_16x16x32_bf16 v[126:129], v[154:157], v[198:201], v[126:129]
	v_mfma_f32_16x16x32_bf16 v[122:125], v[174:177], v[198:201], v[122:125]
	v_mfma_f32_16x16x32_bf16 v[110:113], v[154:157], v[206:209], v[110:113]
	v_mfma_f32_16x16x32_bf16 v[106:109], v[174:177], v[206:209], v[106:109]
	v_mfma_f32_16x16x32_bf16 v[94:97], v[154:157], v[224:227], v[94:97]
	v_mfma_f32_16x16x32_bf16 v[90:93], v[174:177], v[224:227], v[90:93]
	v_mfma_f32_16x16x32_bf16 v[78:81], v[154:157], v[236:239], v[78:81]
	v_mfma_f32_16x16x32_bf16 v[74:77], v[174:177], v[236:239], v[74:77]
	v_mfma_f32_16x16x32_bf16 v[118:121], v[178:181], v[194:197], v[118:121]
	v_mfma_f32_16x16x32_bf16 v[114:117], v[186:189], v[194:197], v[114:117]
	v_mfma_f32_16x16x32_bf16 v[102:105], v[178:181], v[202:205], v[102:105]
	v_mfma_f32_16x16x32_bf16 v[98:101], v[186:189], v[202:205], v[98:101]
	v_mfma_f32_16x16x32_bf16 v[86:89], v[178:181], v[210:213], v[86:89]
	v_mfma_f32_16x16x32_bf16 v[82:85], v[186:189], v[210:213], v[82:85]
	v_mfma_f32_16x16x32_bf16 v[70:73], v[178:181], v[232:235], v[70:73]
	v_mfma_f32_16x16x32_bf16 v[66:69], v[186:189], v[232:235], v[66:69]
	v_mfma_f32_16x16x32_bf16 v[118:121], v[182:185], v[198:201], v[118:121]
	v_mfma_f32_16x16x32_bf16 v[114:117], v[190:193], v[198:201], v[114:117]
	v_mfma_f32_16x16x32_bf16 v[102:105], v[182:185], v[206:209], v[102:105]
	v_mfma_f32_16x16x32_bf16 v[98:101], v[190:193], v[206:209], v[98:101]
	v_mfma_f32_16x16x32_bf16 v[86:89], v[182:185], v[224:227], v[86:89]
	v_mfma_f32_16x16x32_bf16 v[82:85], v[190:193], v[224:227], v[82:85]
	v_mfma_f32_16x16x32_bf16 v[70:73], v[182:185], v[236:239], v[70:73]
	v_mfma_f32_16x16x32_bf16 v[66:69], v[190:193], v[236:239], v[66:69]
	s_setprio 0
	s_barrier
	s_add_i32 s54, s42, s2
	v_lshl_add_u64 v[138:139], s[28:29], 0, v[168:169]
	s_mov_b32 m0, s54
	ds_read_b128 v[194:197], v149 offset:16384
	ds_read_b128 v[198:201], v149 offset:17408
	ds_read_b128 v[202:205], v149 offset:18432
	ds_read_b128 v[206:209], v149 offset:19456
	ds_read_b128 v[210:213], v149 offset:20480
	ds_read_b128 v[224:227], v149 offset:21504
	ds_read_b128 v[232:235], v149 offset:22528
	ds_read_b128 v[236:239], v149 offset:23552
	global_load_lds_dwordx4 v[138:139], off
	s_add_i32 m0, s54, 0x2000
	s_add_u32 s56, s28, 0x80000
	v_lshl_add_u64 v[240:241], s[28:29], 0, v[172:173]
	s_addc_u32 s57, s29, 0
	s_add_i32 s54, s43, s2
	global_load_lds_dwordx4 v[240:241], off
	v_lshl_add_u64 v[242:243], s[56:57], 0, v[168:169]
	s_mov_b32 m0, s54
	v_lshl_add_u64 v[244:245], s[30:31], 0, v[170:171]
	global_load_lds_dwordx4 v[242:243], off
	v_lshl_add_u64 v[242:243], s[56:57], 0, v[172:173]
	s_add_i32 m0, s54, 0x2000
	s_nop 0
	global_load_lds_dwordx4 v[242:243], off
	v_lshl_add_u64 v[242:243], s[30:31], 0, v[166:167]
	s_mov_b32 m0, s27
	s_nop 0
	global_load_lds_dwordx4 v[242:243], off
	s_mov_b32 m0, s34
	s_nop 0
	global_load_lds_dwordx4 v[244:245], off
	s_waitcnt vmcnt(8)
	s_waitcnt lgkmcnt(0)
	s_barrier
; #define PG8_STAGE(bufoff, gbase, voff) do { _Pragma("unroll") for (int _i = 0; _i < 2; ++_i) \
;         __builtin_amdgcn_global_load_lds((const unsigned*)((const char*)(gbase) + (voff)[_i]), (PG8_LAS unsigned*)(lds + (bufoff) + ldsw + _i * 8192), 16, 0, 0); } while (0)
; #define PG8_LDA(dst, b, h) do { _Pragma("unroll") for (int m = 0; m < 4; ++m) _Pragma("unroll") for (int k = 0; k < 2; ++k) dst[m][k] = *(const PG8_LAS bf16x8*)(lds + PG8_SA(b, h) + aoff + m * 2048 + k * 1024); } while (0)
; #define PG8_LDB(dst, b, h) do { _Pragma("unroll") for (int n = 0; n < 2; ++n) _Pragma("unroll") for (int k = 0; k < 2; ++k) dst[n][k] = *(const PG8_LAS bf16x8*)(lds + PG8_SB(b, h) + boff + n * 2048 + k * 1024); } while (0)
; #define PG8_MMA(ai, bj, At, Bt) do { __builtin_amdgcn_s_setprio(1); _Pragma("unroll") for (int m = 0; m < 4; ++m) _Pragma("unroll") for (int n = 0; n < 2; ++n) _Pragma("unroll") for (int k = 0; k < 2; ++k) \
;         acc[ai][bj][m][n] = __builtin_amdgcn_mfma_f32_16x16x32_bf16(Bt[n][k], At[m][k], acc[ai][bj][m][n], 0, 0, 0); __builtin_amdgcn_s_setprio(0); } while (0)
; #define PG8_WAIT_V(n) asm volatile("s_waitcnt vmcnt(" #n ")" ::: "memory")
; #define PG8_WAIT_L(n) asm volatile("s_waitcnt lgkmcnt(" #n ")" ::: "memory")
; #define PG8_BAR __builtin_amdgcn_s_barrier()
; #define PG8_SCHED __builtin_amdgcn_sched_barrier(0)
; template <class Epi, class Sched, bool ALIGN_EPI = false, bool SP2 = false>
; __device__ __forceinline__ void gemm_phase(PG8_LAS unsigned char* lds, const Gemm g, const Sched& S, const Epi& E) {
;     ...
;             PG8_WAIT_V(8); PG8_WAIT_L(0); PG8_BAR; PG8_MMA(1, 0, At, B0); PG8_MMA(1, 1, At, B1); PG8_BAR; PG8_SCHED;
;             PG8_LDB(B0, 1, 0); PG8_LDB(B1, 1, 1); PG8_SCHED; PG8_LDA(At, 1, 0); PG8_STAGE(PG8_SA(0, 1), a2 + hstep, voffA);
;             PG8_WAIT_V(8); PG8_WAIT_L(0); PG8_BAR; PG8_MMA(0, 0, At, B0); PG8_MMA(0, 1, At, B1); PG8_BAR; PG8_SCHED;
	s_setprio 1
	v_mfma_f32_16x16x32_bf16 v[62:65], v[150:153], v[194:197], v[62:65]
	v_mfma_f32_16x16x32_bf16 v[58:61], v[158:161], v[194:197], v[58:61]
	v_mfma_f32_16x16x32_bf16 v[46:49], v[150:153], v[202:205], v[46:49]
	v_mfma_f32_16x16x32_bf16 v[42:45], v[158:161], v[202:205], v[42:45]
	v_mfma_f32_16x16x32_bf16 v[30:33], v[150:153], v[210:213], v[30:33]
	v_mfma_f32_16x16x32_bf16 v[26:29], v[158:161], v[210:213], v[26:29]
	v_mfma_f32_16x16x32_bf16 v[14:17], v[150:153], v[232:235], v[14:17]
	v_mfma_f32_16x16x32_bf16 v[10:13], v[158:161], v[232:235], v[10:13]
	v_mfma_f32_16x16x32_bf16 v[62:65], v[154:157], v[198:201], v[62:65]
	v_mfma_f32_16x16x32_bf16 v[58:61], v[174:177], v[198:201], v[58:61]
	v_mfma_f32_16x16x32_bf16 v[46:49], v[154:157], v[206:209], v[46:49]
	v_mfma_f32_16x16x32_bf16 v[42:45], v[174:177], v[206:209], v[42:45]
	v_mfma_f32_16x16x32_bf16 v[30:33], v[154:157], v[224:227], v[30:33]
	v_mfma_f32_16x16x32_bf16 v[26:29], v[174:177], v[224:227], v[26:29]
	v_mfma_f32_16x16x32_bf16 v[14:17], v[154:157], v[236:239], v[14:17]
	v_mfma_f32_16x16x32_bf16 v[10:13], v[174:177], v[236:239], v[10:13]
	v_mfma_f32_16x16x32_bf16 v[54:57], v[178:181], v[194:197], v[54:57]
	v_mfma_f32_16x16x32_bf16 v[50:53], v[186:189], v[194:197], v[50:53]
	v_mfma_f32_16x16x32_bf16 v[38:41], v[178:181], v[202:205], v[38:41]
	v_mfma_f32_16x16x32_bf16 v[34:37], v[186:189], v[202:205], v[34:37]
	v_mfma_f32_16x16x32_bf16 v[22:25], v[178:181], v[210:213], v[22:25]
	v_mfma_f32_16x16x32_bf16 v[18:21], v[186:189], v[210:213], v[18:21]
	v_mfma_f32_16x16x32_bf16 v[6:9], v[178:181], v[232:235], v[6:9]
	v_mfma_f32_16x16x32_bf16 v[2:5], v[186:189], v[232:235], v[2:5]
	v_mfma_f32_16x16x32_bf16 v[54:57], v[182:185], v[198:201], v[54:57]
	v_mfma_f32_16x16x32_bf16 v[50:53], v[190:193], v[198:201], v[50:53]
	v_mfma_f32_16x16x32_bf16 v[38:41], v[182:185], v[206:209], v[38:41]
	v_mfma_f32_16x16x32_bf16 v[34:37], v[190:193], v[206:209], v[34:37]
	v_mfma_f32_16x16x32_bf16 v[22:25], v[182:185], v[224:227], v[22:25]
	v_mfma_f32_16x16x32_bf16 v[18:21], v[190:193], v[224:227], v[18:21]
	v_mfma_f32_16x16x32_bf16 v[6:9], v[182:185], v[236:239], v[6:9]
	v_mfma_f32_16x16x32_bf16 v[2:5], v[190:193], v[236:239], v[2:5]
	s_setprio 0
	s_barrier
	s_add_i32 s54, 0, 0x18000
	s_add_i32 s56, 0, 0x1c000
	v_add_u32_e32 v174, s54, v145
	v_add_u32_e32 v190, s56, v145
	ds_read_b128 v[150:153], v174
	ds_read_b128 v[154:157], v174 offset:1024
	ds_read_b128 v[158:161], v174 offset:2048
	ds_read_b128 v[174:177], v174 offset:3072
	ds_read_b128 v[178:181], v190
	ds_read_b128 v[182:185], v190 offset:1024
	ds_read_b128 v[186:189], v190 offset:2048
	ds_read_b128 v[190:193], v190 offset:3072
	s_add_u32 s30, s30, 0x80000
	s_addc_u32 s31, s31, 0
	s_mov_b32 m0, s35
	v_lshl_add_u64 v[246:247], s[30:31], 0, v[166:167]
	ds_read_b128 v[194:197], v149 offset:32768
	ds_read_b128 v[198:201], v149 offset:33792
	ds_read_b128 v[202:205], v149 offset:34816
	ds_read_b128 v[206:209], v149 offset:35840
	ds_read_b128 v[210:213], v149 offset:36864
	ds_read_b128 v[224:227], v149 offset:37888
	ds_read_b128 v[232:235], v149 offset:38912
	ds_read_b128 v[236:239], v149 offset:39936
	global_load_lds_dwordx4 v[246:247], off
	v_lshl_add_u64 v[246:247], s[30:31], 0, v[170:171]
	s_mov_b32 m0, s36
	s_nop 0
	global_load_lds_dwordx4 v[246:247], off
	s_waitcnt vmcnt(8)
	s_waitcnt lgkmcnt(0)
	s_barrier
	s_setprio 1
	v_mfma_f32_16x16x32_bf16 v[126:129], v[150:153], v[194:197], v[126:129]
	v_mfma_f32_16x16x32_bf16 v[122:125], v[158:161], v[194:197], v[122:125]
	v_mfma_f32_16x16x32_bf16 v[110:113], v[150:153], v[202:205], v[110:113]
	v_mfma_f32_16x16x32_bf16 v[106:109], v[158:161], v[202:205], v[106:109]
	v_mfma_f32_16x16x32_bf16 v[94:97], v[150:153], v[210:213], v[94:97]
	v_mfma_f32_16x16x32_bf16 v[90:93], v[158:161], v[210:213], v[90:93]
	v_mfma_f32_16x16x32_bf16 v[78:81], v[150:153], v[232:235], v[78:81]
	v_mfma_f32_16x16x32_bf16 v[74:77], v[158:161], v[232:235], v[74:77]
	v_mfma_f32_16x16x32_bf16 v[126:129], v[154:157], v[198:201], v[126:129]
	v_mfma_f32_16x16x32_bf16 v[122:125], v[174:177], v[198:201], v[122:125]
	v_mfma_f32_16x16x32_bf16 v[110:113], v[154:157], v[206:209], v[110:113]
	v_mfma_f32_16x16x32_bf16 v[106:109], v[174:177], v[206:209], v[106:109]
	v_mfma_f32_16x16x32_bf16 v[94:97], v[154:157], v[224:227], v[94:97]
	v_mfma_f32_16x16x32_bf16 v[90:93], v[174:177], v[224:227], v[90:93]
	v_mfma_f32_16x16x32_bf16 v[78:81], v[154:157], v[236:239], v[78:81]
	v_mfma_f32_16x16x32_bf16 v[74:77], v[174:177], v[236:239], v[74:77]
	v_mfma_f32_16x16x32_bf16 v[118:121], v[178:181], v[194:197], v[118:121]
	v_mfma_f32_16x16x32_bf16 v[114:117], v[186:189], v[194:197], v[114:117]
	v_mfma_f32_16x16x32_bf16 v[102:105], v[178:181], v[202:205], v[102:105]
	v_mfma_f32_16x16x32_bf16 v[98:101], v[186:189], v[202:205], v[98:101]
	v_mfma_f32_16x16x32_bf16 v[86:89], v[178:181], v[210:213], v[86:89]
	v_mfma_f32_16x16x32_bf16 v[82:85], v[186:189], v[210:213], v[82:85]
	v_mfma_f32_16x16x32_bf16 v[70:73], v[178:181], v[232:235], v[70:73]
	v_mfma_f32_16x16x32_bf16 v[66:69], v[186:189], v[232:235], v[66:69]
	v_mfma_f32_16x16x32_bf16 v[118:121], v[182:185], v[198:201], v[118:121]
	v_mfma_f32_16x16x32_bf16 v[114:117], v[190:193], v[198:201], v[114:117]
	v_mfma_f32_16x16x32_bf16 v[102:105], v[182:185], v[206:209], v[102:105]
	v_mfma_f32_16x16x32_bf16 v[98:101], v[190:193], v[206:209], v[98:101]
	v_mfma_f32_16x16x32_bf16 v[86:89], v[182:185], v[224:227], v[86:89]
	v_mfma_f32_16x16x32_bf16 v[82:85], v[190:193], v[224:227], v[82:85]
	v_mfma_f32_16x16x32_bf16 v[70:73], v[182:185], v[236:239], v[70:73]
	v_mfma_f32_16x16x32_bf16 v[66:69], v[190:193], v[236:239], v[66:69]
	s_setprio 0
	s_barrier
; #define PG8_STAGE(bufoff, gbase, voff) do { _Pragma("unroll") for (int _i = 0; _i < 2; ++_i) \
;         __builtin_amdgcn_global_load_lds((const unsigned*)((const char*)(gbase) + (voff)[_i]), (PG8_LAS unsigned*)(lds + (bufoff) + ldsw + _i * 8192), 16, 0, 0); } while (0)
; #define PG8_LDA(dst, b, h) do { _Pragma("unroll") for (int m = 0; m < 4; ++m) _Pragma("unroll") for (int k = 0; k < 2; ++k) dst[m][k] = *(const PG8_LAS bf16x8*)(lds + PG8_SA(b, h) + aoff + m * 2048 + k * 1024); } while (0)
; #define PG8_MMA(ai, bj, At, Bt) do { __builtin_amdgcn_s_setprio(1); _Pragma("unroll") for (int m = 0; m < 4; ++m) _Pragma("unroll") for (int n = 0; n < 2; ++n) _Pragma("unroll") for (int k = 0; k < 2; ++k) \
;         acc[ai][bj][m][n] = __builtin_amdgcn_mfma_f32_16x16x32_bf16(Bt[n][k], At[m][k], acc[ai][bj][m][n], 0, 0, 0); __builtin_amdgcn_s_setprio(0); } while (0)
; #define PG8_WAIT_V(n) asm volatile("s_waitcnt vmcnt(" #n ")" ::: "memory")
; #define PG8_WAIT_L(n) asm volatile("s_waitcnt lgkmcnt(" #n ")" ::: "memory")
; #define PG8_BAR __builtin_amdgcn_s_barrier()
; #define PG8_SCHED __builtin_amdgcn_sched_barrier(0)
; template <class Epi, class Sched, bool ALIGN_EPI = false, bool SP2 = false>
; __device__ __forceinline__ void gemm_phase(PG8_LAS unsigned char* lds, const Gemm g, const Sched& S, const Epi& E) {
;     ...
;             PG8_LDA(At, 1, 1); PG8_STAGE(PG8_SB(1, 0), b3, voffB); PG8_STAGE(PG8_SB(1, 1), b3 + hstep, voffB); PG8_STAGE(PG8_SA(1, 0), a3, voffA);
;             PG8_WAIT_V(8); PG8_WAIT_L(0); PG8_BAR; PG8_MMA(1, 0, At, B0); PG8_MMA(1, 1, At, B1); PG8_BAR; PG8_SCHED;
;     ...
;         }
;         if constexpr (ALIGN_EPI) { if (wr == 0) PG8_BAR; }
	s_add_i32 s30, s54, s2
	v_lshl_add_u64 v[138:139], v[138:139], 0, s[14:15]
	s_mov_b32 m0, s30
	ds_read_b128 v[194:197], v149 offset:49152
	ds_read_b128 v[198:201], v149 offset:50176
	ds_read_b128 v[202:205], v149 offset:51200
	ds_read_b128 v[206:209], v149 offset:52224
	ds_read_b128 v[210:213], v149 offset:53248
	ds_read_b128 v[224:227], v149 offset:54272
	ds_read_b128 v[232:235], v149 offset:55296
	ds_read_b128 v[236:239], v149 offset:56320
	global_load_lds_dwordx4 v[138:139], off
	s_add_i32 m0, s30, 0x2000
	s_add_u32 s28, s28, 0x80080
	v_lshl_add_u64 v[138:139], v[240:241], 0, s[14:15]
	s_addc_u32 s29, s29, 0
	s_add_i32 s30, s56, s2
	global_load_lds_dwordx4 v[138:139], off
	v_lshl_add_u64 v[138:139], s[28:29], 0, v[168:169]
	s_mov_b32 m0, s30
	s_nop 0
	global_load_lds_dwordx4 v[138:139], off
	v_lshl_add_u64 v[138:139], s[28:29], 0, v[172:173]
	s_add_i32 m0, s30, 0x2000
	s_nop 0
	global_load_lds_dwordx4 v[138:139], off
	v_lshl_add_u64 v[138:139], v[242:243], 0, s[14:15]
	s_mov_b32 m0, s38
	s_nop 0
	global_load_lds_dwordx4 v[138:139], off
	v_lshl_add_u64 v[138:139], v[244:245], 0, s[14:15]
	s_mov_b32 m0, s39
	s_nop 0
	global_load_lds_dwordx4 v[138:139], off
	s_waitcnt vmcnt(8)
	s_waitcnt lgkmcnt(0)
	s_barrier
	s_setprio 1
	v_mfma_f32_16x16x32_bf16 v[62:65], v[150:153], v[194:197], v[62:65]
	v_mfma_f32_16x16x32_bf16 v[58:61], v[158:161], v[194:197], v[58:61]
	v_mfma_f32_16x16x32_bf16 v[46:49], v[150:153], v[202:205], v[46:49]
	v_mfma_f32_16x16x32_bf16 v[42:45], v[158:161], v[202:205], v[42:45]
	v_mfma_f32_16x16x32_bf16 v[30:33], v[150:153], v[210:213], v[30:33]
	v_mfma_f32_16x16x32_bf16 v[26:29], v[158:161], v[210:213], v[26:29]
	v_mfma_f32_16x16x32_bf16 v[14:17], v[150:153], v[232:235], v[14:17]
	v_mfma_f32_16x16x32_bf16 v[10:13], v[158:161], v[232:235], v[10:13]
	v_mfma_f32_16x16x32_bf16 v[62:65], v[154:157], v[198:201], v[62:65]
	v_mfma_f32_16x16x32_bf16 v[58:61], v[174:177], v[198:201], v[58:61]
	v_mfma_f32_16x16x32_bf16 v[46:49], v[154:157], v[206:209], v[46:49]
	v_mfma_f32_16x16x32_bf16 v[42:45], v[174:177], v[206:209], v[42:45]
	v_mfma_f32_16x16x32_bf16 v[30:33], v[154:157], v[224:227], v[30:33]
	v_mfma_f32_16x16x32_bf16 v[26:29], v[174:177], v[224:227], v[26:29]
	v_mfma_f32_16x16x32_bf16 v[14:17], v[154:157], v[236:239], v[14:17]
	v_mfma_f32_16x16x32_bf16 v[10:13], v[174:177], v[236:239], v[10:13]
	v_mfma_f32_16x16x32_bf16 v[54:57], v[178:181], v[194:197], v[54:57]
	v_mfma_f32_16x16x32_bf16 v[50:53], v[186:189], v[194:197], v[50:53]
	v_mfma_f32_16x16x32_bf16 v[38:41], v[178:181], v[202:205], v[38:41]
	v_mfma_f32_16x16x32_bf16 v[34:37], v[186:189], v[202:205], v[34:37]
	v_mfma_f32_16x16x32_bf16 v[22:25], v[178:181], v[210:213], v[22:25]
	v_mfma_f32_16x16x32_bf16 v[18:21], v[186:189], v[210:213], v[18:21]
	v_mfma_f32_16x16x32_bf16 v[6:9], v[178:181], v[232:235], v[6:9]
	v_mfma_f32_16x16x32_bf16 v[2:5], v[186:189], v[232:235], v[2:5]
	v_mfma_f32_16x16x32_bf16 v[54:57], v[182:185], v[198:201], v[54:57]
	v_mfma_f32_16x16x32_bf16 v[50:53], v[190:193], v[198:201], v[50:53]
	v_mfma_f32_16x16x32_bf16 v[38:41], v[182:185], v[206:209], v[38:41]
	v_mfma_f32_16x16x32_bf16 v[34:37], v[190:193], v[206:209], v[34:37]
	v_mfma_f32_16x16x32_bf16 v[22:25], v[182:185], v[224:227], v[22:25]
	v_mfma_f32_16x16x32_bf16 v[18:21], v[190:193], v[224:227], v[18:21]
	v_mfma_f32_16x16x32_bf16 v[6:9], v[182:185], v[236:239], v[6:9]
	v_mfma_f32_16x16x32_bf16 v[2:5], v[190:193], v[236:239], v[2:5]
	s_setprio 0
	s_barrier
	s_add_u32 s0, s0, 0x100
	s_addc_u32 s1, s1, 0
	s_add_u32 s51, s51, 0x100
	s_addc_u32 s53, s53, 0
	s_cmp_ge_u32 s55, s47
	s_mov_b32 s54, s55
	s_cbranch_scc0 .LBB0_116
	s_and_b64 vcc, exec, s[16:17]
	s_cbranch_vccz .LBB0_119
	s_barrier

; #define PG8_STAGE(bufoff, gbase, voff) do { _Pragma("unroll") for (int _i = 0; _i < 2; ++_i) \
;         __builtin_amdgcn_global_load_lds((const unsigned*)((const char*)(gbase) + (voff)[_i]), (PG8_LAS unsigned*)(lds + (bufoff) + ldsw + _i * 8192), 16, 0, 0); } while (0)
; #define PG8_LDA(dst, b, h) do { _Pragma("unroll") for (int m = 0; m < 4; ++m) _Pragma("unroll") for (int k = 0; k < 2; ++k) dst[m][k] = *(const PG8_LAS bf16x8*)(lds + PG8_SA(b, h) + aoff + m * 2048 + k * 1024); } while (0)
; #define PG8_LDB(dst, b, h) do { _Pragma("unroll") for (int n = 0; n < 2; ++n) _Pragma("unroll") for (int k = 0; k < 2; ++k) dst[n][k] = *(const PG8_LAS bf16x8*)(lds + PG8_SB(b, h) + boff + n * 2048 + k * 1024); } while (0)
; #define PG8_MMA(ai, bj, At, Bt) do { __builtin_amdgcn_s_setprio(1); _Pragma("unroll") for (int m = 0; m < 4; ++m) _Pragma("unroll") for (int n = 0; n < 2; ++n) _Pragma("unroll") for (int k = 0; k < 2; ++k) \
;         acc[ai][bj][m][n] = __builtin_amdgcn_mfma_f32_16x16x32_bf16(Bt[n][k], At[m][k], acc[ai][bj][m][n], 0, 0, 0); __builtin_amdgcn_s_setprio(0); } while (0)
; #define PG8_WAIT_V(n) asm volatile("s_waitcnt vmcnt(" #n ")" ::: "memory")
; #define PG8_BAR __builtin_amdgcn_s_barrier()
; template <class Epi, class Sched, bool ALIGN_EPI = false, bool SP2 = false>
; __device__ __forceinline__ void gemm_phase(PG8_LAS unsigned char* lds, const Gemm g, const Sched& S, const Epi& E) {
;     ...
;         for (int t = 0; t < nt; t += 2) {
;             const bool last = (t == nt - 2);
;             const char* a1 = cA + (size_t)(t + 1) * kstep;
;             const char* a2 = last ? nA : cA + (size_t)(t + 2) * kstep; const char* b2 = last ? nB : cB + (size_t)(t + 2) * kstep;
;             const char* a3 = a2 + kstep; const char* b3 = b2 + kstep;
;             if (last && has_next) S.a_ready(nxt);
;             if constexpr (SP2) {
;             PG8_LDB(B0, 0, 0); PG8_LDB(B1, 0, 1); PG8_SCHED; PG8_LDA(At, 0, 0); PG8_STAGE(PG8_SA(1, 1), a1 + hstep, voffA);
;             PG8_WAIT_V(8); PG8_WAIT_L(0); PG8_BAR; PG8_MMA(0, 0, At, B0); PG8_MMA(0, 1, At, B1); PG8_BAR; PG8_SCHED;
;             PG8_LDA(At, 0, 1); PG8_STAGE(PG8_SB(0, 0), b2, voffB); PG8_STAGE(PG8_SB(0, 1), b2 + hstep, voffB); PG8_STAGE(PG8_SA(0, 0), a2, voffA);
;             PG8_WAIT_V(8); PG8_WAIT_L(0); PG8_BAR; PG8_MMA(1, 0, At, B0); PG8_MMA(1, 1, At, B1); PG8_BAR; PG8_SCHED;
.LBB0_281:
	ds_read_b128 v[136:139], v146
	ds_read_b128 v[150:153], v146 offset:1024
	ds_read_b128 v[154:157], v146 offset:2048
	ds_read_b128 v[158:161], v146 offset:3072
	ds_read_b128 v[178:181], v147
	ds_read_b128 v[182:185], v147 offset:1024
	ds_read_b128 v[186:189], v147 offset:2048
	ds_read_b128 v[190:193], v147 offset:3072
	s_add_i32 s54, s24, 2
	s_add_u32 s25, s22, 0xffea0080
	s_addc_u32 s26, s23, -1
	s_cmp_eq_u32 s50, s24
	s_cselect_b32 s24, s20, s51
	s_cselect_b32 s27, s19, s26
	s_cselect_b32 s26, s18, s25
	s_cselect_b32 s25, s21, s53
	v_lshl_add_u64 v[244:245], s[22:23], 0, v[130:131]
	s_add_i32 m0, s3, 0xc000
	ds_read_b128 v[194:197], v148
	ds_read_b128 v[198:201], v148 offset:1024
	ds_read_b128 v[202:205], v148 offset:2048
	ds_read_b128 v[206:209], v148 offset:3072
	ds_read_b128 v[210:213], v148 offset:4096
	ds_read_b128 v[232:235], v148 offset:5120
	ds_read_b128 v[236:239], v148 offset:6144
	ds_read_b128 v[240:243], v148 offset:7168
	global_load_lds_dwordx4 v[244:245], off
	v_lshl_add_u64 v[244:245], s[22:23], 0, v[132:133]
	s_add_i32 m0, s3, 0xe000
	s_nop 0
	global_load_lds_dwordx4 v[244:245], off
	s_waitcnt vmcnt(8)
	s_waitcnt lgkmcnt(0)
	s_barrier
	s_setprio 1
	v_mfma_f32_16x16x32_bf16 v[126:129], v[136:139], v[194:197], v[126:129]
	v_mfma_f32_16x16x32_bf16 v[122:125], v[154:157], v[194:197], v[122:125]
	v_mfma_f32_16x16x32_bf16 v[118:121], v[136:139], v[202:205], v[118:121]
	v_mfma_f32_16x16x32_bf16 v[114:117], v[154:157], v[202:205], v[114:117]
	v_mfma_f32_16x16x32_bf16 v[102:105], v[136:139], v[210:213], v[102:105]
	v_mfma_f32_16x16x32_bf16 v[98:101], v[154:157], v[210:213], v[98:101]
	v_mfma_f32_16x16x32_bf16 v[86:89], v[136:139], v[236:239], v[86:89]
	v_mfma_f32_16x16x32_bf16 v[82:85], v[154:157], v[236:239], v[82:85]
	v_mfma_f32_16x16x32_bf16 v[126:129], v[150:153], v[198:201], v[126:129]
	v_mfma_f32_16x16x32_bf16 v[122:125], v[158:161], v[198:201], v[122:125]
	v_mfma_f32_16x16x32_bf16 v[118:121], v[150:153], v[206:209], v[118:121]
	v_mfma_f32_16x16x32_bf16 v[114:117], v[158:161], v[206:209], v[114:117]
	v_mfma_f32_16x16x32_bf16 v[102:105], v[150:153], v[232:235], v[102:105]
	v_mfma_f32_16x16x32_bf16 v[98:101], v[158:161], v[232:235], v[98:101]
	v_mfma_f32_16x16x32_bf16 v[86:89], v[150:153], v[240:243], v[86:89]
	v_mfma_f32_16x16x32_bf16 v[82:85], v[158:161], v[240:243], v[82:85]
	v_mfma_f32_16x16x32_bf16 v[110:113], v[178:181], v[194:197], v[110:113]
	v_mfma_f32_16x16x32_bf16 v[106:109], v[186:189], v[194:197], v[106:109]
	v_mfma_f32_16x16x32_bf16 v[94:97], v[178:181], v[202:205], v[94:97]
	v_mfma_f32_16x16x32_bf16 v[90:93], v[186:189], v[202:205], v[90:93]
	v_mfma_f32_16x16x32_bf16 v[78:81], v[178:181], v[210:213], v[78:81]
	v_mfma_f32_16x16x32_bf16 v[74:77], v[186:189], v[210:213], v[74:77]
	v_mfma_f32_16x16x32_bf16 v[70:73], v[178:181], v[236:239], v[70:73]
	v_mfma_f32_16x16x32_bf16 v[66:69], v[186:189], v[236:239], v[66:69]
	v_mfma_f32_16x16x32_bf16 v[110:113], v[182:185], v[198:201], v[110:113]
	v_mfma_f32_16x16x32_bf16 v[106:109], v[190:193], v[198:201], v[106:109]
	v_mfma_f32_16x16x32_bf16 v[94:97], v[182:185], v[206:209], v[94:97]
	v_mfma_f32_16x16x32_bf16 v[90:93], v[190:193], v[206:209], v[90:93]
	v_mfma_f32_16x16x32_bf16 v[78:81], v[182:185], v[232:235], v[78:81]
	v_mfma_f32_16x16x32_bf16 v[74:77], v[190:193], v[232:235], v[74:77]
	v_mfma_f32_16x16x32_bf16 v[70:73], v[182:185], v[240:243], v[70:73]
	v_mfma_f32_16x16x32_bf16 v[66:69], v[190:193], v[240:243], v[66:69]
	s_setprio 0
	s_barrier
	s_add_i32 s55, s40, s2
	v_lshl_add_u64 v[244:245], s[24:25], 0, v[174:175]
	s_mov_b32 m0, s55
	ds_read_b128 v[194:197], v148 offset:16384
	ds_read_b128 v[198:201], v148 offset:17408
	ds_read_b128 v[202:205], v148 offset:18432
	ds_read_b128 v[206:209], v148 offset:19456
	ds_read_b128 v[210:213], v148 offset:20480
	ds_read_b128 v[232:235], v148 offset:21504
	ds_read_b128 v[236:239], v148 offset:22528
	ds_read_b128 v[240:243], v148 offset:23552
	global_load_lds_dwordx4 v[244:245], off
	s_add_i32 m0, s55, 0x2000
	s_add_u32 s56, s24, 0x160000
	v_lshl_add_u64 v[246:247], s[24:25], 0, v[176:177]
	s_addc_u32 s57, s25, 0
	s_add_i32 s55, s41, s2
	global_load_lds_dwordx4 v[246:247], off
	v_lshl_add_u64 v[248:249], s[56:57], 0, v[174:175]
	s_mov_b32 m0, s55
	v_lshl_add_u64 v[250:251], s[26:27], 0, v[176:177]
	global_load_lds_dwordx4 v[248:249], off
	v_lshl_add_u64 v[248:249], s[56:57], 0, v[176:177]
	s_add_i32 m0, s55, 0x2000
	s_nop 0
	global_load_lds_dwordx4 v[248:249], off
	v_lshl_add_u64 v[248:249], s[26:27], 0, v[174:175]
	s_mov_b32 m0, s3
	s_nop 0
	global_load_lds_dwordx4 v[248:249], off
	s_mov_b32 m0, s28
	s_nop 0
	global_load_lds_dwordx4 v[250:251], off
	s_waitcnt vmcnt(8)
	s_waitcnt lgkmcnt(0)
	s_barrier
; #define PG8_STAGE(bufoff, gbase, voff) do { _Pragma("unroll") for (int _i = 0; _i < 2; ++_i) \
;         __builtin_amdgcn_global_load_lds((const unsigned*)((const char*)(gbase) + (voff)[_i]), (PG8_LAS unsigned*)(lds + (bufoff) + ldsw + _i * 8192), 16, 0, 0); } while (0)
; #define PG8_LDA(dst, b, h) do { _Pragma("unroll") for (int m = 0; m < 4; ++m) _Pragma("unroll") for (int k = 0; k < 2; ++k) dst[m][k] = *(const PG8_LAS bf16x8*)(lds + PG8_SA(b, h) + aoff + m * 2048 + k * 1024); } while (0)
; #define PG8_LDB(dst, b, h) do { _Pragma("unroll") for (int n = 0; n < 2; ++n) _Pragma("unroll") for (int k = 0; k < 2; ++k) dst[n][k] = *(const PG8_LAS bf16x8*)(lds + PG8_SB(b, h) + boff + n * 2048 + k * 1024); } while (0)
; #define PG8_MMA(ai, bj, At, Bt) do { __builtin_amdgcn_s_setprio(1); _Pragma("unroll") for (int m = 0; m < 4; ++m) _Pragma("unroll") for (int n = 0; n < 2; ++n) _Pragma("unroll") for (int k = 0; k < 2; ++k) \
;         acc[ai][bj][m][n] = __builtin_amdgcn_mfma_f32_16x16x32_bf16(Bt[n][k], At[m][k], acc[ai][bj][m][n], 0, 0, 0); __builtin_amdgcn_s_setprio(0); } while (0)
; #define PG8_WAIT_V(n) asm volatile("s_waitcnt vmcnt(" #n ")" ::: "memory")
; #define PG8_WAIT_L(n) asm volatile("s_waitcnt lgkmcnt(" #n ")" ::: "memory")
; #define PG8_BAR __builtin_amdgcn_s_barrier()
; #define PG8_SCHED __builtin_amdgcn_sched_barrier(0)
; template <class Epi, class Sched, bool ALIGN_EPI = false, bool SP2 = false>
; __device__ __forceinline__ void gemm_phase(PG8_LAS unsigned char* lds, const Gemm g, const Sched& S, const Epi& E) {
;     ...
;             PG8_WAIT_V(8); PG8_WAIT_L(0); PG8_BAR; PG8_MMA(1, 0, At, B0); PG8_MMA(1, 1, At, B1); PG8_BAR; PG8_SCHED;
;             PG8_LDB(B0, 1, 0); PG8_LDB(B1, 1, 1); PG8_SCHED; PG8_LDA(At, 1, 0); PG8_STAGE(PG8_SA(0, 1), a2 + hstep, voffA);
;             PG8_WAIT_V(8); PG8_WAIT_L(0); PG8_BAR; PG8_MMA(0, 0, At, B0); PG8_MMA(0, 1, At, B1); PG8_BAR; PG8_SCHED;
	s_setprio 1
	v_mfma_f32_16x16x32_bf16 v[62:65], v[136:139], v[194:197], v[62:65]
	v_mfma_f32_16x16x32_bf16 v[58:61], v[154:157], v[194:197], v[58:61]
	v_mfma_f32_16x16x32_bf16 v[54:57], v[136:139], v[202:205], v[54:57]
	v_mfma_f32_16x16x32_bf16 v[50:53], v[154:157], v[202:205], v[50:53]
	v_mfma_f32_16x16x32_bf16 v[38:41], v[136:139], v[210:213], v[38:41]
	v_mfma_f32_16x16x32_bf16 v[34:37], v[154:157], v[210:213], v[34:37]
	v_mfma_f32_16x16x32_bf16 v[22:25], v[136:139], v[236:239], v[22:25]
	v_mfma_f32_16x16x32_bf16 v[18:21], v[154:157], v[236:239], v[18:21]
	v_mfma_f32_16x16x32_bf16 v[62:65], v[150:153], v[198:201], v[62:65]
	v_mfma_f32_16x16x32_bf16 v[58:61], v[158:161], v[198:201], v[58:61]
	v_mfma_f32_16x16x32_bf16 v[54:57], v[150:153], v[206:209], v[54:57]
	v_mfma_f32_16x16x32_bf16 v[50:53], v[158:161], v[206:209], v[50:53]
	v_mfma_f32_16x16x32_bf16 v[38:41], v[150:153], v[232:235], v[38:41]
	v_mfma_f32_16x16x32_bf16 v[34:37], v[158:161], v[232:235], v[34:37]
	v_mfma_f32_16x16x32_bf16 v[22:25], v[150:153], v[240:243], v[22:25]
	v_mfma_f32_16x16x32_bf16 v[18:21], v[158:161], v[240:243], v[18:21]
	v_mfma_f32_16x16x32_bf16 v[46:49], v[178:181], v[194:197], v[46:49]
	v_mfma_f32_16x16x32_bf16 v[42:45], v[186:189], v[194:197], v[42:45]
	v_mfma_f32_16x16x32_bf16 v[30:33], v[178:181], v[202:205], v[30:33]
	v_mfma_f32_16x16x32_bf16 v[26:29], v[186:189], v[202:205], v[26:29]
	v_mfma_f32_16x16x32_bf16 v[14:17], v[178:181], v[210:213], v[14:17]
	v_mfma_f32_16x16x32_bf16 v[10:13], v[186:189], v[210:213], v[10:13]
	v_mfma_f32_16x16x32_bf16 v[6:9], v[178:181], v[236:239], v[6:9]
	v_mfma_f32_16x16x32_bf16 v[2:5], v[186:189], v[236:239], v[2:5]
	v_mfma_f32_16x16x32_bf16 v[46:49], v[182:185], v[198:201], v[46:49]
	v_mfma_f32_16x16x32_bf16 v[42:45], v[190:193], v[198:201], v[42:45]
	v_mfma_f32_16x16x32_bf16 v[30:33], v[182:185], v[206:209], v[30:33]
	v_mfma_f32_16x16x32_bf16 v[26:29], v[190:193], v[206:209], v[26:29]
	v_mfma_f32_16x16x32_bf16 v[14:17], v[182:185], v[232:235], v[14:17]
	v_mfma_f32_16x16x32_bf16 v[10:13], v[190:193], v[232:235], v[10:13]
	v_mfma_f32_16x16x32_bf16 v[6:9], v[182:185], v[240:243], v[6:9]
	v_mfma_f32_16x16x32_bf16 v[2:5], v[190:193], v[240:243], v[2:5]
	s_setprio 0
	s_barrier
	s_add_i32 s55, 0, 0x18000
	v_add_u32_e32 v149, s55, v144
	s_add_i32 s56, 0, 0x1c000
	ds_read_b128 v[136:139], v149
	ds_read_b128 v[150:153], v149 offset:1024
	ds_read_b128 v[154:157], v149 offset:2048
	ds_read_b128 v[158:161], v149 offset:3072
	v_add_u32_e32 v149, s56, v144
	ds_read_b128 v[178:181], v149
	ds_read_b128 v[182:185], v149 offset:1024
	ds_read_b128 v[186:189], v149 offset:2048
	ds_read_b128 v[190:193], v149 offset:3072
	s_add_u32 s26, s26, 0x160000
	s_addc_u32 s27, s27, 0
	s_mov_b32 m0, s29
	v_lshl_add_u64 v[252:253], s[26:27], 0, v[174:175]
	ds_read_b128 v[194:197], v148 offset:32768
	ds_read_b128 v[198:201], v148 offset:33792
	ds_read_b128 v[202:205], v148 offset:34816
	ds_read_b128 v[206:209], v148 offset:35840
	ds_read_b128 v[210:213], v148 offset:36864
	ds_read_b128 v[232:235], v148 offset:37888
	ds_read_b128 v[236:239], v148 offset:38912
	ds_read_b128 v[240:243], v148 offset:39936
	global_load_lds_dwordx4 v[252:253], off
	v_lshl_add_u64 v[252:253], s[26:27], 0, v[176:177]
	s_mov_b32 m0, s30
	s_nop 0
	global_load_lds_dwordx4 v[252:253], off
	s_waitcnt vmcnt(8)
	s_waitcnt lgkmcnt(0)
	s_barrier
	s_setprio 1
	v_mfma_f32_16x16x32_bf16 v[126:129], v[136:139], v[194:197], v[126:129]
	v_mfma_f32_16x16x32_bf16 v[122:125], v[154:157], v[194:197], v[122:125]
	v_mfma_f32_16x16x32_bf16 v[118:121], v[136:139], v[202:205], v[118:121]
	v_mfma_f32_16x16x32_bf16 v[114:117], v[154:157], v[202:205], v[114:117]
	v_mfma_f32_16x16x32_bf16 v[102:105], v[136:139], v[210:213], v[102:105]
	v_mfma_f32_16x16x32_bf16 v[98:101], v[154:157], v[210:213], v[98:101]
	v_mfma_f32_16x16x32_bf16 v[86:89], v[136:139], v[236:239], v[86:89]
	v_mfma_f32_16x16x32_bf16 v[82:85], v[154:157], v[236:239], v[82:85]
	v_mfma_f32_16x16x32_bf16 v[126:129], v[150:153], v[198:201], v[126:129]
	v_mfma_f32_16x16x32_bf16 v[122:125], v[158:161], v[198:201], v[122:125]
	v_mfma_f32_16x16x32_bf16 v[118:121], v[150:153], v[206:209], v[118:121]
	v_mfma_f32_16x16x32_bf16 v[114:117], v[158:161], v[206:209], v[114:117]
	v_mfma_f32_16x16x32_bf16 v[102:105], v[150:153], v[232:235], v[102:105]
	v_mfma_f32_16x16x32_bf16 v[98:101], v[158:161], v[232:235], v[98:101]
	v_mfma_f32_16x16x32_bf16 v[86:89], v[150:153], v[240:243], v[86:89]
	v_mfma_f32_16x16x32_bf16 v[82:85], v[158:161], v[240:243], v[82:85]
	v_mfma_f32_16x16x32_bf16 v[110:113], v[178:181], v[194:197], v[110:113]
	v_mfma_f32_16x16x32_bf16 v[106:109], v[186:189], v[194:197], v[106:109]
	v_mfma_f32_16x16x32_bf16 v[94:97], v[178:181], v[202:205], v[94:97]
	v_mfma_f32_16x16x32_bf16 v[90:93], v[186:189], v[202:205], v[90:93]
	v_mfma_f32_16x16x32_bf16 v[78:81], v[178:181], v[210:213], v[78:81]
	v_mfma_f32_16x16x32_bf16 v[74:77], v[186:189], v[210:213], v[74:77]
	v_mfma_f32_16x16x32_bf16 v[70:73], v[178:181], v[236:239], v[70:73]
	v_mfma_f32_16x16x32_bf16 v[66:69], v[186:189], v[236:239], v[66:69]
	v_mfma_f32_16x16x32_bf16 v[110:113], v[182:185], v[198:201], v[110:113]
	v_mfma_f32_16x16x32_bf16 v[106:109], v[190:193], v[198:201], v[106:109]
	v_mfma_f32_16x16x32_bf16 v[94:97], v[182:185], v[206:209], v[94:97]
	v_mfma_f32_16x16x32_bf16 v[90:93], v[190:193], v[206:209], v[90:93]
	v_mfma_f32_16x16x32_bf16 v[78:81], v[182:185], v[232:235], v[78:81]
	v_mfma_f32_16x16x32_bf16 v[74:77], v[190:193], v[232:235], v[74:77]
	v_mfma_f32_16x16x32_bf16 v[70:73], v[182:185], v[240:243], v[70:73]
	v_mfma_f32_16x16x32_bf16 v[66:69], v[190:193], v[240:243], v[66:69]
	s_setprio 0
	s_barrier
; #define PG8_STAGE(bufoff, gbase, voff) do { _Pragma("unroll") for (int _i = 0; _i < 2; ++_i) \
;         __builtin_amdgcn_global_load_lds((const unsigned*)((const char*)(gbase) + (voff)[_i]), (PG8_LAS unsigned*)(lds + (bufoff) + ldsw + _i * 8192), 16, 0, 0); } while (0)
; #define PG8_LDA(dst, b, h) do { _Pragma("unroll") for (int m = 0; m < 4; ++m) _Pragma("unroll") for (int k = 0; k < 2; ++k) dst[m][k] = *(const PG8_LAS bf16x8*)(lds + PG8_SA(b, h) + aoff + m * 2048 + k * 1024); } while (0)
; #define PG8_WAIT_V(n) asm volatile("s_waitcnt vmcnt(" #n ")" ::: "memory")
; template <class Epi, class Sched, bool ALIGN_EPI = false, bool SP2 = false>
; __device__ __forceinline__ void gemm_phase(PG8_LAS unsigned char* lds, const Gemm g, const Sched& S, const Epi& E) {
;     ...
;             PG8_LDA(At, 1, 1); PG8_STAGE(PG8_SB(1, 0), b3, voffB); PG8_STAGE(PG8_SB(1, 1), b3 + hstep, voffB); PG8_STAGE(PG8_SA(1, 0), a3, voffA);
;             PG8_WAIT_V(8); PG8_WAIT_L(0); PG8_BAR; PG8_MMA(1, 0, At, B0); PG8_MMA(1, 1, At, B1); PG8_BAR; PG8_SCHED;
;             } else {
;             PG8_LDB(B0, 0, 0); PG8_SCHED; PG8_LDA(At, 0, 0); PG8_STAGE(PG8_SA(1, 1), a1 + hstep, voffA);
;             PG8_WAIT_L(8); PG8_BAR; PG8_WAIT_L(0); PG8_MMA(0, 0, At, B0); PG8_BAR; PG8_SCHED;
;             PG8_LDB(B1, 0, 1); PG8_STAGE(PG8_SB(0, 0), b2, voffB);
;             PG8_BAR; PG8_WAIT_L(0); PG8_MMA(0, 1, At, B1); PG8_BAR;
;             PG8_LDA(At, 0, 1); PG8_STAGE(PG8_SA(0, 0), a2, voffA);
;             PG8_BAR; PG8_WAIT_L(0); PG8_MMA(1, 0, At, B0); PG8_BAR; PG8_SCHED;
;             PG8_STAGE(PG8_SB(0, 1), b2 + hstep, voffB);
;             PG8_WAIT_V(6); PG8_BAR; PG8_MMA(1, 1, At, B1); PG8_BAR;
;             PG8_LDB(B0, 1, 0); PG8_SCHED; PG8_LDA(At, 1, 0); PG8_STAGE(PG8_SA(0, 1), a2 + hstep, voffA);
;             PG8_WAIT_L(8); PG8_BAR; PG8_WAIT_L(0); PG8_MMA(0, 0, At, B0); PG8_BAR; PG8_SCHED;
;             PG8_LDB(B1, 1, 1); PG8_STAGE(PG8_SB(1, 0), b3, voffB);
;             PG8_BAR; PG8_WAIT_L(0); PG8_MMA(0, 1, At, B1); PG8_BAR;
;             PG8_LDA(At, 1, 1); PG8_STAGE(PG8_SA(1, 0), a3, voffA);
;             PG8_BAR; PG8_WAIT_L(0); PG8_MMA(1, 0, At, B0); PG8_BAR; PG8_SCHED;
;             PG8_STAGE(PG8_SB(1, 1), b3 + hstep, voffB);
;             PG8_WAIT_V(6); PG8_BAR; PG8_MMA(1, 1, At, B1); PG8_BAR;
;             }
;         }
;         if constexpr (ALIGN_EPI) { if (wr == 0) PG8_BAR; }
	s_add_i32 s26, s55, s2
	v_lshl_add_u64 v[244:245], v[244:245], 0, s[12:13]
	s_mov_b32 m0, s26
	ds_read_b128 v[194:197], v148 offset:49152
	ds_read_b128 v[198:201], v148 offset:50176
	ds_read_b128 v[202:205], v148 offset:51200
	ds_read_b128 v[206:209], v148 offset:52224
	ds_read_b128 v[210:213], v148 offset:53248
	ds_read_b128 v[232:235], v148 offset:54272
	ds_read_b128 v[236:239], v148 offset:55296
	ds_read_b128 v[240:243], v148 offset:56320
	global_load_lds_dwordx4 v[244:245], off
	s_add_i32 m0, s26, 0x2000
	s_add_u32 s24, s24, 0x160080
	v_lshl_add_u64 v[244:245], v[246:247], 0, s[12:13]
	s_addc_u32 s25, s25, 0
	s_add_i32 s26, s56, s2
	global_load_lds_dwordx4 v[244:245], off
	v_lshl_add_u64 v[244:245], s[24:25], 0, v[174:175]
	s_mov_b32 m0, s26
	s_nop 0
	global_load_lds_dwordx4 v[244:245], off
	v_lshl_add_u64 v[244:245], s[24:25], 0, v[176:177]
	s_add_i32 m0, s26, 0x2000
	s_nop 0
	global_load_lds_dwordx4 v[244:245], off
	v_lshl_add_u64 v[244:245], v[248:249], 0, s[12:13]
	s_mov_b32 m0, s31
	s_nop 0
	global_load_lds_dwordx4 v[244:245], off
	v_lshl_add_u64 v[244:245], v[250:251], 0, s[12:13]
	s_mov_b32 m0, s33
	s_nop 0
	global_load_lds_dwordx4 v[244:245], off
	s_waitcnt vmcnt(8)
	s_waitcnt lgkmcnt(0)
	s_barrier
	s_setprio 1
	v_mfma_f32_16x16x32_bf16 v[62:65], v[136:139], v[194:197], v[62:65]
	v_mfma_f32_16x16x32_bf16 v[58:61], v[154:157], v[194:197], v[58:61]
	v_mfma_f32_16x16x32_bf16 v[54:57], v[136:139], v[202:205], v[54:57]
	v_mfma_f32_16x16x32_bf16 v[50:53], v[154:157], v[202:205], v[50:53]
	v_mfma_f32_16x16x32_bf16 v[38:41], v[136:139], v[210:213], v[38:41]
	v_mfma_f32_16x16x32_bf16 v[34:37], v[154:157], v[210:213], v[34:37]
	v_mfma_f32_16x16x32_bf16 v[22:25], v[136:139], v[236:239], v[22:25]
	v_mfma_f32_16x16x32_bf16 v[18:21], v[154:157], v[236:239], v[18:21]
	v_mfma_f32_16x16x32_bf16 v[62:65], v[150:153], v[198:201], v[62:65]
	v_mfma_f32_16x16x32_bf16 v[58:61], v[158:161], v[198:201], v[58:61]
	v_mfma_f32_16x16x32_bf16 v[54:57], v[150:153], v[206:209], v[54:57]
	v_mfma_f32_16x16x32_bf16 v[50:53], v[158:161], v[206:209], v[50:53]
	v_mfma_f32_16x16x32_bf16 v[38:41], v[150:153], v[232:235], v[38:41]
	v_mfma_f32_16x16x32_bf16 v[34:37], v[158:161], v[232:235], v[34:37]
	v_mfma_f32_16x16x32_bf16 v[22:25], v[150:153], v[240:243], v[22:25]
	v_mfma_f32_16x16x32_bf16 v[18:21], v[158:161], v[240:243], v[18:21]
	v_mfma_f32_16x16x32_bf16 v[46:49], v[178:181], v[194:197], v[46:49]
	v_mfma_f32_16x16x32_bf16 v[42:45], v[186:189], v[194:197], v[42:45]
	v_mfma_f32_16x16x32_bf16 v[30:33], v[178:181], v[202:205], v[30:33]
	v_mfma_f32_16x16x32_bf16 v[26:29], v[186:189], v[202:205], v[26:29]
	v_mfma_f32_16x16x32_bf16 v[14:17], v[178:181], v[210:213], v[14:17]
	v_mfma_f32_16x16x32_bf16 v[10:13], v[186:189], v[210:213], v[10:13]
	v_mfma_f32_16x16x32_bf16 v[6:9], v[178:181], v[236:239], v[6:9]
	v_mfma_f32_16x16x32_bf16 v[2:5], v[186:189], v[236:239], v[2:5]
	v_mfma_f32_16x16x32_bf16 v[46:49], v[182:185], v[198:201], v[46:49]
	v_mfma_f32_16x16x32_bf16 v[42:45], v[190:193], v[198:201], v[42:45]
	v_mfma_f32_16x16x32_bf16 v[30:33], v[182:185], v[206:209], v[30:33]
	v_mfma_f32_16x16x32_bf16 v[26:29], v[190:193], v[206:209], v[26:29]
	v_mfma_f32_16x16x32_bf16 v[14:17], v[182:185], v[232:235], v[14:17]
	v_mfma_f32_16x16x32_bf16 v[10:13], v[190:193], v[232:235], v[10:13]
	v_mfma_f32_16x16x32_bf16 v[6:9], v[182:185], v[240:243], v[6:9]
	v_mfma_f32_16x16x32_bf16 v[2:5], v[190:193], v[240:243], v[2:5]
	s_setprio 0
	s_barrier
	s_add_u32 s22, s22, 0x100
	s_addc_u32 s23, s23, 0
	s_add_u32 s51, s51, 0x100
	s_addc_u32 s53, s53, 0
	s_cmp_ge_u32 s54, s43
	s_mov_b32 s24, s54
	s_cbranch_scc0 .LBB0_281
	s_and_b64 vcc, exec, s[14:15]
	s_cbranch_vccz .LBB0_284
	s_barrier

; #define PG8_STAGE(bufoff, gbase, voff) do { _Pragma("unroll") for (int _i = 0; _i < 2; ++_i) \
;         __builtin_amdgcn_global_load_lds((const unsigned*)((const char*)(gbase) + (voff)[_i]), (PG8_LAS unsigned*)(lds + (bufoff) + ldsw + _i * 8192), 16, 0, 0); } while (0)
; #define PG8_LDA(dst, b, h) do { _Pragma("unroll") for (int m = 0; m < 4; ++m) _Pragma("unroll") for (int k = 0; k < 2; ++k) dst[m][k] = *(const PG8_LAS bf16x8*)(lds + PG8_SA(b, h) + aoff + m * 2048 + k * 1024); } while (0)
; #define PG8_LDB(dst, b, h) do { _Pragma("unroll") for (int n = 0; n < 2; ++n) _Pragma("unroll") for (int k = 0; k < 2; ++k) dst[n][k] = *(const PG8_LAS bf16x8*)(lds + PG8_SB(b, h) + boff + n * 2048 + k * 1024); } while (0)
; #define PG8_MMA(ai, bj, At, Bt) do { __builtin_amdgcn_s_setprio(1); _Pragma("unroll") for (int m = 0; m < 4; ++m) _Pragma("unroll") for (int n = 0; n < 2; ++n) _Pragma("unroll") for (int k = 0; k < 2; ++k) \
;         acc[ai][bj][m][n] = __builtin_amdgcn_mfma_f32_16x16x32_bf16(Bt[n][k], At[m][k], acc[ai][bj][m][n], 0, 0, 0); __builtin_amdgcn_s_setprio(0); } while (0)
; #define PG8_WAIT_V(n) asm volatile("s_waitcnt vmcnt(" #n ")" ::: "memory")
; #define PG8_BAR __builtin_amdgcn_s_barrier()
; template <class Epi, class Sched, bool ALIGN_EPI = false, bool SP2 = false>
; __device__ __forceinline__ void gemm_phase(PG8_LAS unsigned char* lds, const Gemm g, const Sched& S, const Epi& E) {
;     ...
;         for (int t = 0; t < nt; t += 2) {
;             const bool last = (t == nt - 2);
;             const char* a1 = cA + (size_t)(t + 1) * kstep;
;             const char* a2 = last ? nA : cA + (size_t)(t + 2) * kstep; const char* b2 = last ? nB : cB + (size_t)(t + 2) * kstep;
;             const char* a3 = a2 + kstep; const char* b3 = b2 + kstep;
;             if (last && has_next) S.a_ready(nxt);
;             if constexpr (SP2) {
;             PG8_LDB(B0, 0, 0); PG8_LDB(B1, 0, 1); PG8_SCHED; PG8_LDA(At, 0, 0); PG8_STAGE(PG8_SA(1, 1), a1 + hstep, voffA);
;             PG8_WAIT_V(8); PG8_WAIT_L(0); PG8_BAR; PG8_MMA(0, 0, At, B0); PG8_MMA(0, 1, At, B1); PG8_BAR; PG8_SCHED;
;             PG8_LDA(At, 0, 1); PG8_STAGE(PG8_SB(0, 0), b2, voffB); PG8_STAGE(PG8_SB(0, 1), b2 + hstep, voffB); PG8_STAGE(PG8_SA(0, 0), a2, voffA);
;             PG8_WAIT_V(8); PG8_WAIT_L(0); PG8_BAR; PG8_MMA(1, 0, At, B0); PG8_MMA(1, 1, At, B1); PG8_BAR; PG8_SCHED;
.LBB0_423:
	ds_read_b128 v[146:149], v139
	ds_read_b128 v[150:153], v139 offset:1024
	ds_read_b128 v[154:157], v139 offset:2048
	ds_read_b128 v[158:161], v139 offset:3072
	ds_read_b128 v[180:183], v143
	ds_read_b128 v[184:187], v143 offset:1024
	ds_read_b128 v[188:191], v143 offset:2048
	ds_read_b128 v[192:195], v143 offset:3072
	s_add_i32 s49, s48, 2
	s_add_u32 s24, s4, 0xfff80080
	s_addc_u32 s25, s5, -1
	s_cmp_eq_u32 s45, s48
	s_cselect_b32 s27, s19, s25
	s_cselect_b32 s26, s43, s24
	s_cselect_b32 s25, s17, s47
	s_cselect_b32 s24, s44, s46
	v_lshl_add_u64 v[212:213], s[4:5], 0, v[130:131]
	s_add_i32 m0, s15, 0xc000
	ds_read_b128 v[196:199], v144
	ds_read_b128 v[200:203], v144 offset:1024
	ds_read_b128 v[204:207], v144 offset:2048
	ds_read_b128 v[208:211], v144 offset:3072
	ds_read_b128 v[232:235], v144 offset:4096
	ds_read_b128 v[236:239], v144 offset:5120
	ds_read_b128 v[240:243], v144 offset:6144
	ds_read_b128 v[244:247], v144 offset:7168
	global_load_lds_dwordx4 v[212:213], off
	v_lshl_add_u64 v[212:213], s[4:5], 0, v[132:133]
	s_add_i32 m0, s15, 0xe000
	s_nop 0
	global_load_lds_dwordx4 v[212:213], off
	s_waitcnt vmcnt(8)
	s_waitcnt lgkmcnt(0)
	s_barrier
	s_setprio 1
	v_mfma_f32_16x16x32_bf16 v[126:129], v[146:149], v[196:199], v[126:129]
	v_mfma_f32_16x16x32_bf16 v[122:125], v[154:157], v[196:199], v[122:125]
	v_mfma_f32_16x16x32_bf16 v[118:121], v[146:149], v[204:207], v[118:121]
	v_mfma_f32_16x16x32_bf16 v[114:117], v[154:157], v[204:207], v[114:117]
	v_mfma_f32_16x16x32_bf16 v[102:105], v[146:149], v[232:235], v[102:105]
	v_mfma_f32_16x16x32_bf16 v[98:101], v[154:157], v[232:235], v[98:101]
	v_mfma_f32_16x16x32_bf16 v[86:89], v[146:149], v[240:243], v[86:89]
	v_mfma_f32_16x16x32_bf16 v[82:85], v[154:157], v[240:243], v[82:85]
	v_mfma_f32_16x16x32_bf16 v[126:129], v[150:153], v[200:203], v[126:129]
	v_mfma_f32_16x16x32_bf16 v[122:125], v[158:161], v[200:203], v[122:125]
	v_mfma_f32_16x16x32_bf16 v[118:121], v[150:153], v[208:211], v[118:121]
	v_mfma_f32_16x16x32_bf16 v[114:117], v[158:161], v[208:211], v[114:117]
	v_mfma_f32_16x16x32_bf16 v[102:105], v[150:153], v[236:239], v[102:105]
	v_mfma_f32_16x16x32_bf16 v[98:101], v[158:161], v[236:239], v[98:101]
	v_mfma_f32_16x16x32_bf16 v[86:89], v[150:153], v[244:247], v[86:89]
	v_mfma_f32_16x16x32_bf16 v[82:85], v[158:161], v[244:247], v[82:85]
	v_mfma_f32_16x16x32_bf16 v[110:113], v[180:183], v[196:199], v[110:113]
	v_mfma_f32_16x16x32_bf16 v[106:109], v[188:191], v[196:199], v[106:109]
	v_mfma_f32_16x16x32_bf16 v[94:97], v[180:183], v[204:207], v[94:97]
	v_mfma_f32_16x16x32_bf16 v[90:93], v[188:191], v[204:207], v[90:93]
	v_mfma_f32_16x16x32_bf16 v[78:81], v[180:183], v[232:235], v[78:81]
	v_mfma_f32_16x16x32_bf16 v[74:77], v[188:191], v[232:235], v[74:77]
	v_mfma_f32_16x16x32_bf16 v[70:73], v[180:183], v[240:243], v[70:73]
	v_mfma_f32_16x16x32_bf16 v[66:69], v[188:191], v[240:243], v[66:69]
	v_mfma_f32_16x16x32_bf16 v[110:113], v[184:187], v[200:203], v[110:113]
	v_mfma_f32_16x16x32_bf16 v[106:109], v[192:195], v[200:203], v[106:109]
	v_mfma_f32_16x16x32_bf16 v[94:97], v[184:187], v[208:211], v[94:97]
	v_mfma_f32_16x16x32_bf16 v[90:93], v[192:195], v[208:211], v[90:93]
	v_mfma_f32_16x16x32_bf16 v[78:81], v[184:187], v[236:239], v[78:81]
	v_mfma_f32_16x16x32_bf16 v[74:77], v[192:195], v[236:239], v[74:77]
	v_mfma_f32_16x16x32_bf16 v[70:73], v[184:187], v[244:247], v[70:73]
	v_mfma_f32_16x16x32_bf16 v[66:69], v[192:195], v[244:247], v[66:69]
	s_setprio 0
	s_barrier
	s_add_i32 s48, s37, s2
	v_lshl_add_u64 v[212:213], s[24:25], 0, v[168:169]
	s_mov_b32 m0, s48
	ds_read_b128 v[196:199], v144 offset:16384
	ds_read_b128 v[200:203], v144 offset:17408
	ds_read_b128 v[204:207], v144 offset:18432
	ds_read_b128 v[208:211], v144 offset:19456
	ds_read_b128 v[232:235], v144 offset:20480
	ds_read_b128 v[236:239], v144 offset:21504
	ds_read_b128 v[240:243], v144 offset:22528
	ds_read_b128 v[244:247], v144 offset:23552
	global_load_lds_dwordx4 v[212:213], off
	s_add_i32 m0, s48, 0x2000
	s_add_u32 s50, s24, 0x80000
	v_lshl_add_u64 v[248:249], s[24:25], 0, v[172:173]
	s_addc_u32 s51, s25, 0
	s_add_i32 s48, s38, s2
	global_load_lds_dwordx4 v[248:249], off
	v_lshl_add_u64 v[250:251], s[50:51], 0, v[168:169]
	s_mov_b32 m0, s48
	v_lshl_add_u64 v[252:253], s[26:27], 0, v[170:171]
	global_load_lds_dwordx4 v[250:251], off
	v_lshl_add_u64 v[250:251], s[50:51], 0, v[172:173]
	s_add_i32 m0, s48, 0x2000
	s_nop 0
	global_load_lds_dwordx4 v[250:251], off
	v_lshl_add_u64 v[250:251], s[26:27], 0, v[166:167]
	s_mov_b32 m0, s15
	s_nop 0
	global_load_lds_dwordx4 v[250:251], off
	s_mov_b32 m0, s29
	s_nop 0
	global_load_lds_dwordx4 v[252:253], off
	s_waitcnt vmcnt(8)
	s_waitcnt lgkmcnt(0)
	s_barrier
; #define PG8_STAGE(bufoff, gbase, voff) do { _Pragma("unroll") for (int _i = 0; _i < 2; ++_i) \
;         __builtin_amdgcn_global_load_lds((const unsigned*)((const char*)(gbase) + (voff)[_i]), (PG8_LAS unsigned*)(lds + (bufoff) + ldsw + _i * 8192), 16, 0, 0); } while (0)
; #define PG8_LDA(dst, b, h) do { _Pragma("unroll") for (int m = 0; m < 4; ++m) _Pragma("unroll") for (int k = 0; k < 2; ++k) dst[m][k] = *(const PG8_LAS bf16x8*)(lds + PG8_SA(b, h) + aoff + m * 2048 + k * 1024); } while (0)
; #define PG8_LDB(dst, b, h) do { _Pragma("unroll") for (int n = 0; n < 2; ++n) _Pragma("unroll") for (int k = 0; k < 2; ++k) dst[n][k] = *(const PG8_LAS bf16x8*)(lds + PG8_SB(b, h) + boff + n * 2048 + k * 1024); } while (0)
; #define PG8_MMA(ai, bj, At, Bt) do { __builtin_amdgcn_s_setprio(1); _Pragma("unroll") for (int m = 0; m < 4; ++m) _Pragma("unroll") for (int n = 0; n < 2; ++n) _Pragma("unroll") for (int k = 0; k < 2; ++k) \
;         acc[ai][bj][m][n] = __builtin_amdgcn_mfma_f32_16x16x32_bf16(Bt[n][k], At[m][k], acc[ai][bj][m][n], 0, 0, 0); __builtin_amdgcn_s_setprio(0); } while (0)
; #define PG8_WAIT_V(n) asm volatile("s_waitcnt vmcnt(" #n ")" ::: "memory")
; #define PG8_WAIT_L(n) asm volatile("s_waitcnt lgkmcnt(" #n ")" ::: "memory")
; #define PG8_BAR __builtin_amdgcn_s_barrier()
; #define PG8_SCHED __builtin_amdgcn_sched_barrier(0)
; template <class Epi, class Sched, bool ALIGN_EPI = false, bool SP2 = false>
; __device__ __forceinline__ void gemm_phase(PG8_LAS unsigned char* lds, const Gemm g, const Sched& S, const Epi& E) {
;     ...
;             PG8_WAIT_V(8); PG8_WAIT_L(0); PG8_BAR; PG8_MMA(1, 0, At, B0); PG8_MMA(1, 1, At, B1); PG8_BAR; PG8_SCHED;
;             PG8_LDB(B0, 1, 0); PG8_LDB(B1, 1, 1); PG8_SCHED; PG8_LDA(At, 1, 0); PG8_STAGE(PG8_SA(0, 1), a2 + hstep, voffA);
;             PG8_WAIT_V(8); PG8_WAIT_L(0); PG8_BAR; PG8_MMA(0, 0, At, B0); PG8_MMA(0, 1, At, B1); PG8_BAR; PG8_SCHED;
	s_setprio 1
	v_mfma_f32_16x16x32_bf16 v[62:65], v[146:149], v[196:199], v[62:65]
	v_mfma_f32_16x16x32_bf16 v[58:61], v[154:157], v[196:199], v[58:61]
	v_mfma_f32_16x16x32_bf16 v[54:57], v[146:149], v[204:207], v[54:57]
	v_mfma_f32_16x16x32_bf16 v[50:53], v[154:157], v[204:207], v[50:53]
	v_mfma_f32_16x16x32_bf16 v[38:41], v[146:149], v[232:235], v[38:41]
	v_mfma_f32_16x16x32_bf16 v[34:37], v[154:157], v[232:235], v[34:37]
	v_mfma_f32_16x16x32_bf16 v[22:25], v[146:149], v[240:243], v[22:25]
	v_mfma_f32_16x16x32_bf16 v[18:21], v[154:157], v[240:243], v[18:21]
	v_mfma_f32_16x16x32_bf16 v[62:65], v[150:153], v[200:203], v[62:65]
	v_mfma_f32_16x16x32_bf16 v[58:61], v[158:161], v[200:203], v[58:61]
	v_mfma_f32_16x16x32_bf16 v[54:57], v[150:153], v[208:211], v[54:57]
	v_mfma_f32_16x16x32_bf16 v[50:53], v[158:161], v[208:211], v[50:53]
	v_mfma_f32_16x16x32_bf16 v[38:41], v[150:153], v[236:239], v[38:41]
	v_mfma_f32_16x16x32_bf16 v[34:37], v[158:161], v[236:239], v[34:37]
	v_mfma_f32_16x16x32_bf16 v[22:25], v[150:153], v[244:247], v[22:25]
	v_mfma_f32_16x16x32_bf16 v[18:21], v[158:161], v[244:247], v[18:21]
	v_mfma_f32_16x16x32_bf16 v[46:49], v[180:183], v[196:199], v[46:49]
	v_mfma_f32_16x16x32_bf16 v[42:45], v[188:191], v[196:199], v[42:45]
	v_mfma_f32_16x16x32_bf16 v[30:33], v[180:183], v[204:207], v[30:33]
	v_mfma_f32_16x16x32_bf16 v[26:29], v[188:191], v[204:207], v[26:29]
	v_mfma_f32_16x16x32_bf16 v[14:17], v[180:183], v[232:235], v[14:17]
	v_mfma_f32_16x16x32_bf16 v[10:13], v[188:191], v[232:235], v[10:13]
	v_mfma_f32_16x16x32_bf16 v[6:9], v[180:183], v[240:243], v[6:9]
	v_mfma_f32_16x16x32_bf16 v[2:5], v[188:191], v[240:243], v[2:5]
	v_mfma_f32_16x16x32_bf16 v[46:49], v[184:187], v[200:203], v[46:49]
	v_mfma_f32_16x16x32_bf16 v[42:45], v[192:195], v[200:203], v[42:45]
	v_mfma_f32_16x16x32_bf16 v[30:33], v[184:187], v[208:211], v[30:33]
	v_mfma_f32_16x16x32_bf16 v[26:29], v[192:195], v[208:211], v[26:29]
	v_mfma_f32_16x16x32_bf16 v[14:17], v[184:187], v[236:239], v[14:17]
	v_mfma_f32_16x16x32_bf16 v[10:13], v[192:195], v[236:239], v[10:13]
	v_mfma_f32_16x16x32_bf16 v[6:9], v[184:187], v[244:247], v[6:9]
	v_mfma_f32_16x16x32_bf16 v[2:5], v[192:195], v[244:247], v[2:5]
	s_setprio 0
	s_barrier
	s_add_i32 s48, 0, 0x18000
	v_add_u32_e32 v145, s48, v137
	s_add_i32 s50, 0, 0x1c000
	ds_read_b128 v[146:149], v145
	ds_read_b128 v[150:153], v145 offset:1024
	ds_read_b128 v[154:157], v145 offset:2048
	ds_read_b128 v[158:161], v145 offset:3072
	v_add_u32_e32 v145, s50, v137
	ds_read_b128 v[180:183], v145
	ds_read_b128 v[184:187], v145 offset:1024
	ds_read_b128 v[188:191], v145 offset:2048
	ds_read_b128 v[192:195], v145 offset:3072
	s_add_u32 s26, s26, 0x80000
	s_addc_u32 s27, s27, 0
	s_mov_b32 m0, s30
	v_lshl_add_u64 v[222:223], s[26:27], 0, v[166:167]
	ds_read_b128 v[196:199], v144 offset:32768
	ds_read_b128 v[200:203], v144 offset:33792
	ds_read_b128 v[204:207], v144 offset:34816
	ds_read_b128 v[208:211], v144 offset:35840
	ds_read_b128 v[232:235], v144 offset:36864
	ds_read_b128 v[236:239], v144 offset:37888
	ds_read_b128 v[240:243], v144 offset:38912
	ds_read_b128 v[244:247], v144 offset:39936
	global_load_lds_dwordx4 v[222:223], off
	v_lshl_add_u64 v[222:223], s[26:27], 0, v[170:171]
	s_mov_b32 m0, s31
	s_nop 0
	global_load_lds_dwordx4 v[222:223], off
	s_waitcnt vmcnt(8)
	s_waitcnt lgkmcnt(0)
	s_barrier
	s_setprio 1
	v_mfma_f32_16x16x32_bf16 v[126:129], v[146:149], v[196:199], v[126:129]
	v_mfma_f32_16x16x32_bf16 v[122:125], v[154:157], v[196:199], v[122:125]
	v_mfma_f32_16x16x32_bf16 v[118:121], v[146:149], v[204:207], v[118:121]
	v_mfma_f32_16x16x32_bf16 v[114:117], v[154:157], v[204:207], v[114:117]
	v_mfma_f32_16x16x32_bf16 v[102:105], v[146:149], v[232:235], v[102:105]
	v_mfma_f32_16x16x32_bf16 v[98:101], v[154:157], v[232:235], v[98:101]
	v_mfma_f32_16x16x32_bf16 v[86:89], v[146:149], v[240:243], v[86:89]
	v_mfma_f32_16x16x32_bf16 v[82:85], v[154:157], v[240:243], v[82:85]
	v_mfma_f32_16x16x32_bf16 v[126:129], v[150:153], v[200:203], v[126:129]
	v_mfma_f32_16x16x32_bf16 v[122:125], v[158:161], v[200:203], v[122:125]
	v_mfma_f32_16x16x32_bf16 v[118:121], v[150:153], v[208:211], v[118:121]
	v_mfma_f32_16x16x32_bf16 v[114:117], v[158:161], v[208:211], v[114:117]
	v_mfma_f32_16x16x32_bf16 v[102:105], v[150:153], v[236:239], v[102:105]
	v_mfma_f32_16x16x32_bf16 v[98:101], v[158:161], v[236:239], v[98:101]
	v_mfma_f32_16x16x32_bf16 v[86:89], v[150:153], v[244:247], v[86:89]
	v_mfma_f32_16x16x32_bf16 v[82:85], v[158:161], v[244:247], v[82:85]
	v_mfma_f32_16x16x32_bf16 v[110:113], v[180:183], v[196:199], v[110:113]
	v_mfma_f32_16x16x32_bf16 v[106:109], v[188:191], v[196:199], v[106:109]
	v_mfma_f32_16x16x32_bf16 v[94:97], v[180:183], v[204:207], v[94:97]
	v_mfma_f32_16x16x32_bf16 v[90:93], v[188:191], v[204:207], v[90:93]
	v_mfma_f32_16x16x32_bf16 v[78:81], v[180:183], v[232:235], v[78:81]
	v_mfma_f32_16x16x32_bf16 v[74:77], v[188:191], v[232:235], v[74:77]
	v_mfma_f32_16x16x32_bf16 v[70:73], v[180:183], v[240:243], v[70:73]
	v_mfma_f32_16x16x32_bf16 v[66:69], v[188:191], v[240:243], v[66:69]
	v_mfma_f32_16x16x32_bf16 v[110:113], v[184:187], v[200:203], v[110:113]
	v_mfma_f32_16x16x32_bf16 v[106:109], v[192:195], v[200:203], v[106:109]
	v_mfma_f32_16x16x32_bf16 v[94:97], v[184:187], v[208:211], v[94:97]
	v_mfma_f32_16x16x32_bf16 v[90:93], v[192:195], v[208:211], v[90:93]
	v_mfma_f32_16x16x32_bf16 v[78:81], v[184:187], v[236:239], v[78:81]
	v_mfma_f32_16x16x32_bf16 v[74:77], v[192:195], v[236:239], v[74:77]
	v_mfma_f32_16x16x32_bf16 v[70:73], v[184:187], v[244:247], v[70:73]
	v_mfma_f32_16x16x32_bf16 v[66:69], v[192:195], v[244:247], v[66:69]
	s_setprio 0
	s_barrier
; #define PG8_STAGE(bufoff, gbase, voff) do { _Pragma("unroll") for (int _i = 0; _i < 2; ++_i) \
;         __builtin_amdgcn_global_load_lds((const unsigned*)((const char*)(gbase) + (voff)[_i]), (PG8_LAS unsigned*)(lds + (bufoff) + ldsw + _i * 8192), 16, 0, 0); } while (0)
; #define PG8_LDA(dst, b, h) do { _Pragma("unroll") for (int m = 0; m < 4; ++m) _Pragma("unroll") for (int k = 0; k < 2; ++k) dst[m][k] = *(const PG8_LAS bf16x8*)(lds + PG8_SA(b, h) + aoff + m * 2048 + k * 1024); } while (0)
; #define PG8_WAIT_V(n) asm volatile("s_waitcnt vmcnt(" #n ")" ::: "memory")
; template <class Epi, class Sched, bool ALIGN_EPI = false, bool SP2 = false>
; __device__ __forceinline__ void gemm_phase(PG8_LAS unsigned char* lds, const Gemm g, const Sched& S, const Epi& E) {
;     ...
;             PG8_LDA(At, 1, 1); PG8_STAGE(PG8_SB(1, 0), b3, voffB); PG8_STAGE(PG8_SB(1, 1), b3 + hstep, voffB); PG8_STAGE(PG8_SA(1, 0), a3, voffA);
;             PG8_WAIT_V(8); PG8_WAIT_L(0); PG8_BAR; PG8_MMA(1, 0, At, B0); PG8_MMA(1, 1, At, B1); PG8_BAR; PG8_SCHED;
;             } else {
;             PG8_LDB(B0, 0, 0); PG8_SCHED; PG8_LDA(At, 0, 0); PG8_STAGE(PG8_SA(1, 1), a1 + hstep, voffA);
;             PG8_WAIT_L(8); PG8_BAR; PG8_WAIT_L(0); PG8_MMA(0, 0, At, B0); PG8_BAR; PG8_SCHED;
;             PG8_LDB(B1, 0, 1); PG8_STAGE(PG8_SB(0, 0), b2, voffB);
;             PG8_BAR; PG8_WAIT_L(0); PG8_MMA(0, 1, At, B1); PG8_BAR;
;             PG8_LDA(At, 0, 1); PG8_STAGE(PG8_SA(0, 0), a2, voffA);
;             PG8_BAR; PG8_WAIT_L(0); PG8_MMA(1, 0, At, B0); PG8_BAR; PG8_SCHED;
;             PG8_STAGE(PG8_SB(0, 1), b2 + hstep, voffB);
;             PG8_WAIT_V(6); PG8_BAR; PG8_MMA(1, 1, At, B1); PG8_BAR;
;             PG8_LDB(B0, 1, 0); PG8_SCHED; PG8_LDA(At, 1, 0); PG8_STAGE(PG8_SA(0, 1), a2 + hstep, voffA);
;             PG8_WAIT_L(8); PG8_BAR; PG8_WAIT_L(0); PG8_MMA(0, 0, At, B0); PG8_BAR; PG8_SCHED;
;             PG8_LDB(B1, 1, 1); PG8_STAGE(PG8_SB(1, 0), b3, voffB);
;             PG8_BAR; PG8_WAIT_L(0); PG8_MMA(0, 1, At, B1); PG8_BAR;
;             PG8_LDA(At, 1, 1); PG8_STAGE(PG8_SA(1, 0), a3, voffA);
;             PG8_BAR; PG8_WAIT_L(0); PG8_MMA(1, 0, At, B0); PG8_BAR; PG8_SCHED;
;             PG8_STAGE(PG8_SB(1, 1), b3 + hstep, voffB);
;             PG8_WAIT_V(6); PG8_BAR; PG8_MMA(1, 1, At, B1); PG8_BAR;
;             }
;         }
;         if constexpr (ALIGN_EPI) { if (wr == 0) PG8_BAR; }
	s_add_i32 s26, s48, s2
	v_lshl_add_u64 v[212:213], v[212:213], 0, s[10:11]
	s_mov_b32 m0, s26
	ds_read_b128 v[196:199], v144 offset:49152
	ds_read_b128 v[200:203], v144 offset:50176
	ds_read_b128 v[204:207], v144 offset:51200
	ds_read_b128 v[208:211], v144 offset:52224
	ds_read_b128 v[232:235], v144 offset:53248
	ds_read_b128 v[236:239], v144 offset:54272
	ds_read_b128 v[240:243], v144 offset:55296
	ds_read_b128 v[244:247], v144 offset:56320
	global_load_lds_dwordx4 v[212:213], off
	s_add_i32 m0, s26, 0x2000
	s_add_u32 s24, s24, 0x80080
	v_lshl_add_u64 v[212:213], v[248:249], 0, s[10:11]
	s_addc_u32 s25, s25, 0
	s_add_i32 s26, s50, s2
	global_load_lds_dwordx4 v[212:213], off
	v_lshl_add_u64 v[212:213], s[24:25], 0, v[168:169]
	s_mov_b32 m0, s26
	s_nop 0
	global_load_lds_dwordx4 v[212:213], off
	v_lshl_add_u64 v[212:213], s[24:25], 0, v[172:173]
	s_add_i32 m0, s26, 0x2000
	s_nop 0
	global_load_lds_dwordx4 v[212:213], off
	v_lshl_add_u64 v[212:213], v[250:251], 0, s[10:11]
	s_mov_b32 m0, s34
	s_nop 0
	global_load_lds_dwordx4 v[212:213], off
	v_lshl_add_u64 v[212:213], v[252:253], 0, s[10:11]
	s_mov_b32 m0, s35
	s_nop 0
	global_load_lds_dwordx4 v[212:213], off
	s_waitcnt vmcnt(8)
	s_waitcnt lgkmcnt(0)
	s_barrier
	s_setprio 1
	v_mfma_f32_16x16x32_bf16 v[62:65], v[146:149], v[196:199], v[62:65]
	v_mfma_f32_16x16x32_bf16 v[58:61], v[154:157], v[196:199], v[58:61]
	v_mfma_f32_16x16x32_bf16 v[54:57], v[146:149], v[204:207], v[54:57]
	v_mfma_f32_16x16x32_bf16 v[50:53], v[154:157], v[204:207], v[50:53]
	v_mfma_f32_16x16x32_bf16 v[38:41], v[146:149], v[232:235], v[38:41]
	v_mfma_f32_16x16x32_bf16 v[34:37], v[154:157], v[232:235], v[34:37]
	v_mfma_f32_16x16x32_bf16 v[22:25], v[146:149], v[240:243], v[22:25]
	v_mfma_f32_16x16x32_bf16 v[18:21], v[154:157], v[240:243], v[18:21]
	v_mfma_f32_16x16x32_bf16 v[62:65], v[150:153], v[200:203], v[62:65]
	v_mfma_f32_16x16x32_bf16 v[58:61], v[158:161], v[200:203], v[58:61]
	v_mfma_f32_16x16x32_bf16 v[54:57], v[150:153], v[208:211], v[54:57]
	v_mfma_f32_16x16x32_bf16 v[50:53], v[158:161], v[208:211], v[50:53]
	v_mfma_f32_16x16x32_bf16 v[38:41], v[150:153], v[236:239], v[38:41]
	v_mfma_f32_16x16x32_bf16 v[34:37], v[158:161], v[236:239], v[34:37]
	v_mfma_f32_16x16x32_bf16 v[22:25], v[150:153], v[244:247], v[22:25]
	v_mfma_f32_16x16x32_bf16 v[18:21], v[158:161], v[244:247], v[18:21]
	v_mfma_f32_16x16x32_bf16 v[46:49], v[180:183], v[196:199], v[46:49]
	v_mfma_f32_16x16x32_bf16 v[42:45], v[188:191], v[196:199], v[42:45]
	v_mfma_f32_16x16x32_bf16 v[30:33], v[180:183], v[204:207], v[30:33]
	v_mfma_f32_16x16x32_bf16 v[26:29], v[188:191], v[204:207], v[26:29]
	v_mfma_f32_16x16x32_bf16 v[14:17], v[180:183], v[232:235], v[14:17]
	v_mfma_f32_16x16x32_bf16 v[10:13], v[188:191], v[232:235], v[10:13]
	v_mfma_f32_16x16x32_bf16 v[6:9], v[180:183], v[240:243], v[6:9]
	v_mfma_f32_16x16x32_bf16 v[2:5], v[188:191], v[240:243], v[2:5]
	v_mfma_f32_16x16x32_bf16 v[46:49], v[184:187], v[200:203], v[46:49]
	v_mfma_f32_16x16x32_bf16 v[42:45], v[192:195], v[200:203], v[42:45]
	v_mfma_f32_16x16x32_bf16 v[30:33], v[184:187], v[208:211], v[30:33]
	v_mfma_f32_16x16x32_bf16 v[26:29], v[192:195], v[208:211], v[26:29]
	v_mfma_f32_16x16x32_bf16 v[14:17], v[184:187], v[236:239], v[14:17]
	v_mfma_f32_16x16x32_bf16 v[10:13], v[192:195], v[236:239], v[10:13]
	v_mfma_f32_16x16x32_bf16 v[6:9], v[184:187], v[244:247], v[6:9]
	v_mfma_f32_16x16x32_bf16 v[2:5], v[192:195], v[244:247], v[2:5]
	s_setprio 0
	s_barrier
	s_add_u32 s4, s4, 0x100
	s_addc_u32 s5, s5, 0
	s_add_u32 s46, s46, 0x100
	s_addc_u32 s47, s47, 0
	s_cmp_ge_u32 s49, s41
	s_mov_b32 s48, s49
	s_cbranch_scc0 .LBB0_423
	s_and_b64 vcc, exec, s[12:13]
	s_cbranch_vccz .LBB0_426
	s_barrier

; #define PG8_STAGE(bufoff, gbase, voff) do { _Pragma("unroll") for (int _i = 0; _i < 2; ++_i) \
;         __builtin_amdgcn_global_load_lds((const unsigned*)((const char*)(gbase) + (voff)[_i]), (PG8_LAS unsigned*)(lds + (bufoff) + ldsw + _i * 8192), 16, 0, 0); } while (0)
; #define PG8_LDA(dst, b, h) do { _Pragma("unroll") for (int m = 0; m < 4; ++m) _Pragma("unroll") for (int k = 0; k < 2; ++k) dst[m][k] = *(const PG8_LAS bf16x8*)(lds + PG8_SA(b, h) + aoff + m * 2048 + k * 1024); } while (0)
; #define PG8_LDB(dst, b, h) do { _Pragma("unroll") for (int n = 0; n < 2; ++n) _Pragma("unroll") for (int k = 0; k < 2; ++k) dst[n][k] = *(const PG8_LAS bf16x8*)(lds + PG8_SB(b, h) + boff + n * 2048 + k * 1024); } while (0)
; #define PG8_MMA(ai, bj, At, Bt) do { __builtin_amdgcn_s_setprio(1); _Pragma("unroll") for (int m = 0; m < 4; ++m) _Pragma("unroll") for (int n = 0; n < 2; ++n) _Pragma("unroll") for (int k = 0; k < 2; ++k) \
;         acc[ai][bj][m][n] = __builtin_amdgcn_mfma_f32_16x16x32_bf16(Bt[n][k], At[m][k], acc[ai][bj][m][n], 0, 0, 0); __builtin_amdgcn_s_setprio(0); } while (0)
; #define PG8_WAIT_V(n) asm volatile("s_waitcnt vmcnt(" #n ")" ::: "memory")
; #define PG8_BAR __builtin_amdgcn_s_barrier()
; template <class Epi, class Sched, bool ALIGN_EPI = false, bool SP2 = false>
; __device__ __forceinline__ void gemm_phase(PG8_LAS unsigned char* lds, const Gemm g, const Sched& S, const Epi& E) {
;     ...
;         for (int t = 0; t < nt; t += 2) {
;             const bool last = (t == nt - 2);
;             const char* a1 = cA + (size_t)(t + 1) * kstep;
;             const char* a2 = last ? nA : cA + (size_t)(t + 2) * kstep; const char* b2 = last ? nB : cB + (size_t)(t + 2) * kstep;
;             const char* a3 = a2 + kstep; const char* b3 = b2 + kstep;
;             if (last && has_next) S.a_ready(nxt);
;             if constexpr (SP2) {
;             PG8_LDB(B0, 0, 0); PG8_LDB(B1, 0, 1); PG8_SCHED; PG8_LDA(At, 0, 0); PG8_STAGE(PG8_SA(1, 1), a1 + hstep, voffA);
;             PG8_WAIT_V(8); PG8_WAIT_L(0); PG8_BAR; PG8_MMA(0, 0, At, B0); PG8_MMA(0, 1, At, B1); PG8_BAR; PG8_SCHED;
;             PG8_LDA(At, 0, 1); PG8_STAGE(PG8_SB(0, 0), b2, voffB); PG8_STAGE(PG8_SB(0, 1), b2 + hstep, voffB); PG8_STAGE(PG8_SA(0, 0), a2, voffA);
;             PG8_WAIT_V(8); PG8_WAIT_L(0); PG8_BAR; PG8_MMA(1, 0, At, B0); PG8_MMA(1, 1, At, B1); PG8_BAR; PG8_SCHED;
.LBB0_892:
	ds_read_b128 v[136:139], v143
	ds_read_b128 v[146:149], v143 offset:1024
	ds_read_b128 v[150:153], v143 offset:2048
	ds_read_b128 v[154:157], v143 offset:3072
	ds_read_b128 v[158:161], v144
	ds_read_b128 v[180:183], v144 offset:1024
	ds_read_b128 v[184:187], v144 offset:2048
	ds_read_b128 v[188:191], v144 offset:3072
	s_add_i32 s53, s28, 2
	s_add_u32 s29, s26, 0xfff80080
	s_addc_u32 s30, s27, -1
	s_cmp_eq_u32 s49, s28
	s_cselect_b32 s28, s48, s51
	s_cselect_b32 s31, s13, s30
	s_cselect_b32 s30, s19, s29
	s_cselect_b32 s29, s17, s52
	v_lshl_add_u64 v[212:213], s[26:27], 0, v[130:131]
	s_add_i32 m0, s3, 0xc000
	ds_read_b128 v[192:195], v145
	ds_read_b128 v[196:199], v145 offset:1024
	ds_read_b128 v[200:203], v145 offset:2048
	ds_read_b128 v[204:207], v145 offset:3072
	ds_read_b128 v[208:211], v145 offset:4096
	ds_read_b128 v[232:235], v145 offset:5120
	ds_read_b128 v[236:239], v145 offset:6144
	ds_read_b128 v[240:243], v145 offset:7168
	global_load_lds_dwordx4 v[212:213], off
	v_lshl_add_u64 v[212:213], s[26:27], 0, v[132:133]
	s_add_i32 m0, s3, 0xe000
	s_nop 0
	global_load_lds_dwordx4 v[212:213], off
	s_waitcnt vmcnt(8)
	s_waitcnt lgkmcnt(0)
	s_barrier
	s_setprio 1
	v_mfma_f32_16x16x32_bf16 v[126:129], v[136:139], v[192:195], v[126:129]
	v_mfma_f32_16x16x32_bf16 v[122:125], v[150:153], v[192:195], v[122:125]
	v_mfma_f32_16x16x32_bf16 v[118:121], v[136:139], v[200:203], v[118:121]
	v_mfma_f32_16x16x32_bf16 v[114:117], v[150:153], v[200:203], v[114:117]
	v_mfma_f32_16x16x32_bf16 v[102:105], v[136:139], v[208:211], v[102:105]
	v_mfma_f32_16x16x32_bf16 v[98:101], v[150:153], v[208:211], v[98:101]
	v_mfma_f32_16x16x32_bf16 v[86:89], v[136:139], v[236:239], v[86:89]
	v_mfma_f32_16x16x32_bf16 v[82:85], v[150:153], v[236:239], v[82:85]
	v_mfma_f32_16x16x32_bf16 v[126:129], v[146:149], v[196:199], v[126:129]
	v_mfma_f32_16x16x32_bf16 v[122:125], v[154:157], v[196:199], v[122:125]
	v_mfma_f32_16x16x32_bf16 v[118:121], v[146:149], v[204:207], v[118:121]
	v_mfma_f32_16x16x32_bf16 v[114:117], v[154:157], v[204:207], v[114:117]
	v_mfma_f32_16x16x32_bf16 v[102:105], v[146:149], v[232:235], v[102:105]
	v_mfma_f32_16x16x32_bf16 v[98:101], v[154:157], v[232:235], v[98:101]
	v_mfma_f32_16x16x32_bf16 v[86:89], v[146:149], v[240:243], v[86:89]
	v_mfma_f32_16x16x32_bf16 v[82:85], v[154:157], v[240:243], v[82:85]
	v_mfma_f32_16x16x32_bf16 v[110:113], v[158:161], v[192:195], v[110:113]
	v_mfma_f32_16x16x32_bf16 v[106:109], v[184:187], v[192:195], v[106:109]
	v_mfma_f32_16x16x32_bf16 v[94:97], v[158:161], v[200:203], v[94:97]
	v_mfma_f32_16x16x32_bf16 v[90:93], v[184:187], v[200:203], v[90:93]
	v_mfma_f32_16x16x32_bf16 v[78:81], v[158:161], v[208:211], v[78:81]
	v_mfma_f32_16x16x32_bf16 v[74:77], v[184:187], v[208:211], v[74:77]
	v_mfma_f32_16x16x32_bf16 v[70:73], v[158:161], v[236:239], v[70:73]
	v_mfma_f32_16x16x32_bf16 v[66:69], v[184:187], v[236:239], v[66:69]
	v_mfma_f32_16x16x32_bf16 v[110:113], v[180:183], v[196:199], v[110:113]
	v_mfma_f32_16x16x32_bf16 v[106:109], v[188:191], v[196:199], v[106:109]
	v_mfma_f32_16x16x32_bf16 v[94:97], v[180:183], v[204:207], v[94:97]
	v_mfma_f32_16x16x32_bf16 v[90:93], v[188:191], v[204:207], v[90:93]
	v_mfma_f32_16x16x32_bf16 v[78:81], v[180:183], v[232:235], v[78:81]
	v_mfma_f32_16x16x32_bf16 v[74:77], v[188:191], v[232:235], v[74:77]
	v_mfma_f32_16x16x32_bf16 v[70:73], v[180:183], v[240:243], v[70:73]
	v_mfma_f32_16x16x32_bf16 v[66:69], v[188:191], v[240:243], v[66:69]
	s_setprio 0
	s_barrier
	s_add_i32 s54, s42, s2
	v_lshl_add_u64 v[212:213], s[28:29], 0, v[166:167]
	s_mov_b32 m0, s54
	ds_read_b128 v[192:195], v145 offset:16384
	ds_read_b128 v[196:199], v145 offset:17408
	ds_read_b128 v[200:203], v145 offset:18432
	ds_read_b128 v[204:207], v145 offset:19456
	ds_read_b128 v[208:211], v145 offset:20480
	ds_read_b128 v[232:235], v145 offset:21504
	ds_read_b128 v[236:239], v145 offset:22528
	ds_read_b128 v[240:243], v145 offset:23552
	global_load_lds_dwordx4 v[212:213], off
	s_add_i32 m0, s54, 0x2000
	s_add_u32 s54, s28, 0x80000
	v_lshl_add_u64 v[222:223], s[28:29], 0, v[170:171]
	s_addc_u32 s55, s29, 0
	s_add_i32 s56, s43, s2
	global_load_lds_dwordx4 v[222:223], off
	v_lshl_add_u64 v[244:245], s[54:55], 0, v[166:167]
	s_mov_b32 m0, s56
	v_lshl_add_u64 v[246:247], s[30:31], 0, v[170:171]
	global_load_lds_dwordx4 v[244:245], off
	v_lshl_add_u64 v[244:245], s[54:55], 0, v[170:171]
	s_add_i32 m0, s56, 0x2000
	s_nop 0
	global_load_lds_dwordx4 v[244:245], off
	v_lshl_add_u64 v[244:245], s[30:31], 0, v[166:167]
	s_mov_b32 m0, s3
	s_nop 0
	global_load_lds_dwordx4 v[244:245], off
	s_mov_b32 m0, s15
	s_nop 0
	global_load_lds_dwordx4 v[246:247], off
	s_waitcnt vmcnt(8)
	s_waitcnt lgkmcnt(0)
	s_barrier
; #define PG8_STAGE(bufoff, gbase, voff) do { _Pragma("unroll") for (int _i = 0; _i < 2; ++_i) \
;         __builtin_amdgcn_global_load_lds((const unsigned*)((const char*)(gbase) + (voff)[_i]), (PG8_LAS unsigned*)(lds + (bufoff) + ldsw + _i * 8192), 16, 0, 0); } while (0)
; #define PG8_LDA(dst, b, h) do { _Pragma("unroll") for (int m = 0; m < 4; ++m) _Pragma("unroll") for (int k = 0; k < 2; ++k) dst[m][k] = *(const PG8_LAS bf16x8*)(lds + PG8_SA(b, h) + aoff + m * 2048 + k * 1024); } while (0)
; #define PG8_LDB(dst, b, h) do { _Pragma("unroll") for (int n = 0; n < 2; ++n) _Pragma("unroll") for (int k = 0; k < 2; ++k) dst[n][k] = *(const PG8_LAS bf16x8*)(lds + PG8_SB(b, h) + boff + n * 2048 + k * 1024); } while (0)
; #define PG8_MMA(ai, bj, At, Bt) do { __builtin_amdgcn_s_setprio(1); _Pragma("unroll") for (int m = 0; m < 4; ++m) _Pragma("unroll") for (int n = 0; n < 2; ++n) _Pragma("unroll") for (int k = 0; k < 2; ++k) \
;         acc[ai][bj][m][n] = __builtin_amdgcn_mfma_f32_16x16x32_bf16(Bt[n][k], At[m][k], acc[ai][bj][m][n], 0, 0, 0); __builtin_amdgcn_s_setprio(0); } while (0)
; #define PG8_WAIT_V(n) asm volatile("s_waitcnt vmcnt(" #n ")" ::: "memory")
; #define PG8_WAIT_L(n) asm volatile("s_waitcnt lgkmcnt(" #n ")" ::: "memory")
; #define PG8_BAR __builtin_amdgcn_s_barrier()
; #define PG8_SCHED __builtin_amdgcn_sched_barrier(0)
; template <class Epi, class Sched, bool ALIGN_EPI = false, bool SP2 = false>
; __device__ __forceinline__ void gemm_phase(PG8_LAS unsigned char* lds, const Gemm g, const Sched& S, const Epi& E) {
;     ...
;             PG8_WAIT_V(8); PG8_WAIT_L(0); PG8_BAR; PG8_MMA(1, 0, At, B0); PG8_MMA(1, 1, At, B1); PG8_BAR; PG8_SCHED;
;             PG8_LDB(B0, 1, 0); PG8_LDB(B1, 1, 1); PG8_SCHED; PG8_LDA(At, 1, 0); PG8_STAGE(PG8_SA(0, 1), a2 + hstep, voffA);
;             PG8_WAIT_V(8); PG8_WAIT_L(0); PG8_BAR; PG8_MMA(0, 0, At, B0); PG8_MMA(0, 1, At, B1); PG8_BAR; PG8_SCHED;
	s_setprio 1
	v_mfma_f32_16x16x32_bf16 v[62:65], v[136:139], v[192:195], v[62:65]
	v_mfma_f32_16x16x32_bf16 v[58:61], v[150:153], v[192:195], v[58:61]
	v_mfma_f32_16x16x32_bf16 v[54:57], v[136:139], v[200:203], v[54:57]
	v_mfma_f32_16x16x32_bf16 v[50:53], v[150:153], v[200:203], v[50:53]
	v_mfma_f32_16x16x32_bf16 v[38:41], v[136:139], v[208:211], v[38:41]
	v_mfma_f32_16x16x32_bf16 v[34:37], v[150:153], v[208:211], v[34:37]
	v_mfma_f32_16x16x32_bf16 v[22:25], v[136:139], v[236:239], v[22:25]
	v_mfma_f32_16x16x32_bf16 v[18:21], v[150:153], v[236:239], v[18:21]
	v_mfma_f32_16x16x32_bf16 v[62:65], v[146:149], v[196:199], v[62:65]
	v_mfma_f32_16x16x32_bf16 v[58:61], v[154:157], v[196:199], v[58:61]
	v_mfma_f32_16x16x32_bf16 v[54:57], v[146:149], v[204:207], v[54:57]
	v_mfma_f32_16x16x32_bf16 v[50:53], v[154:157], v[204:207], v[50:53]
	v_mfma_f32_16x16x32_bf16 v[38:41], v[146:149], v[232:235], v[38:41]
	v_mfma_f32_16x16x32_bf16 v[34:37], v[154:157], v[232:235], v[34:37]
	v_mfma_f32_16x16x32_bf16 v[22:25], v[146:149], v[240:243], v[22:25]
	v_mfma_f32_16x16x32_bf16 v[18:21], v[154:157], v[240:243], v[18:21]
	v_mfma_f32_16x16x32_bf16 v[46:49], v[158:161], v[192:195], v[46:49]
	v_mfma_f32_16x16x32_bf16 v[42:45], v[184:187], v[192:195], v[42:45]
	v_mfma_f32_16x16x32_bf16 v[30:33], v[158:161], v[200:203], v[30:33]
	v_mfma_f32_16x16x32_bf16 v[26:29], v[184:187], v[200:203], v[26:29]
	v_mfma_f32_16x16x32_bf16 v[14:17], v[158:161], v[208:211], v[14:17]
	v_mfma_f32_16x16x32_bf16 v[10:13], v[184:187], v[208:211], v[10:13]
	v_mfma_f32_16x16x32_bf16 v[6:9], v[158:161], v[236:239], v[6:9]
	v_mfma_f32_16x16x32_bf16 v[2:5], v[184:187], v[236:239], v[2:5]
	v_mfma_f32_16x16x32_bf16 v[46:49], v[180:183], v[196:199], v[46:49]
	v_mfma_f32_16x16x32_bf16 v[42:45], v[188:191], v[196:199], v[42:45]
	v_mfma_f32_16x16x32_bf16 v[30:33], v[180:183], v[204:207], v[30:33]
	v_mfma_f32_16x16x32_bf16 v[26:29], v[188:191], v[204:207], v[26:29]
	v_mfma_f32_16x16x32_bf16 v[14:17], v[180:183], v[232:235], v[14:17]
	v_mfma_f32_16x16x32_bf16 v[10:13], v[188:191], v[232:235], v[10:13]
	v_mfma_f32_16x16x32_bf16 v[6:9], v[180:183], v[240:243], v[6:9]
	v_mfma_f32_16x16x32_bf16 v[2:5], v[188:191], v[240:243], v[2:5]
	s_setprio 0
	s_barrier
	s_add_i32 s54, 0, 0x18000
	s_add_i32 s55, 0, 0x1c000
	v_add_u32_e32 v154, s54, v141
	v_add_u32_e32 v169, s55, v141
	ds_read_b128 v[136:139], v154
	ds_read_b128 v[146:149], v154 offset:1024
	ds_read_b128 v[150:153], v154 offset:2048
	ds_read_b128 v[154:157], v154 offset:3072
	ds_read_b128 v[158:161], v169
	ds_read_b128 v[180:183], v169 offset:1024
	ds_read_b128 v[184:187], v169 offset:2048
	ds_read_b128 v[188:191], v169 offset:3072
	s_add_u32 s30, s30, 0x80000
	s_addc_u32 s31, s31, 0
	s_mov_b32 m0, s33
	v_lshl_add_u64 v[248:249], s[30:31], 0, v[166:167]
	ds_read_b128 v[192:195], v145 offset:32768
	ds_read_b128 v[196:199], v145 offset:33792
	ds_read_b128 v[200:203], v145 offset:34816
	ds_read_b128 v[204:207], v145 offset:35840
	ds_read_b128 v[208:211], v145 offset:36864
	ds_read_b128 v[232:235], v145 offset:37888
	ds_read_b128 v[236:239], v145 offset:38912
	ds_read_b128 v[240:243], v145 offset:39936
	global_load_lds_dwordx4 v[248:249], off
	v_lshl_add_u64 v[248:249], s[30:31], 0, v[170:171]
	s_mov_b32 m0, s34
	s_nop 0
	global_load_lds_dwordx4 v[248:249], off
	s_waitcnt vmcnt(8)
	s_waitcnt lgkmcnt(0)
	s_barrier
	s_setprio 1
	v_mfma_f32_16x16x32_bf16 v[126:129], v[136:139], v[192:195], v[126:129]
	v_mfma_f32_16x16x32_bf16 v[122:125], v[150:153], v[192:195], v[122:125]
	v_mfma_f32_16x16x32_bf16 v[118:121], v[136:139], v[200:203], v[118:121]
	v_mfma_f32_16x16x32_bf16 v[114:117], v[150:153], v[200:203], v[114:117]
	v_mfma_f32_16x16x32_bf16 v[102:105], v[136:139], v[208:211], v[102:105]
	v_mfma_f32_16x16x32_bf16 v[98:101], v[150:153], v[208:211], v[98:101]
	v_mfma_f32_16x16x32_bf16 v[86:89], v[136:139], v[236:239], v[86:89]
	v_mfma_f32_16x16x32_bf16 v[82:85], v[150:153], v[236:239], v[82:85]
	v_mfma_f32_16x16x32_bf16 v[126:129], v[146:149], v[196:199], v[126:129]
	v_mfma_f32_16x16x32_bf16 v[122:125], v[154:157], v[196:199], v[122:125]
	v_mfma_f32_16x16x32_bf16 v[118:121], v[146:149], v[204:207], v[118:121]
	v_mfma_f32_16x16x32_bf16 v[114:117], v[154:157], v[204:207], v[114:117]
	v_mfma_f32_16x16x32_bf16 v[102:105], v[146:149], v[232:235], v[102:105]
	v_mfma_f32_16x16x32_bf16 v[98:101], v[154:157], v[232:235], v[98:101]
	v_mfma_f32_16x16x32_bf16 v[86:89], v[146:149], v[240:243], v[86:89]
	v_mfma_f32_16x16x32_bf16 v[82:85], v[154:157], v[240:243], v[82:85]
	v_mfma_f32_16x16x32_bf16 v[110:113], v[158:161], v[192:195], v[110:113]
	v_mfma_f32_16x16x32_bf16 v[106:109], v[184:187], v[192:195], v[106:109]
	v_mfma_f32_16x16x32_bf16 v[94:97], v[158:161], v[200:203], v[94:97]
	v_mfma_f32_16x16x32_bf16 v[90:93], v[184:187], v[200:203], v[90:93]
	v_mfma_f32_16x16x32_bf16 v[78:81], v[158:161], v[208:211], v[78:81]
	v_mfma_f32_16x16x32_bf16 v[74:77], v[184:187], v[208:211], v[74:77]
	v_mfma_f32_16x16x32_bf16 v[70:73], v[158:161], v[236:239], v[70:73]
	v_mfma_f32_16x16x32_bf16 v[66:69], v[184:187], v[236:239], v[66:69]
	v_mfma_f32_16x16x32_bf16 v[110:113], v[180:183], v[196:199], v[110:113]
	v_mfma_f32_16x16x32_bf16 v[106:109], v[188:191], v[196:199], v[106:109]
	v_mfma_f32_16x16x32_bf16 v[94:97], v[180:183], v[204:207], v[94:97]
	v_mfma_f32_16x16x32_bf16 v[90:93], v[188:191], v[204:207], v[90:93]
	v_mfma_f32_16x16x32_bf16 v[78:81], v[180:183], v[232:235], v[78:81]
	v_mfma_f32_16x16x32_bf16 v[74:77], v[188:191], v[232:235], v[74:77]
	v_mfma_f32_16x16x32_bf16 v[70:73], v[180:183], v[240:243], v[70:73]
	v_mfma_f32_16x16x32_bf16 v[66:69], v[188:191], v[240:243], v[66:69]
	s_setprio 0
	s_barrier
; #define PG8_STAGE(bufoff, gbase, voff) do { _Pragma("unroll") for (int _i = 0; _i < 2; ++_i) \
;         __builtin_amdgcn_global_load_lds((const unsigned*)((const char*)(gbase) + (voff)[_i]), (PG8_LAS unsigned*)(lds + (bufoff) + ldsw + _i * 8192), 16, 0, 0); } while (0)
; #define PG8_LDA(dst, b, h) do { _Pragma("unroll") for (int m = 0; m < 4; ++m) _Pragma("unroll") for (int k = 0; k < 2; ++k) dst[m][k] = *(const PG8_LAS bf16x8*)(lds + PG8_SA(b, h) + aoff + m * 2048 + k * 1024); } while (0)
; #define PG8_WAIT_V(n) asm volatile("s_waitcnt vmcnt(" #n ")" ::: "memory")
; template <class Epi, class Sched, bool ALIGN_EPI = false, bool SP2 = false>
; __device__ __forceinline__ void gemm_phase(PG8_LAS unsigned char* lds, const Gemm g, const Sched& S, const Epi& E) {
;     ...
;             PG8_LDA(At, 1, 1); PG8_STAGE(PG8_SB(1, 0), b3, voffB); PG8_STAGE(PG8_SB(1, 1), b3 + hstep, voffB); PG8_STAGE(PG8_SA(1, 0), a3, voffA);
;             PG8_WAIT_V(8); PG8_WAIT_L(0); PG8_BAR; PG8_MMA(1, 0, At, B0); PG8_MMA(1, 1, At, B1); PG8_BAR; PG8_SCHED;
;             } else {
;             PG8_LDB(B0, 0, 0); PG8_SCHED; PG8_LDA(At, 0, 0); PG8_STAGE(PG8_SA(1, 1), a1 + hstep, voffA);
;             PG8_WAIT_L(8); PG8_BAR; PG8_WAIT_L(0); PG8_MMA(0, 0, At, B0); PG8_BAR; PG8_SCHED;
;             PG8_LDB(B1, 0, 1); PG8_STAGE(PG8_SB(0, 0), b2, voffB);
;             PG8_BAR; PG8_WAIT_L(0); PG8_MMA(0, 1, At, B1); PG8_BAR;
;             PG8_LDA(At, 0, 1); PG8_STAGE(PG8_SA(0, 0), a2, voffA);
;             PG8_BAR; PG8_WAIT_L(0); PG8_MMA(1, 0, At, B0); PG8_BAR; PG8_SCHED;
;             PG8_STAGE(PG8_SB(0, 1), b2 + hstep, voffB);
;             PG8_WAIT_V(6); PG8_BAR; PG8_MMA(1, 1, At, B1); PG8_BAR;
;             PG8_LDB(B0, 1, 0); PG8_SCHED; PG8_LDA(At, 1, 0); PG8_STAGE(PG8_SA(0, 1), a2 + hstep, voffA);
;             PG8_WAIT_L(8); PG8_BAR; PG8_WAIT_L(0); PG8_MMA(0, 0, At, B0); PG8_BAR; PG8_SCHED;
;             PG8_LDB(B1, 1, 1); PG8_STAGE(PG8_SB(1, 0), b3, voffB);
;             PG8_BAR; PG8_WAIT_L(0); PG8_MMA(0, 1, At, B1); PG8_BAR;
;             PG8_LDA(At, 1, 1); PG8_STAGE(PG8_SA(1, 0), a3, voffA);
;             PG8_BAR; PG8_WAIT_L(0); PG8_MMA(1, 0, At, B0); PG8_BAR; PG8_SCHED;
;             PG8_STAGE(PG8_SB(1, 1), b3 + hstep, voffB);
;             PG8_WAIT_V(6); PG8_BAR; PG8_MMA(1, 1, At, B1); PG8_BAR;
;             }
;         }
;         if constexpr (ALIGN_EPI) { if (wr == 0) PG8_BAR; }
	s_add_i32 s30, s54, s2
	v_lshl_add_u64 v[212:213], v[212:213], 0, s[6:7]
	s_mov_b32 m0, s30
	ds_read_b128 v[192:195], v145 offset:49152
	ds_read_b128 v[196:199], v145 offset:50176
	ds_read_b128 v[200:203], v145 offset:51200
	ds_read_b128 v[204:207], v145 offset:52224
	ds_read_b128 v[208:211], v145 offset:53248
	ds_read_b128 v[232:235], v145 offset:54272
	ds_read_b128 v[236:239], v145 offset:55296
	ds_read_b128 v[240:243], v145 offset:56320
	global_load_lds_dwordx4 v[212:213], off
	s_add_i32 m0, s30, 0x2000
	s_add_u32 s28, s28, 0x80080
	v_lshl_add_u64 v[212:213], v[222:223], 0, s[6:7]
	s_addc_u32 s29, s29, 0
	s_add_i32 s30, s55, s2
	global_load_lds_dwordx4 v[212:213], off
	v_lshl_add_u64 v[212:213], s[28:29], 0, v[166:167]
	s_mov_b32 m0, s30
	s_nop 0
	global_load_lds_dwordx4 v[212:213], off
	v_lshl_add_u64 v[212:213], s[28:29], 0, v[170:171]
	s_add_i32 m0, s30, 0x2000
	s_nop 0
	global_load_lds_dwordx4 v[212:213], off
	v_lshl_add_u64 v[212:213], v[244:245], 0, s[6:7]
	s_mov_b32 m0, s35
	s_nop 0
	global_load_lds_dwordx4 v[212:213], off
	v_lshl_add_u64 v[212:213], v[246:247], 0, s[6:7]
	s_mov_b32 m0, s36
	s_nop 0
	global_load_lds_dwordx4 v[212:213], off
	s_waitcnt vmcnt(8)
	s_waitcnt lgkmcnt(0)
	s_barrier
	s_setprio 1
	v_mfma_f32_16x16x32_bf16 v[62:65], v[136:139], v[192:195], v[62:65]
	v_mfma_f32_16x16x32_bf16 v[58:61], v[150:153], v[192:195], v[58:61]
	v_mfma_f32_16x16x32_bf16 v[54:57], v[136:139], v[200:203], v[54:57]
	v_mfma_f32_16x16x32_bf16 v[50:53], v[150:153], v[200:203], v[50:53]
	v_mfma_f32_16x16x32_bf16 v[38:41], v[136:139], v[208:211], v[38:41]
	v_mfma_f32_16x16x32_bf16 v[34:37], v[150:153], v[208:211], v[34:37]
	v_mfma_f32_16x16x32_bf16 v[22:25], v[136:139], v[236:239], v[22:25]
	v_mfma_f32_16x16x32_bf16 v[18:21], v[150:153], v[236:239], v[18:21]
	v_mfma_f32_16x16x32_bf16 v[62:65], v[146:149], v[196:199], v[62:65]
	v_mfma_f32_16x16x32_bf16 v[58:61], v[154:157], v[196:199], v[58:61]
	v_mfma_f32_16x16x32_bf16 v[54:57], v[146:149], v[204:207], v[54:57]
	v_mfma_f32_16x16x32_bf16 v[50:53], v[154:157], v[204:207], v[50:53]
	v_mfma_f32_16x16x32_bf16 v[38:41], v[146:149], v[232:235], v[38:41]
	v_mfma_f32_16x16x32_bf16 v[34:37], v[154:157], v[232:235], v[34:37]
	v_mfma_f32_16x16x32_bf16 v[22:25], v[146:149], v[240:243], v[22:25]
	v_mfma_f32_16x16x32_bf16 v[18:21], v[154:157], v[240:243], v[18:21]
	v_mfma_f32_16x16x32_bf16 v[46:49], v[158:161], v[192:195], v[46:49]
	v_mfma_f32_16x16x32_bf16 v[42:45], v[184:187], v[192:195], v[42:45]
	v_mfma_f32_16x16x32_bf16 v[30:33], v[158:161], v[200:203], v[30:33]
	v_mfma_f32_16x16x32_bf16 v[26:29], v[184:187], v[200:203], v[26:29]
	v_mfma_f32_16x16x32_bf16 v[14:17], v[158:161], v[208:211], v[14:17]
	v_mfma_f32_16x16x32_bf16 v[10:13], v[184:187], v[208:211], v[10:13]
	v_mfma_f32_16x16x32_bf16 v[6:9], v[158:161], v[236:239], v[6:9]
	v_mfma_f32_16x16x32_bf16 v[2:5], v[184:187], v[236:239], v[2:5]
	v_mfma_f32_16x16x32_bf16 v[46:49], v[180:183], v[196:199], v[46:49]
	v_mfma_f32_16x16x32_bf16 v[42:45], v[188:191], v[196:199], v[42:45]
	v_mfma_f32_16x16x32_bf16 v[30:33], v[180:183], v[204:207], v[30:33]
	v_mfma_f32_16x16x32_bf16 v[26:29], v[188:191], v[204:207], v[26:29]
	v_mfma_f32_16x16x32_bf16 v[14:17], v[180:183], v[232:235], v[14:17]
	v_mfma_f32_16x16x32_bf16 v[10:13], v[188:191], v[232:235], v[10:13]
	v_mfma_f32_16x16x32_bf16 v[6:9], v[180:183], v[240:243], v[6:9]
	v_mfma_f32_16x16x32_bf16 v[2:5], v[188:191], v[240:243], v[2:5]
	s_setprio 0
	s_barrier
	s_add_u32 s26, s26, 0x100
	s_addc_u32 s27, s27, 0
	s_add_u32 s51, s51, 0x100
	s_addc_u32 s52, s52, 0
	s_cmp_ge_u32 s53, s45
	s_mov_b32 s28, s53
	s_cbranch_scc0 .LBB0_892
	s_and_b64 vcc, exec, s[8:9]
	s_cbranch_vccz .LBB0_895
	s_barrier

; #define PG8_STAGE(bufoff, gbase, voff) do { _Pragma("unroll") for (int _i = 0; _i < 2; ++_i) \
;         __builtin_amdgcn_global_load_lds((const unsigned*)((const char*)(gbase) + (voff)[_i]), (PG8_LAS unsigned*)(lds + (bufoff) + ldsw + _i * 8192), 16, 0, 0); } while (0)
; #define PG8_LDA(dst, b, h) do { _Pragma("unroll") for (int m = 0; m < 4; ++m) _Pragma("unroll") for (int k = 0; k < 2; ++k) dst[m][k] = *(const PG8_LAS bf16x8*)(lds + PG8_SA(b, h) + aoff + m * 2048 + k * 1024); } while (0)
; #define PG8_LDB(dst, b, h) do { _Pragma("unroll") for (int n = 0; n < 2; ++n) _Pragma("unroll") for (int k = 0; k < 2; ++k) dst[n][k] = *(const PG8_LAS bf16x8*)(lds + PG8_SB(b, h) + boff + n * 2048 + k * 1024); } while (0)
; #define PG8_MMA(ai, bj, At, Bt) do { __builtin_amdgcn_s_setprio(1); _Pragma("unroll") for (int m = 0; m < 4; ++m) _Pragma("unroll") for (int n = 0; n < 2; ++n) _Pragma("unroll") for (int k = 0; k < 2; ++k) \
;         acc[ai][bj][m][n] = __builtin_amdgcn_mfma_f32_16x16x32_bf16(Bt[n][k], At[m][k], acc[ai][bj][m][n], 0, 0, 0); __builtin_amdgcn_s_setprio(0); } while (0)
; #define PG8_WAIT_V(n) asm volatile("s_waitcnt vmcnt(" #n ")" ::: "memory")
; #define PG8_BAR __builtin_amdgcn_s_barrier()
; template <class Epi, class Sched, bool ALIGN_EPI = false, bool SP2 = false>
; __device__ __forceinline__ void gemm_phase(PG8_LAS unsigned char* lds, const Gemm g, const Sched& S, const Epi& E) {
;     ...
;         for (int t = 0; t < nt; t += 2) {
;             const bool last = (t == nt - 2);
;             const char* a1 = cA + (size_t)(t + 1) * kstep;
;             const char* a2 = last ? nA : cA + (size_t)(t + 2) * kstep; const char* b2 = last ? nB : cB + (size_t)(t + 2) * kstep;
;             const char* a3 = a2 + kstep; const char* b3 = b2 + kstep;
;             if (last && has_next) S.a_ready(nxt);
;             if constexpr (SP2) {
;             PG8_LDB(B0, 0, 0); PG8_LDB(B1, 0, 1); PG8_SCHED; PG8_LDA(At, 0, 0); PG8_STAGE(PG8_SA(1, 1), a1 + hstep, voffA);
;             PG8_WAIT_V(8); PG8_WAIT_L(0); PG8_BAR; PG8_MMA(0, 0, At, B0); PG8_MMA(0, 1, At, B1); PG8_BAR; PG8_SCHED;
;             PG8_LDA(At, 0, 1); PG8_STAGE(PG8_SB(0, 0), b2, voffB); PG8_STAGE(PG8_SB(0, 1), b2 + hstep, voffB); PG8_STAGE(PG8_SA(0, 0), a2, voffA);
;             PG8_WAIT_V(8); PG8_WAIT_L(0); PG8_BAR; PG8_MMA(1, 0, At, B0); PG8_MMA(1, 1, At, B1); PG8_BAR; PG8_SCHED;
.LBB0_1029:
	ds_read_b128 v[144:147], v141
	ds_read_b128 v[148:151], v141 offset:1024
	ds_read_b128 v[152:155], v141 offset:2048
	ds_read_b128 v[156:159], v141 offset:3072
	ds_read_b128 v[180:183], v142
	ds_read_b128 v[184:187], v142 offset:1024
	ds_read_b128 v[188:191], v142 offset:2048
	ds_read_b128 v[192:195], v142 offset:3072
	s_add_i32 s45, s44, 2
	s_add_u32 s22, s6, 0xfff80080
	s_addc_u32 s23, s7, -1
	s_cmp_eq_u32 s41, s44
	s_cselect_b32 s25, s17, s23
	s_cselect_b32 s24, s39, s22
	s_cselect_b32 s23, s15, s43
	s_cselect_b32 s22, s40, s42
	v_lshl_add_u64 v[160:161], s[6:7], 0, v[130:131]
	s_add_i32 m0, s13, 0xc000
	ds_read_b128 v[196:199], v143
	ds_read_b128 v[200:203], v143 offset:1024
	ds_read_b128 v[204:207], v143 offset:2048
	ds_read_b128 v[208:211], v143 offset:3072
	ds_read_b128 v[232:235], v143 offset:4096
	ds_read_b128 v[236:239], v143 offset:5120
	ds_read_b128 v[240:243], v143 offset:6144
	ds_read_b128 v[244:247], v143 offset:7168
	global_load_lds_dwordx4 v[160:161], off
	v_lshl_add_u64 v[160:161], s[6:7], 0, v[132:133]
	s_add_i32 m0, s13, 0xe000
	s_nop 0
	global_load_lds_dwordx4 v[160:161], off
	s_waitcnt vmcnt(8)
	s_waitcnt lgkmcnt(0)
	s_barrier
	s_setprio 1
	v_mfma_f32_16x16x32_bf16 v[126:129], v[144:147], v[196:199], v[126:129]
	v_mfma_f32_16x16x32_bf16 v[122:125], v[152:155], v[196:199], v[122:125]
	v_mfma_f32_16x16x32_bf16 v[118:121], v[144:147], v[204:207], v[118:121]
	v_mfma_f32_16x16x32_bf16 v[114:117], v[152:155], v[204:207], v[114:117]
	v_mfma_f32_16x16x32_bf16 v[102:105], v[144:147], v[232:235], v[102:105]
	v_mfma_f32_16x16x32_bf16 v[98:101], v[152:155], v[232:235], v[98:101]
	v_mfma_f32_16x16x32_bf16 v[86:89], v[144:147], v[240:243], v[86:89]
	v_mfma_f32_16x16x32_bf16 v[82:85], v[152:155], v[240:243], v[82:85]
	v_mfma_f32_16x16x32_bf16 v[126:129], v[148:151], v[200:203], v[126:129]
	v_mfma_f32_16x16x32_bf16 v[122:125], v[156:159], v[200:203], v[122:125]
	v_mfma_f32_16x16x32_bf16 v[118:121], v[148:151], v[208:211], v[118:121]
	v_mfma_f32_16x16x32_bf16 v[114:117], v[156:159], v[208:211], v[114:117]
	v_mfma_f32_16x16x32_bf16 v[102:105], v[148:151], v[236:239], v[102:105]
	v_mfma_f32_16x16x32_bf16 v[98:101], v[156:159], v[236:239], v[98:101]
	v_mfma_f32_16x16x32_bf16 v[86:89], v[148:151], v[244:247], v[86:89]
	v_mfma_f32_16x16x32_bf16 v[82:85], v[156:159], v[244:247], v[82:85]
	v_mfma_f32_16x16x32_bf16 v[110:113], v[180:183], v[196:199], v[110:113]
	v_mfma_f32_16x16x32_bf16 v[106:109], v[188:191], v[196:199], v[106:109]
	v_mfma_f32_16x16x32_bf16 v[94:97], v[180:183], v[204:207], v[94:97]
	v_mfma_f32_16x16x32_bf16 v[90:93], v[188:191], v[204:207], v[90:93]
	v_mfma_f32_16x16x32_bf16 v[78:81], v[180:183], v[232:235], v[78:81]
	v_mfma_f32_16x16x32_bf16 v[74:77], v[188:191], v[232:235], v[74:77]
	v_mfma_f32_16x16x32_bf16 v[70:73], v[180:183], v[240:243], v[70:73]
	v_mfma_f32_16x16x32_bf16 v[66:69], v[188:191], v[240:243], v[66:69]
	v_mfma_f32_16x16x32_bf16 v[110:113], v[184:187], v[200:203], v[110:113]
	v_mfma_f32_16x16x32_bf16 v[106:109], v[192:195], v[200:203], v[106:109]
	v_mfma_f32_16x16x32_bf16 v[94:97], v[184:187], v[208:211], v[94:97]
	v_mfma_f32_16x16x32_bf16 v[90:93], v[192:195], v[208:211], v[90:93]
	v_mfma_f32_16x16x32_bf16 v[78:81], v[184:187], v[236:239], v[78:81]
	v_mfma_f32_16x16x32_bf16 v[74:77], v[192:195], v[236:239], v[74:77]
	v_mfma_f32_16x16x32_bf16 v[70:73], v[184:187], v[244:247], v[70:73]
	v_mfma_f32_16x16x32_bf16 v[66:69], v[192:195], v[244:247], v[66:69]
	s_setprio 0
	s_barrier
	s_add_i32 s44, s34, s2
	v_lshl_add_u64 v[160:161], s[22:23], 0, v[168:169]
	s_mov_b32 m0, s44
	ds_read_b128 v[196:199], v143 offset:16384
	ds_read_b128 v[200:203], v143 offset:17408
	ds_read_b128 v[204:207], v143 offset:18432
	ds_read_b128 v[208:211], v143 offset:19456
	ds_read_b128 v[232:235], v143 offset:20480
	ds_read_b128 v[236:239], v143 offset:21504
	ds_read_b128 v[240:243], v143 offset:22528
	ds_read_b128 v[244:247], v143 offset:23552
	global_load_lds_dwordx4 v[160:161], off
	s_add_i32 m0, s44, 0x2000
	s_add_u32 s46, s22, 0x80000
	v_lshl_add_u64 v[212:213], s[22:23], 0, v[172:173]
	s_addc_u32 s47, s23, 0
	s_add_i32 s44, s35, s2
	global_load_lds_dwordx4 v[212:213], off
	v_lshl_add_u64 v[222:223], s[46:47], 0, v[168:169]
	s_mov_b32 m0, s44
	v_lshl_add_u64 v[248:249], s[24:25], 0, v[170:171]
	global_load_lds_dwordx4 v[222:223], off
	v_lshl_add_u64 v[222:223], s[46:47], 0, v[172:173]
	s_add_i32 m0, s44, 0x2000
	s_nop 0
	global_load_lds_dwordx4 v[222:223], off
	v_lshl_add_u64 v[222:223], s[24:25], 0, v[166:167]
	s_mov_b32 m0, s13
	s_nop 0
	global_load_lds_dwordx4 v[222:223], off
	s_mov_b32 m0, s26
	s_nop 0
	global_load_lds_dwordx4 v[248:249], off
	s_waitcnt vmcnt(8)
	s_waitcnt lgkmcnt(0)
	s_barrier
; #define PG8_STAGE(bufoff, gbase, voff) do { _Pragma("unroll") for (int _i = 0; _i < 2; ++_i) \
;         __builtin_amdgcn_global_load_lds((const unsigned*)((const char*)(gbase) + (voff)[_i]), (PG8_LAS unsigned*)(lds + (bufoff) + ldsw + _i * 8192), 16, 0, 0); } while (0)
; #define PG8_LDA(dst, b, h) do { _Pragma("unroll") for (int m = 0; m < 4; ++m) _Pragma("unroll") for (int k = 0; k < 2; ++k) dst[m][k] = *(const PG8_LAS bf16x8*)(lds + PG8_SA(b, h) + aoff + m * 2048 + k * 1024); } while (0)
; #define PG8_LDB(dst, b, h) do { _Pragma("unroll") for (int n = 0; n < 2; ++n) _Pragma("unroll") for (int k = 0; k < 2; ++k) dst[n][k] = *(const PG8_LAS bf16x8*)(lds + PG8_SB(b, h) + boff + n * 2048 + k * 1024); } while (0)
; #define PG8_MMA(ai, bj, At, Bt) do { __builtin_amdgcn_s_setprio(1); _Pragma("unroll") for (int m = 0; m < 4; ++m) _Pragma("unroll") for (int n = 0; n < 2; ++n) _Pragma("unroll") for (int k = 0; k < 2; ++k) \
;         acc[ai][bj][m][n] = __builtin_amdgcn_mfma_f32_16x16x32_bf16(Bt[n][k], At[m][k], acc[ai][bj][m][n], 0, 0, 0); __builtin_amdgcn_s_setprio(0); } while (0)
; #define PG8_WAIT_V(n) asm volatile("s_waitcnt vmcnt(" #n ")" ::: "memory")
; #define PG8_WAIT_L(n) asm volatile("s_waitcnt lgkmcnt(" #n ")" ::: "memory")
; #define PG8_BAR __builtin_amdgcn_s_barrier()
; #define PG8_SCHED __builtin_amdgcn_sched_barrier(0)
; template <class Epi, class Sched, bool ALIGN_EPI = false, bool SP2 = false>
; __device__ __forceinline__ void gemm_phase(PG8_LAS unsigned char* lds, const Gemm g, const Sched& S, const Epi& E) {
;     ...
;             PG8_WAIT_V(8); PG8_WAIT_L(0); PG8_BAR; PG8_MMA(1, 0, At, B0); PG8_MMA(1, 1, At, B1); PG8_BAR; PG8_SCHED;
;             PG8_LDB(B0, 1, 0); PG8_LDB(B1, 1, 1); PG8_SCHED; PG8_LDA(At, 1, 0); PG8_STAGE(PG8_SA(0, 1), a2 + hstep, voffA);
;             PG8_WAIT_V(8); PG8_WAIT_L(0); PG8_BAR; PG8_MMA(0, 0, At, B0); PG8_MMA(0, 1, At, B1); PG8_BAR; PG8_SCHED;
	s_setprio 1
	v_mfma_f32_16x16x32_bf16 v[62:65], v[144:147], v[196:199], v[62:65]
	v_mfma_f32_16x16x32_bf16 v[58:61], v[152:155], v[196:199], v[58:61]
	v_mfma_f32_16x16x32_bf16 v[54:57], v[144:147], v[204:207], v[54:57]
	v_mfma_f32_16x16x32_bf16 v[50:53], v[152:155], v[204:207], v[50:53]
	v_mfma_f32_16x16x32_bf16 v[38:41], v[144:147], v[232:235], v[38:41]
	v_mfma_f32_16x16x32_bf16 v[34:37], v[152:155], v[232:235], v[34:37]
	v_mfma_f32_16x16x32_bf16 v[22:25], v[144:147], v[240:243], v[22:25]
	v_mfma_f32_16x16x32_bf16 v[18:21], v[152:155], v[240:243], v[18:21]
	v_mfma_f32_16x16x32_bf16 v[62:65], v[148:151], v[200:203], v[62:65]
	v_mfma_f32_16x16x32_bf16 v[58:61], v[156:159], v[200:203], v[58:61]
	v_mfma_f32_16x16x32_bf16 v[54:57], v[148:151], v[208:211], v[54:57]
	v_mfma_f32_16x16x32_bf16 v[50:53], v[156:159], v[208:211], v[50:53]
	v_mfma_f32_16x16x32_bf16 v[38:41], v[148:151], v[236:239], v[38:41]
	v_mfma_f32_16x16x32_bf16 v[34:37], v[156:159], v[236:239], v[34:37]
	v_mfma_f32_16x16x32_bf16 v[22:25], v[148:151], v[244:247], v[22:25]
	v_mfma_f32_16x16x32_bf16 v[18:21], v[156:159], v[244:247], v[18:21]
	v_mfma_f32_16x16x32_bf16 v[46:49], v[180:183], v[196:199], v[46:49]
	v_mfma_f32_16x16x32_bf16 v[42:45], v[188:191], v[196:199], v[42:45]
	v_mfma_f32_16x16x32_bf16 v[30:33], v[180:183], v[204:207], v[30:33]
	v_mfma_f32_16x16x32_bf16 v[26:29], v[188:191], v[204:207], v[26:29]
	v_mfma_f32_16x16x32_bf16 v[14:17], v[180:183], v[232:235], v[14:17]
	v_mfma_f32_16x16x32_bf16 v[10:13], v[188:191], v[232:235], v[10:13]
	v_mfma_f32_16x16x32_bf16 v[6:9], v[180:183], v[240:243], v[6:9]
	v_mfma_f32_16x16x32_bf16 v[2:5], v[188:191], v[240:243], v[2:5]
	v_mfma_f32_16x16x32_bf16 v[46:49], v[184:187], v[200:203], v[46:49]
	v_mfma_f32_16x16x32_bf16 v[42:45], v[192:195], v[200:203], v[42:45]
	v_mfma_f32_16x16x32_bf16 v[30:33], v[184:187], v[208:211], v[30:33]
	v_mfma_f32_16x16x32_bf16 v[26:29], v[192:195], v[208:211], v[26:29]
	v_mfma_f32_16x16x32_bf16 v[14:17], v[184:187], v[236:239], v[14:17]
	v_mfma_f32_16x16x32_bf16 v[10:13], v[192:195], v[236:239], v[10:13]
	v_mfma_f32_16x16x32_bf16 v[6:9], v[184:187], v[244:247], v[6:9]
	v_mfma_f32_16x16x32_bf16 v[2:5], v[192:195], v[244:247], v[2:5]
	s_setprio 0
	s_barrier
	s_add_i32 s44, 0, 0x18000
	s_add_i32 s46, 0, 0x1c000
	v_add_u32_e32 v156, s44, v139
	v_add_u32_e32 v192, s46, v139
	ds_read_b128 v[144:147], v156
	ds_read_b128 v[148:151], v156 offset:1024
	ds_read_b128 v[152:155], v156 offset:2048
	ds_read_b128 v[156:159], v156 offset:3072
	ds_read_b128 v[180:183], v192
	ds_read_b128 v[184:187], v192 offset:1024
	ds_read_b128 v[188:191], v192 offset:2048
	ds_read_b128 v[192:195], v192 offset:3072
	s_add_u32 s24, s24, 0x80000
	s_addc_u32 s25, s25, 0
	s_mov_b32 m0, s27
	v_lshl_add_u64 v[250:251], s[24:25], 0, v[166:167]
	ds_read_b128 v[196:199], v143 offset:32768
	ds_read_b128 v[200:203], v143 offset:33792
	ds_read_b128 v[204:207], v143 offset:34816
	ds_read_b128 v[208:211], v143 offset:35840
	ds_read_b128 v[232:235], v143 offset:36864
	ds_read_b128 v[236:239], v143 offset:37888
	ds_read_b128 v[240:243], v143 offset:38912
	ds_read_b128 v[244:247], v143 offset:39936
	global_load_lds_dwordx4 v[250:251], off
	v_lshl_add_u64 v[250:251], s[24:25], 0, v[170:171]
	s_mov_b32 m0, s28
	s_nop 0
	global_load_lds_dwordx4 v[250:251], off
	s_waitcnt vmcnt(8)
	s_waitcnt lgkmcnt(0)
	s_barrier
	s_setprio 1
	v_mfma_f32_16x16x32_bf16 v[126:129], v[144:147], v[196:199], v[126:129]
	v_mfma_f32_16x16x32_bf16 v[122:125], v[152:155], v[196:199], v[122:125]
	v_mfma_f32_16x16x32_bf16 v[118:121], v[144:147], v[204:207], v[118:121]
	v_mfma_f32_16x16x32_bf16 v[114:117], v[152:155], v[204:207], v[114:117]
	v_mfma_f32_16x16x32_bf16 v[102:105], v[144:147], v[232:235], v[102:105]
	v_mfma_f32_16x16x32_bf16 v[98:101], v[152:155], v[232:235], v[98:101]
	v_mfma_f32_16x16x32_bf16 v[86:89], v[144:147], v[240:243], v[86:89]
	v_mfma_f32_16x16x32_bf16 v[82:85], v[152:155], v[240:243], v[82:85]
	v_mfma_f32_16x16x32_bf16 v[126:129], v[148:151], v[200:203], v[126:129]
	v_mfma_f32_16x16x32_bf16 v[122:125], v[156:159], v[200:203], v[122:125]
	v_mfma_f32_16x16x32_bf16 v[118:121], v[148:151], v[208:211], v[118:121]
	v_mfma_f32_16x16x32_bf16 v[114:117], v[156:159], v[208:211], v[114:117]
	v_mfma_f32_16x16x32_bf16 v[102:105], v[148:151], v[236:239], v[102:105]
	v_mfma_f32_16x16x32_bf16 v[98:101], v[156:159], v[236:239], v[98:101]
	v_mfma_f32_16x16x32_bf16 v[86:89], v[148:151], v[244:247], v[86:89]
	v_mfma_f32_16x16x32_bf16 v[82:85], v[156:159], v[244:247], v[82:85]
	v_mfma_f32_16x16x32_bf16 v[110:113], v[180:183], v[196:199], v[110:113]
	v_mfma_f32_16x16x32_bf16 v[106:109], v[188:191], v[196:199], v[106:109]
	v_mfma_f32_16x16x32_bf16 v[94:97], v[180:183], v[204:207], v[94:97]
	v_mfma_f32_16x16x32_bf16 v[90:93], v[188:191], v[204:207], v[90:93]
	v_mfma_f32_16x16x32_bf16 v[78:81], v[180:183], v[232:235], v[78:81]
	v_mfma_f32_16x16x32_bf16 v[74:77], v[188:191], v[232:235], v[74:77]
	v_mfma_f32_16x16x32_bf16 v[70:73], v[180:183], v[240:243], v[70:73]
	v_mfma_f32_16x16x32_bf16 v[66:69], v[188:191], v[240:243], v[66:69]
	v_mfma_f32_16x16x32_bf16 v[110:113], v[184:187], v[200:203], v[110:113]
	v_mfma_f32_16x16x32_bf16 v[106:109], v[192:195], v[200:203], v[106:109]
	v_mfma_f32_16x16x32_bf16 v[94:97], v[184:187], v[208:211], v[94:97]
	v_mfma_f32_16x16x32_bf16 v[90:93], v[192:195], v[208:211], v[90:93]
	v_mfma_f32_16x16x32_bf16 v[78:81], v[184:187], v[236:239], v[78:81]
	v_mfma_f32_16x16x32_bf16 v[74:77], v[192:195], v[236:239], v[74:77]
	v_mfma_f32_16x16x32_bf16 v[70:73], v[184:187], v[244:247], v[70:73]
	v_mfma_f32_16x16x32_bf16 v[66:69], v[192:195], v[244:247], v[66:69]
	s_setprio 0
	s_barrier
; #define PG8_STAGE(bufoff, gbase, voff) do { _Pragma("unroll") for (int _i = 0; _i < 2; ++_i) \
;         __builtin_amdgcn_global_load_lds((const unsigned*)((const char*)(gbase) + (voff)[_i]), (PG8_LAS unsigned*)(lds + (bufoff) + ldsw + _i * 8192), 16, 0, 0); } while (0)
; #define PG8_LDA(dst, b, h) do { _Pragma("unroll") for (int m = 0; m < 4; ++m) _Pragma("unroll") for (int k = 0; k < 2; ++k) dst[m][k] = *(const PG8_LAS bf16x8*)(lds + PG8_SA(b, h) + aoff + m * 2048 + k * 1024); } while (0)
; #define PG8_WAIT_V(n) asm volatile("s_waitcnt vmcnt(" #n ")" ::: "memory")
; template <class Epi, class Sched, bool ALIGN_EPI = false, bool SP2 = false>
; __device__ __forceinline__ void gemm_phase(PG8_LAS unsigned char* lds, const Gemm g, const Sched& S, const Epi& E) {
;     ...
;             PG8_LDA(At, 1, 1); PG8_STAGE(PG8_SB(1, 0), b3, voffB); PG8_STAGE(PG8_SB(1, 1), b3 + hstep, voffB); PG8_STAGE(PG8_SA(1, 0), a3, voffA);
;             PG8_WAIT_V(8); PG8_WAIT_L(0); PG8_BAR; PG8_MMA(1, 0, At, B0); PG8_MMA(1, 1, At, B1); PG8_BAR; PG8_SCHED;
;             } else {
;             PG8_LDB(B0, 0, 0); PG8_SCHED; PG8_LDA(At, 0, 0); PG8_STAGE(PG8_SA(1, 1), a1 + hstep, voffA);
;             PG8_WAIT_L(8); PG8_BAR; PG8_WAIT_L(0); PG8_MMA(0, 0, At, B0); PG8_BAR; PG8_SCHED;
;             PG8_LDB(B1, 0, 1); PG8_STAGE(PG8_SB(0, 0), b2, voffB);
;             PG8_BAR; PG8_WAIT_L(0); PG8_MMA(0, 1, At, B1); PG8_BAR;
;             PG8_LDA(At, 0, 1); PG8_STAGE(PG8_SA(0, 0), a2, voffA);
;             PG8_BAR; PG8_WAIT_L(0); PG8_MMA(1, 0, At, B0); PG8_BAR; PG8_SCHED;
;             PG8_STAGE(PG8_SB(0, 1), b2 + hstep, voffB);
;             PG8_WAIT_V(6); PG8_BAR; PG8_MMA(1, 1, At, B1); PG8_BAR;
;             PG8_LDB(B0, 1, 0); PG8_SCHED; PG8_LDA(At, 1, 0); PG8_STAGE(PG8_SA(0, 1), a2 + hstep, voffA);
;             PG8_WAIT_L(8); PG8_BAR; PG8_WAIT_L(0); PG8_MMA(0, 0, At, B0); PG8_BAR; PG8_SCHED;
;             PG8_LDB(B1, 1, 1); PG8_STAGE(PG8_SB(1, 0), b3, voffB);
;             PG8_BAR; PG8_WAIT_L(0); PG8_MMA(0, 1, At, B1); PG8_BAR;
;             PG8_LDA(At, 1, 1); PG8_STAGE(PG8_SA(1, 0), a3, voffA);
;             PG8_BAR; PG8_WAIT_L(0); PG8_MMA(1, 0, At, B0); PG8_BAR; PG8_SCHED;
;             PG8_STAGE(PG8_SB(1, 1), b3 + hstep, voffB);
;             PG8_WAIT_V(6); PG8_BAR; PG8_MMA(1, 1, At, B1); PG8_BAR;
;             }
;         }
;         if constexpr (ALIGN_EPI) { if (wr == 0) PG8_BAR; }
	s_add_i32 s24, s44, s2
	v_lshl_add_u64 v[160:161], v[160:161], 0, s[8:9]
	s_mov_b32 m0, s24
	ds_read_b128 v[196:199], v143 offset:49152
	ds_read_b128 v[200:203], v143 offset:50176
	ds_read_b128 v[204:207], v143 offset:51200
	ds_read_b128 v[208:211], v143 offset:52224
	ds_read_b128 v[232:235], v143 offset:53248
	ds_read_b128 v[236:239], v143 offset:54272
	ds_read_b128 v[240:243], v143 offset:55296
	ds_read_b128 v[244:247], v143 offset:56320
	global_load_lds_dwordx4 v[160:161], off
	s_add_i32 m0, s24, 0x2000
	s_add_u32 s22, s22, 0x80080
	v_lshl_add_u64 v[160:161], v[212:213], 0, s[8:9]
	s_addc_u32 s23, s23, 0
	s_add_i32 s24, s46, s2
	global_load_lds_dwordx4 v[160:161], off
	v_lshl_add_u64 v[160:161], s[22:23], 0, v[168:169]
	s_mov_b32 m0, s24
	s_nop 0
	global_load_lds_dwordx4 v[160:161], off
	v_lshl_add_u64 v[160:161], s[22:23], 0, v[172:173]
	s_add_i32 m0, s24, 0x2000
	s_nop 0
	global_load_lds_dwordx4 v[160:161], off
	v_lshl_add_u64 v[160:161], v[222:223], 0, s[8:9]
	s_mov_b32 m0, s30
	s_nop 0
	global_load_lds_dwordx4 v[160:161], off
	v_lshl_add_u64 v[160:161], v[248:249], 0, s[8:9]
	s_mov_b32 m0, s31
	s_nop 0
	global_load_lds_dwordx4 v[160:161], off
	s_waitcnt vmcnt(8)
	s_waitcnt lgkmcnt(0)
	s_barrier
	s_setprio 1
	v_mfma_f32_16x16x32_bf16 v[62:65], v[144:147], v[196:199], v[62:65]
	v_mfma_f32_16x16x32_bf16 v[58:61], v[152:155], v[196:199], v[58:61]
	v_mfma_f32_16x16x32_bf16 v[54:57], v[144:147], v[204:207], v[54:57]
	v_mfma_f32_16x16x32_bf16 v[50:53], v[152:155], v[204:207], v[50:53]
	v_mfma_f32_16x16x32_bf16 v[38:41], v[144:147], v[232:235], v[38:41]
	v_mfma_f32_16x16x32_bf16 v[34:37], v[152:155], v[232:235], v[34:37]
	v_mfma_f32_16x16x32_bf16 v[22:25], v[144:147], v[240:243], v[22:25]
	v_mfma_f32_16x16x32_bf16 v[18:21], v[152:155], v[240:243], v[18:21]
	v_mfma_f32_16x16x32_bf16 v[62:65], v[148:151], v[200:203], v[62:65]
	v_mfma_f32_16x16x32_bf16 v[58:61], v[156:159], v[200:203], v[58:61]
	v_mfma_f32_16x16x32_bf16 v[54:57], v[148:151], v[208:211], v[54:57]
	v_mfma_f32_16x16x32_bf16 v[50:53], v[156:159], v[208:211], v[50:53]
	v_mfma_f32_16x16x32_bf16 v[38:41], v[148:151], v[236:239], v[38:41]
	v_mfma_f32_16x16x32_bf16 v[34:37], v[156:159], v[236:239], v[34:37]
	v_mfma_f32_16x16x32_bf16 v[22:25], v[148:151], v[244:247], v[22:25]
	v_mfma_f32_16x16x32_bf16 v[18:21], v[156:159], v[244:247], v[18:21]
	v_mfma_f32_16x16x32_bf16 v[46:49], v[180:183], v[196:199], v[46:49]
	v_mfma_f32_16x16x32_bf16 v[42:45], v[188:191], v[196:199], v[42:45]
	v_mfma_f32_16x16x32_bf16 v[30:33], v[180:183], v[204:207], v[30:33]
	v_mfma_f32_16x16x32_bf16 v[26:29], v[188:191], v[204:207], v[26:29]
	v_mfma_f32_16x16x32_bf16 v[14:17], v[180:183], v[232:235], v[14:17]
	v_mfma_f32_16x16x32_bf16 v[10:13], v[188:191], v[232:235], v[10:13]
	v_mfma_f32_16x16x32_bf16 v[6:9], v[180:183], v[240:243], v[6:9]
	v_mfma_f32_16x16x32_bf16 v[2:5], v[188:191], v[240:243], v[2:5]
	v_mfma_f32_16x16x32_bf16 v[46:49], v[184:187], v[200:203], v[46:49]
	v_mfma_f32_16x16x32_bf16 v[42:45], v[192:195], v[200:203], v[42:45]
	v_mfma_f32_16x16x32_bf16 v[30:33], v[184:187], v[208:211], v[30:33]
	v_mfma_f32_16x16x32_bf16 v[26:29], v[192:195], v[208:211], v[26:29]
	v_mfma_f32_16x16x32_bf16 v[14:17], v[184:187], v[236:239], v[14:17]
	v_mfma_f32_16x16x32_bf16 v[10:13], v[192:195], v[236:239], v[10:13]
	v_mfma_f32_16x16x32_bf16 v[6:9], v[184:187], v[244:247], v[6:9]
	v_mfma_f32_16x16x32_bf16 v[2:5], v[192:195], v[244:247], v[2:5]
	s_setprio 0
	s_barrier
	s_add_u32 s6, s6, 0x100
	s_addc_u32 s7, s7, 0
	s_add_u32 s42, s42, 0x100
	s_addc_u32 s43, s43, 0
	s_cmp_ge_u32 s45, s38
	s_mov_b32 s44, s45
	s_cbranch_scc0 .LBB0_1029
	s_and_b64 vcc, exec, s[10:11]
	s_cbranch_vccz .LBB0_1032
	s_barrier

; #define PG8_STAGE(bufoff, gbase, voff) do { _Pragma("unroll") for (int _i = 0; _i < 2; ++_i) \
;         __builtin_amdgcn_global_load_lds((const unsigned*)((const char*)(gbase) + (voff)[_i]), (PG8_LAS unsigned*)(lds + (bufoff) + ldsw + _i * 8192), 16, 0, 0); } while (0)
; #define PG8_LDA(dst, b, h) do { _Pragma("unroll") for (int m = 0; m < 4; ++m) _Pragma("unroll") for (int k = 0; k < 2; ++k) dst[m][k] = *(const PG8_LAS bf16x8*)(lds + PG8_SA(b, h) + aoff + m * 2048 + k * 1024); } while (0)
; #define PG8_LDB(dst, b, h) do { _Pragma("unroll") for (int n = 0; n < 2; ++n) _Pragma("unroll") for (int k = 0; k < 2; ++k) dst[n][k] = *(const PG8_LAS bf16x8*)(lds + PG8_SB(b, h) + boff + n * 2048 + k * 1024); } while (0)
; #define PG8_MMA(ai, bj, At, Bt) do { __builtin_amdgcn_s_setprio(1); _Pragma("unroll") for (int m = 0; m < 4; ++m) _Pragma("unroll") for (int n = 0; n < 2; ++n) _Pragma("unroll") for (int k = 0; k < 2; ++k) \
;         acc[ai][bj][m][n] = __builtin_amdgcn_mfma_f32_16x16x32_bf16(Bt[n][k], At[m][k], acc[ai][bj][m][n], 0, 0, 0); __builtin_amdgcn_s_setprio(0); } while (0)
; #define PG8_WAIT_V(n) asm volatile("s_waitcnt vmcnt(" #n ")" ::: "memory")
; #define PG8_BAR __builtin_amdgcn_s_barrier()
; template <class Epi, class Sched, bool ALIGN_EPI = false, bool SP2 = false>
; __device__ __forceinline__ void gemm_phase(PG8_LAS unsigned char* lds, const Gemm g, const Sched& S, const Epi& E) {
;     ...
;         for (int t = 0; t < nt; t += 2) {
;             const bool last = (t == nt - 2);
;             const char* a1 = cA + (size_t)(t + 1) * kstep;
;             const char* a2 = last ? nA : cA + (size_t)(t + 2) * kstep; const char* b2 = last ? nB : cB + (size_t)(t + 2) * kstep;
;             const char* a3 = a2 + kstep; const char* b3 = b2 + kstep;
;             if (last && has_next) S.a_ready(nxt);
;             if constexpr (SP2) {
;             PG8_LDB(B0, 0, 0); PG8_LDB(B1, 0, 1); PG8_SCHED; PG8_LDA(At, 0, 0); PG8_STAGE(PG8_SA(1, 1), a1 + hstep, voffA);
;             PG8_WAIT_V(8); PG8_WAIT_L(0); PG8_BAR; PG8_MMA(0, 0, At, B0); PG8_MMA(0, 1, At, B1); PG8_BAR; PG8_SCHED;
;             PG8_LDA(At, 0, 1); PG8_STAGE(PG8_SB(0, 0), b2, voffB); PG8_STAGE(PG8_SB(0, 1), b2 + hstep, voffB); PG8_STAGE(PG8_SA(0, 0), a2, voffA);
;             PG8_WAIT_V(8); PG8_WAIT_L(0); PG8_BAR; PG8_MMA(1, 0, At, B0); PG8_MMA(1, 1, At, B1); PG8_BAR; PG8_SCHED;
.LBB0_1053:
	ds_read_b128 v[140:143], v137
	ds_read_b128 v[144:147], v137 offset:1024
	ds_read_b128 v[148:151], v137 offset:2048
	ds_read_b128 v[152:155], v137 offset:3072
	ds_read_b128 v[156:159], v138
	ds_read_b128 v[180:183], v138 offset:1024
	ds_read_b128 v[184:187], v138 offset:2048
	ds_read_b128 v[188:191], v138 offset:3072
	s_add_i32 s54, s26, 2
	s_add_u32 s27, s24, 0xfff80080
	s_addc_u32 s28, s25, -1
	s_cmp_eq_u32 s48, s26
	s_cselect_b32 s26, s47, s49
	s_cselect_b32 s29, s19, s28
	s_cselect_b32 s28, s46, s27
	s_cselect_b32 s27, s17, s53
	v_lshl_add_u64 v[160:161], s[24:25], 0, v[130:131]
	s_add_i32 m0, s34, 0xc000
	ds_read_b128 v[192:195], v139
	ds_read_b128 v[196:199], v139 offset:1024
	ds_read_b128 v[200:203], v139 offset:2048
	ds_read_b128 v[204:207], v139 offset:3072
	ds_read_b128 v[208:211], v139 offset:4096
	ds_read_b128 v[232:235], v139 offset:5120
	ds_read_b128 v[236:239], v139 offset:6144
	ds_read_b128 v[240:243], v139 offset:7168
	global_load_lds_dwordx4 v[160:161], off
	v_lshl_add_u64 v[160:161], s[24:25], 0, v[132:133]
	s_add_i32 m0, s34, 0xe000
	s_nop 0
	global_load_lds_dwordx4 v[160:161], off
	s_waitcnt vmcnt(8)
	s_waitcnt lgkmcnt(0)
	s_barrier
	s_setprio 1
	v_mfma_f32_16x16x32_bf16 v[126:129], v[140:143], v[192:195], v[126:129]
	v_mfma_f32_16x16x32_bf16 v[122:125], v[148:151], v[192:195], v[122:125]
	v_mfma_f32_16x16x32_bf16 v[118:121], v[140:143], v[200:203], v[118:121]
	v_mfma_f32_16x16x32_bf16 v[110:113], v[148:151], v[200:203], v[110:113]
	v_mfma_f32_16x16x32_bf16 v[102:105], v[140:143], v[208:211], v[102:105]
	v_mfma_f32_16x16x32_bf16 v[94:97], v[148:151], v[208:211], v[94:97]
	v_mfma_f32_16x16x32_bf16 v[86:89], v[140:143], v[236:239], v[86:89]
	v_mfma_f32_16x16x32_bf16 v[78:81], v[148:151], v[236:239], v[78:81]
	v_mfma_f32_16x16x32_bf16 v[126:129], v[144:147], v[196:199], v[126:129]
	v_mfma_f32_16x16x32_bf16 v[122:125], v[152:155], v[196:199], v[122:125]
	v_mfma_f32_16x16x32_bf16 v[118:121], v[144:147], v[204:207], v[118:121]
	v_mfma_f32_16x16x32_bf16 v[110:113], v[152:155], v[204:207], v[110:113]
	v_mfma_f32_16x16x32_bf16 v[102:105], v[144:147], v[232:235], v[102:105]
	v_mfma_f32_16x16x32_bf16 v[94:97], v[152:155], v[232:235], v[94:97]
	v_mfma_f32_16x16x32_bf16 v[86:89], v[144:147], v[240:243], v[86:89]
	v_mfma_f32_16x16x32_bf16 v[78:81], v[152:155], v[240:243], v[78:81]
	v_mfma_f32_16x16x32_bf16 v[114:117], v[156:159], v[192:195], v[114:117]
	v_mfma_f32_16x16x32_bf16 v[106:109], v[184:187], v[192:195], v[106:109]
	v_mfma_f32_16x16x32_bf16 v[98:101], v[156:159], v[200:203], v[98:101]
	v_mfma_f32_16x16x32_bf16 v[90:93], v[184:187], v[200:203], v[90:93]
	v_mfma_f32_16x16x32_bf16 v[82:85], v[156:159], v[208:211], v[82:85]
	v_mfma_f32_16x16x32_bf16 v[74:77], v[184:187], v[208:211], v[74:77]
	v_mfma_f32_16x16x32_bf16 v[70:73], v[156:159], v[236:239], v[70:73]
	v_mfma_f32_16x16x32_bf16 v[66:69], v[184:187], v[236:239], v[66:69]
	v_mfma_f32_16x16x32_bf16 v[114:117], v[180:183], v[196:199], v[114:117]
	v_mfma_f32_16x16x32_bf16 v[106:109], v[188:191], v[196:199], v[106:109]
	v_mfma_f32_16x16x32_bf16 v[98:101], v[180:183], v[204:207], v[98:101]
	v_mfma_f32_16x16x32_bf16 v[90:93], v[188:191], v[204:207], v[90:93]
	v_mfma_f32_16x16x32_bf16 v[82:85], v[180:183], v[232:235], v[82:85]
	v_mfma_f32_16x16x32_bf16 v[74:77], v[188:191], v[232:235], v[74:77]
	v_mfma_f32_16x16x32_bf16 v[70:73], v[180:183], v[240:243], v[70:73]
	v_mfma_f32_16x16x32_bf16 v[66:69], v[188:191], v[240:243], v[66:69]
	s_setprio 0
	s_barrier
	s_add_i32 s55, s42, s30
	v_lshl_add_u64 v[160:161], s[26:27], 0, v[166:167]
	s_mov_b32 m0, s55
	ds_read_b128 v[192:195], v139 offset:16384
	ds_read_b128 v[196:199], v139 offset:17408
	ds_read_b128 v[200:203], v139 offset:18432
	ds_read_b128 v[204:207], v139 offset:19456
	ds_read_b128 v[208:211], v139 offset:20480
	ds_read_b128 v[232:235], v139 offset:21504
	ds_read_b128 v[236:239], v139 offset:22528
	ds_read_b128 v[240:243], v139 offset:23552
	global_load_lds_dwordx4 v[160:161], off
	s_add_i32 m0, s55, 0x2000
	s_add_u32 s56, s26, 0x80000
	v_lshl_add_u64 v[212:213], s[26:27], 0, v[170:171]
	s_addc_u32 s57, s27, 0
	s_add_i32 s55, s43, s30
	global_load_lds_dwordx4 v[212:213], off
	v_lshl_add_u64 v[222:223], s[56:57], 0, v[166:167]
	s_mov_b32 m0, s55
	v_lshl_add_u64 v[244:245], s[28:29], 0, v[170:171]
	global_load_lds_dwordx4 v[222:223], off
	v_lshl_add_u64 v[222:223], s[56:57], 0, v[170:171]
	s_add_i32 m0, s55, 0x2000
	s_nop 0
	global_load_lds_dwordx4 v[222:223], off
	v_lshl_add_u64 v[222:223], s[28:29], 0, v[166:167]
	s_mov_b32 m0, s34
	s_nop 0
	global_load_lds_dwordx4 v[222:223], off
	s_mov_b32 m0, s35
	s_nop 0
	global_load_lds_dwordx4 v[244:245], off
	s_waitcnt vmcnt(8)
	s_waitcnt lgkmcnt(0)
	s_barrier
; #define PG8_STAGE(bufoff, gbase, voff) do { _Pragma("unroll") for (int _i = 0; _i < 2; ++_i) \
;         __builtin_amdgcn_global_load_lds((const unsigned*)((const char*)(gbase) + (voff)[_i]), (PG8_LAS unsigned*)(lds + (bufoff) + ldsw + _i * 8192), 16, 0, 0); } while (0)
; #define PG8_LDA(dst, b, h) do { _Pragma("unroll") for (int m = 0; m < 4; ++m) _Pragma("unroll") for (int k = 0; k < 2; ++k) dst[m][k] = *(const PG8_LAS bf16x8*)(lds + PG8_SA(b, h) + aoff + m * 2048 + k * 1024); } while (0)
; #define PG8_LDB(dst, b, h) do { _Pragma("unroll") for (int n = 0; n < 2; ++n) _Pragma("unroll") for (int k = 0; k < 2; ++k) dst[n][k] = *(const PG8_LAS bf16x8*)(lds + PG8_SB(b, h) + boff + n * 2048 + k * 1024); } while (0)
; #define PG8_MMA(ai, bj, At, Bt) do { __builtin_amdgcn_s_setprio(1); _Pragma("unroll") for (int m = 0; m < 4; ++m) _Pragma("unroll") for (int n = 0; n < 2; ++n) _Pragma("unroll") for (int k = 0; k < 2; ++k) \
;         acc[ai][bj][m][n] = __builtin_amdgcn_mfma_f32_16x16x32_bf16(Bt[n][k], At[m][k], acc[ai][bj][m][n], 0, 0, 0); __builtin_amdgcn_s_setprio(0); } while (0)
; #define PG8_WAIT_V(n) asm volatile("s_waitcnt vmcnt(" #n ")" ::: "memory")
; #define PG8_WAIT_L(n) asm volatile("s_waitcnt lgkmcnt(" #n ")" ::: "memory")
; #define PG8_BAR __builtin_amdgcn_s_barrier()
; #define PG8_SCHED __builtin_amdgcn_sched_barrier(0)
; template <class Epi, class Sched, bool ALIGN_EPI = false, bool SP2 = false>
; __device__ __forceinline__ void gemm_phase(PG8_LAS unsigned char* lds, const Gemm g, const Sched& S, const Epi& E) {
;     ...
;             PG8_WAIT_V(8); PG8_WAIT_L(0); PG8_BAR; PG8_MMA(1, 0, At, B0); PG8_MMA(1, 1, At, B1); PG8_BAR; PG8_SCHED;
;             PG8_LDB(B0, 1, 0); PG8_LDB(B1, 1, 1); PG8_SCHED; PG8_LDA(At, 1, 0); PG8_STAGE(PG8_SA(0, 1), a2 + hstep, voffA);
;             PG8_WAIT_V(8); PG8_WAIT_L(0); PG8_BAR; PG8_MMA(0, 0, At, B0); PG8_MMA(0, 1, At, B1); PG8_BAR; PG8_SCHED;
	s_setprio 1
	v_mfma_f32_16x16x32_bf16 v[62:65], v[140:143], v[192:195], v[62:65]
	v_mfma_f32_16x16x32_bf16 v[58:61], v[148:151], v[192:195], v[58:61]
	v_mfma_f32_16x16x32_bf16 v[54:57], v[140:143], v[200:203], v[54:57]
	v_mfma_f32_16x16x32_bf16 v[46:49], v[148:151], v[200:203], v[46:49]
	v_mfma_f32_16x16x32_bf16 v[38:41], v[140:143], v[208:211], v[38:41]
	v_mfma_f32_16x16x32_bf16 v[30:33], v[148:151], v[208:211], v[30:33]
	v_mfma_f32_16x16x32_bf16 v[22:25], v[140:143], v[236:239], v[22:25]
	v_mfma_f32_16x16x32_bf16 v[14:17], v[148:151], v[236:239], v[14:17]
	v_mfma_f32_16x16x32_bf16 v[62:65], v[144:147], v[196:199], v[62:65]
	v_mfma_f32_16x16x32_bf16 v[58:61], v[152:155], v[196:199], v[58:61]
	v_mfma_f32_16x16x32_bf16 v[54:57], v[144:147], v[204:207], v[54:57]
	v_mfma_f32_16x16x32_bf16 v[46:49], v[152:155], v[204:207], v[46:49]
	v_mfma_f32_16x16x32_bf16 v[38:41], v[144:147], v[232:235], v[38:41]
	v_mfma_f32_16x16x32_bf16 v[30:33], v[152:155], v[232:235], v[30:33]
	v_mfma_f32_16x16x32_bf16 v[22:25], v[144:147], v[240:243], v[22:25]
	v_mfma_f32_16x16x32_bf16 v[14:17], v[152:155], v[240:243], v[14:17]
	v_mfma_f32_16x16x32_bf16 v[50:53], v[156:159], v[192:195], v[50:53]
	v_mfma_f32_16x16x32_bf16 v[42:45], v[184:187], v[192:195], v[42:45]
	v_mfma_f32_16x16x32_bf16 v[34:37], v[156:159], v[200:203], v[34:37]
	v_mfma_f32_16x16x32_bf16 v[26:29], v[184:187], v[200:203], v[26:29]
	v_mfma_f32_16x16x32_bf16 v[18:21], v[156:159], v[208:211], v[18:21]
	v_mfma_f32_16x16x32_bf16 v[10:13], v[184:187], v[208:211], v[10:13]
	v_mfma_f32_16x16x32_bf16 v[6:9], v[156:159], v[236:239], v[6:9]
	v_mfma_f32_16x16x32_bf16 v[2:5], v[184:187], v[236:239], v[2:5]
	v_mfma_f32_16x16x32_bf16 v[50:53], v[180:183], v[196:199], v[50:53]
	v_mfma_f32_16x16x32_bf16 v[42:45], v[188:191], v[196:199], v[42:45]
	v_mfma_f32_16x16x32_bf16 v[34:37], v[180:183], v[204:207], v[34:37]
	v_mfma_f32_16x16x32_bf16 v[26:29], v[188:191], v[204:207], v[26:29]
	v_mfma_f32_16x16x32_bf16 v[18:21], v[180:183], v[232:235], v[18:21]
	v_mfma_f32_16x16x32_bf16 v[10:13], v[188:191], v[232:235], v[10:13]
	v_mfma_f32_16x16x32_bf16 v[6:9], v[180:183], v[240:243], v[6:9]
	v_mfma_f32_16x16x32_bf16 v[2:5], v[188:191], v[240:243], v[2:5]
	s_setprio 0
	s_barrier
	s_add_i32 s55, 0, 0x18000
	s_add_i32 s56, 0, 0x1c000
	v_add_u32_e32 v152, s55, v135
	v_add_u32_e32 v169, s56, v135
	ds_read_b128 v[140:143], v152
	ds_read_b128 v[144:147], v152 offset:1024
	ds_read_b128 v[148:151], v152 offset:2048
	ds_read_b128 v[152:155], v152 offset:3072
	ds_read_b128 v[156:159], v169
	ds_read_b128 v[180:183], v169 offset:1024
	ds_read_b128 v[184:187], v169 offset:2048
	ds_read_b128 v[188:191], v169 offset:3072
	s_add_u32 s28, s28, 0x80000
	s_addc_u32 s29, s29, 0
	s_mov_b32 m0, s36
	v_lshl_add_u64 v[246:247], s[28:29], 0, v[166:167]
	ds_read_b128 v[192:195], v139 offset:32768
	ds_read_b128 v[196:199], v139 offset:33792
	ds_read_b128 v[200:203], v139 offset:34816
	ds_read_b128 v[204:207], v139 offset:35840
	ds_read_b128 v[208:211], v139 offset:36864
	ds_read_b128 v[232:235], v139 offset:37888
	ds_read_b128 v[236:239], v139 offset:38912
	ds_read_b128 v[240:243], v139 offset:39936
	global_load_lds_dwordx4 v[246:247], off
	v_lshl_add_u64 v[246:247], s[28:29], 0, v[170:171]
	s_mov_b32 m0, s37
	s_nop 0
	global_load_lds_dwordx4 v[246:247], off
	s_waitcnt vmcnt(8)
	s_waitcnt lgkmcnt(0)
	s_barrier
	s_setprio 1
	v_mfma_f32_16x16x32_bf16 v[126:129], v[140:143], v[192:195], v[126:129]
	v_mfma_f32_16x16x32_bf16 v[122:125], v[148:151], v[192:195], v[122:125]
	v_mfma_f32_16x16x32_bf16 v[118:121], v[140:143], v[200:203], v[118:121]
	v_mfma_f32_16x16x32_bf16 v[110:113], v[148:151], v[200:203], v[110:113]
	v_mfma_f32_16x16x32_bf16 v[102:105], v[140:143], v[208:211], v[102:105]
	v_mfma_f32_16x16x32_bf16 v[94:97], v[148:151], v[208:211], v[94:97]
	v_mfma_f32_16x16x32_bf16 v[86:89], v[140:143], v[236:239], v[86:89]
	v_mfma_f32_16x16x32_bf16 v[78:81], v[148:151], v[236:239], v[78:81]
	v_mfma_f32_16x16x32_bf16 v[126:129], v[144:147], v[196:199], v[126:129]
	v_mfma_f32_16x16x32_bf16 v[122:125], v[152:155], v[196:199], v[122:125]
	v_mfma_f32_16x16x32_bf16 v[118:121], v[144:147], v[204:207], v[118:121]
	v_mfma_f32_16x16x32_bf16 v[110:113], v[152:155], v[204:207], v[110:113]
	v_mfma_f32_16x16x32_bf16 v[102:105], v[144:147], v[232:235], v[102:105]
	v_mfma_f32_16x16x32_bf16 v[94:97], v[152:155], v[232:235], v[94:97]
	v_mfma_f32_16x16x32_bf16 v[86:89], v[144:147], v[240:243], v[86:89]
	v_mfma_f32_16x16x32_bf16 v[78:81], v[152:155], v[240:243], v[78:81]
	v_mfma_f32_16x16x32_bf16 v[114:117], v[156:159], v[192:195], v[114:117]
	v_mfma_f32_16x16x32_bf16 v[106:109], v[184:187], v[192:195], v[106:109]
	v_mfma_f32_16x16x32_bf16 v[98:101], v[156:159], v[200:203], v[98:101]
	v_mfma_f32_16x16x32_bf16 v[90:93], v[184:187], v[200:203], v[90:93]
	v_mfma_f32_16x16x32_bf16 v[82:85], v[156:159], v[208:211], v[82:85]
	v_mfma_f32_16x16x32_bf16 v[74:77], v[184:187], v[208:211], v[74:77]
	v_mfma_f32_16x16x32_bf16 v[70:73], v[156:159], v[236:239], v[70:73]
	v_mfma_f32_16x16x32_bf16 v[66:69], v[184:187], v[236:239], v[66:69]
	v_mfma_f32_16x16x32_bf16 v[114:117], v[180:183], v[196:199], v[114:117]
	v_mfma_f32_16x16x32_bf16 v[106:109], v[188:191], v[196:199], v[106:109]
	v_mfma_f32_16x16x32_bf16 v[98:101], v[180:183], v[204:207], v[98:101]
	v_mfma_f32_16x16x32_bf16 v[90:93], v[188:191], v[204:207], v[90:93]
	v_mfma_f32_16x16x32_bf16 v[82:85], v[180:183], v[232:235], v[82:85]
	v_mfma_f32_16x16x32_bf16 v[74:77], v[188:191], v[232:235], v[74:77]
	v_mfma_f32_16x16x32_bf16 v[70:73], v[180:183], v[240:243], v[70:73]
	v_mfma_f32_16x16x32_bf16 v[66:69], v[188:191], v[240:243], v[66:69]
	s_setprio 0
	s_barrier
; #define PG8_STAGE(bufoff, gbase, voff) do { _Pragma("unroll") for (int _i = 0; _i < 2; ++_i) \
;         __builtin_amdgcn_global_load_lds((const unsigned*)((const char*)(gbase) + (voff)[_i]), (PG8_LAS unsigned*)(lds + (bufoff) + ldsw + _i * 8192), 16, 0, 0); } while (0)
; #define PG8_LDA(dst, b, h) do { _Pragma("unroll") for (int m = 0; m < 4; ++m) _Pragma("unroll") for (int k = 0; k < 2; ++k) dst[m][k] = *(const PG8_LAS bf16x8*)(lds + PG8_SA(b, h) + aoff + m * 2048 + k * 1024); } while (0)
; #define PG8_WAIT_V(n) asm volatile("s_waitcnt vmcnt(" #n ")" ::: "memory")
; template <class Epi, class Sched, bool ALIGN_EPI = false, bool SP2 = false>
; __device__ __forceinline__ void gemm_phase(PG8_LAS unsigned char* lds, const Gemm g, const Sched& S, const Epi& E) {
;     ...
;             PG8_LDA(At, 1, 1); PG8_STAGE(PG8_SB(1, 0), b3, voffB); PG8_STAGE(PG8_SB(1, 1), b3 + hstep, voffB); PG8_STAGE(PG8_SA(1, 0), a3, voffA);
;             PG8_WAIT_V(8); PG8_WAIT_L(0); PG8_BAR; PG8_MMA(1, 0, At, B0); PG8_MMA(1, 1, At, B1); PG8_BAR; PG8_SCHED;
;             } else {
;             PG8_LDB(B0, 0, 0); PG8_SCHED; PG8_LDA(At, 0, 0); PG8_STAGE(PG8_SA(1, 1), a1 + hstep, voffA);
;             PG8_WAIT_L(8); PG8_BAR; PG8_WAIT_L(0); PG8_MMA(0, 0, At, B0); PG8_BAR; PG8_SCHED;
;             PG8_LDB(B1, 0, 1); PG8_STAGE(PG8_SB(0, 0), b2, voffB);
;             PG8_BAR; PG8_WAIT_L(0); PG8_MMA(0, 1, At, B1); PG8_BAR;
;             PG8_LDA(At, 0, 1); PG8_STAGE(PG8_SA(0, 0), a2, voffA);
;             PG8_BAR; PG8_WAIT_L(0); PG8_MMA(1, 0, At, B0); PG8_BAR; PG8_SCHED;
;             PG8_STAGE(PG8_SB(0, 1), b2 + hstep, voffB);
;             PG8_WAIT_V(6); PG8_BAR; PG8_MMA(1, 1, At, B1); PG8_BAR;
;             PG8_LDB(B0, 1, 0); PG8_SCHED; PG8_LDA(At, 1, 0); PG8_STAGE(PG8_SA(0, 1), a2 + hstep, voffA);
;             PG8_WAIT_L(8); PG8_BAR; PG8_WAIT_L(0); PG8_MMA(0, 0, At, B0); PG8_BAR; PG8_SCHED;
;             PG8_LDB(B1, 1, 1); PG8_STAGE(PG8_SB(1, 0), b3, voffB);
;             PG8_BAR; PG8_WAIT_L(0); PG8_MMA(0, 1, At, B1); PG8_BAR;
;             PG8_LDA(At, 1, 1); PG8_STAGE(PG8_SA(1, 0), a3, voffA);
;             PG8_BAR; PG8_WAIT_L(0); PG8_MMA(1, 0, At, B0); PG8_BAR; PG8_SCHED;
;             PG8_STAGE(PG8_SB(1, 1), b3 + hstep, voffB);
;             PG8_WAIT_V(6); PG8_BAR; PG8_MMA(1, 1, At, B1); PG8_BAR;
;             }
;         }
;         if constexpr (ALIGN_EPI) { if (wr == 0) PG8_BAR; }
	s_add_i32 s28, s55, s30
	v_lshl_add_u64 v[160:161], v[160:161], 0, s[4:5]
	s_mov_b32 m0, s28
	ds_read_b128 v[192:195], v139 offset:49152
	ds_read_b128 v[196:199], v139 offset:50176
	ds_read_b128 v[200:203], v139 offset:51200
	ds_read_b128 v[204:207], v139 offset:52224
	ds_read_b128 v[208:211], v139 offset:53248
	ds_read_b128 v[232:235], v139 offset:54272
	ds_read_b128 v[236:239], v139 offset:55296
	ds_read_b128 v[240:243], v139 offset:56320
	global_load_lds_dwordx4 v[160:161], off
	s_add_i32 m0, s28, 0x2000
	s_add_u32 s26, s26, 0x80080
	v_lshl_add_u64 v[160:161], v[212:213], 0, s[4:5]
	s_addc_u32 s27, s27, 0
	s_add_i32 s28, s56, s30
	global_load_lds_dwordx4 v[160:161], off
	v_lshl_add_u64 v[160:161], s[26:27], 0, v[166:167]
	s_mov_b32 m0, s28
	s_nop 0
	global_load_lds_dwordx4 v[160:161], off
	v_lshl_add_u64 v[160:161], s[26:27], 0, v[170:171]
	s_add_i32 m0, s28, 0x2000
	s_nop 0
	global_load_lds_dwordx4 v[160:161], off
	v_lshl_add_u64 v[160:161], v[222:223], 0, s[4:5]
	s_mov_b32 m0, s39
	s_nop 0
	global_load_lds_dwordx4 v[160:161], off
	v_lshl_add_u64 v[160:161], v[244:245], 0, s[4:5]
	s_mov_b32 m0, s40
	s_nop 0
	global_load_lds_dwordx4 v[160:161], off
	s_waitcnt vmcnt(8)
	s_waitcnt lgkmcnt(0)
	s_barrier
	s_setprio 1
	v_mfma_f32_16x16x32_bf16 v[62:65], v[140:143], v[192:195], v[62:65]
	v_mfma_f32_16x16x32_bf16 v[58:61], v[148:151], v[192:195], v[58:61]
	v_mfma_f32_16x16x32_bf16 v[54:57], v[140:143], v[200:203], v[54:57]
	v_mfma_f32_16x16x32_bf16 v[46:49], v[148:151], v[200:203], v[46:49]
	v_mfma_f32_16x16x32_bf16 v[38:41], v[140:143], v[208:211], v[38:41]
	v_mfma_f32_16x16x32_bf16 v[30:33], v[148:151], v[208:211], v[30:33]
	v_mfma_f32_16x16x32_bf16 v[22:25], v[140:143], v[236:239], v[22:25]
	v_mfma_f32_16x16x32_bf16 v[14:17], v[148:151], v[236:239], v[14:17]
	v_mfma_f32_16x16x32_bf16 v[62:65], v[144:147], v[196:199], v[62:65]
	v_mfma_f32_16x16x32_bf16 v[58:61], v[152:155], v[196:199], v[58:61]
	v_mfma_f32_16x16x32_bf16 v[54:57], v[144:147], v[204:207], v[54:57]
	v_mfma_f32_16x16x32_bf16 v[46:49], v[152:155], v[204:207], v[46:49]
	v_mfma_f32_16x16x32_bf16 v[38:41], v[144:147], v[232:235], v[38:41]
	v_mfma_f32_16x16x32_bf16 v[30:33], v[152:155], v[232:235], v[30:33]
	v_mfma_f32_16x16x32_bf16 v[22:25], v[144:147], v[240:243], v[22:25]
	v_mfma_f32_16x16x32_bf16 v[14:17], v[152:155], v[240:243], v[14:17]
	v_mfma_f32_16x16x32_bf16 v[50:53], v[156:159], v[192:195], v[50:53]
	v_mfma_f32_16x16x32_bf16 v[42:45], v[184:187], v[192:195], v[42:45]
	v_mfma_f32_16x16x32_bf16 v[34:37], v[156:159], v[200:203], v[34:37]
	v_mfma_f32_16x16x32_bf16 v[26:29], v[184:187], v[200:203], v[26:29]
	v_mfma_f32_16x16x32_bf16 v[18:21], v[156:159], v[208:211], v[18:21]
	v_mfma_f32_16x16x32_bf16 v[10:13], v[184:187], v[208:211], v[10:13]
	v_mfma_f32_16x16x32_bf16 v[6:9], v[156:159], v[236:239], v[6:9]
	v_mfma_f32_16x16x32_bf16 v[2:5], v[184:187], v[236:239], v[2:5]
	v_mfma_f32_16x16x32_bf16 v[50:53], v[180:183], v[196:199], v[50:53]
	v_mfma_f32_16x16x32_bf16 v[42:45], v[188:191], v[196:199], v[42:45]
	v_mfma_f32_16x16x32_bf16 v[34:37], v[180:183], v[204:207], v[34:37]
	v_mfma_f32_16x16x32_bf16 v[26:29], v[188:191], v[204:207], v[26:29]
	v_mfma_f32_16x16x32_bf16 v[18:21], v[180:183], v[232:235], v[18:21]
	v_mfma_f32_16x16x32_bf16 v[10:13], v[188:191], v[232:235], v[10:13]
	v_mfma_f32_16x16x32_bf16 v[6:9], v[180:183], v[240:243], v[6:9]
	v_mfma_f32_16x16x32_bf16 v[2:5], v[188:191], v[240:243], v[2:5]
	s_setprio 0
	s_barrier
	s_add_u32 s24, s24, 0x100
	s_addc_u32 s25, s25, 0
	s_add_u32 s49, s49, 0x100
	s_addc_u32 s53, s53, 0
	s_cmp_ge_u32 s54, s45
	s_mov_b32 s26, s54
	s_cbranch_scc0 .LBB0_1053
	s_and_b64 vcc, exec, s[6:7]
	s_cbranch_vccz .LBB0_1056
	s_barrier

; #define PG8_STAGE(bufoff, gbase, voff) do { _Pragma("unroll") for (int _i = 0; _i < 2; ++_i) \
;         __builtin_amdgcn_global_load_lds((const unsigned*)((const char*)(gbase) + (voff)[_i]), (PG8_LAS unsigned*)(lds + (bufoff) + ldsw + _i * 8192), 16, 0, 0); } while (0)
; #define PG8_LDA(dst, b, h) do { _Pragma("unroll") for (int m = 0; m < 4; ++m) _Pragma("unroll") for (int k = 0; k < 2; ++k) dst[m][k] = *(const PG8_LAS bf16x8*)(lds + PG8_SA(b, h) + aoff + m * 2048 + k * 1024); } while (0)
; #define PG8_LDB(dst, b, h) do { _Pragma("unroll") for (int n = 0; n < 2; ++n) _Pragma("unroll") for (int k = 0; k < 2; ++k) dst[n][k] = *(const PG8_LAS bf16x8*)(lds + PG8_SB(b, h) + boff + n * 2048 + k * 1024); } while (0)
; #define PG8_MMA(ai, bj, At, Bt) do { __builtin_amdgcn_s_setprio(1); _Pragma("unroll") for (int m = 0; m < 4; ++m) _Pragma("unroll") for (int n = 0; n < 2; ++n) _Pragma("unroll") for (int k = 0; k < 2; ++k) \
;         acc[ai][bj][m][n] = __builtin_amdgcn_mfma_f32_16x16x32_bf16(Bt[n][k], At[m][k], acc[ai][bj][m][n], 0, 0, 0); __builtin_amdgcn_s_setprio(0); } while (0)
; #define PG8_WAIT_V(n) asm volatile("s_waitcnt vmcnt(" #n ")" ::: "memory")
; #define PG8_BAR __builtin_amdgcn_s_barrier()
; template <class Epi, class Sched, bool ALIGN_EPI = false, bool SP2 = false>
; __device__ __forceinline__ void gemm_phase(PG8_LAS unsigned char* lds, const Gemm g, const Sched& S, const Epi& E) {
;     ...
;         for (int t = 0; t < nt; t += 2) {
;             const bool last = (t == nt - 2);
;             const char* a1 = cA + (size_t)(t + 1) * kstep;
;             const char* a2 = last ? nA : cA + (size_t)(t + 2) * kstep; const char* b2 = last ? nB : cB + (size_t)(t + 2) * kstep;
;             const char* a3 = a2 + kstep; const char* b3 = b2 + kstep;
;             if (last && has_next) S.a_ready(nxt);
;             if constexpr (SP2) {
;             PG8_LDB(B0, 0, 0); PG8_LDB(B1, 0, 1); PG8_SCHED; PG8_LDA(At, 0, 0); PG8_STAGE(PG8_SA(1, 1), a1 + hstep, voffA);
;             PG8_WAIT_V(8); PG8_WAIT_L(0); PG8_BAR; PG8_MMA(0, 0, At, B0); PG8_MMA(0, 1, At, B1); PG8_BAR; PG8_SCHED;
;             PG8_LDA(At, 0, 1); PG8_STAGE(PG8_SB(0, 0), b2, voffB); PG8_STAGE(PG8_SB(0, 1), b2 + hstep, voffB); PG8_STAGE(PG8_SA(0, 0), a2, voffA);
;             PG8_WAIT_V(8); PG8_WAIT_L(0); PG8_BAR; PG8_MMA(1, 0, At, B0); PG8_MMA(1, 1, At, B1); PG8_BAR; PG8_SCHED;
.LBB0_1228:
	ds_read_b128 v[148:151], v145
	ds_read_b128 v[152:155], v145 offset:1024
	ds_read_b128 v[156:159], v145 offset:2048
	ds_read_b128 v[180:183], v145 offset:3072
	ds_read_b128 v[184:187], v146
	ds_read_b128 v[188:191], v146 offset:1024
	ds_read_b128 v[192:195], v146 offset:2048
	ds_read_b128 v[196:199], v146 offset:3072
	s_add_i32 s48, s47, 2
	s_add_u32 s24, s6, 0xfffe0080
	s_addc_u32 s25, s7, -1
	s_cmp_eq_u32 s44, s47
	s_cselect_b32 s27, s19, s25
	s_cselect_b32 s26, s42, s24
	s_cselect_b32 s25, s17, s46
	s_cselect_b32 s24, s43, s45
	v_lshl_add_u64 v[160:161], s[6:7], 0, v[134:135]
	s_add_i32 m0, s15, 0xc000
	ds_read_b128 v[200:203], v147
	ds_read_b128 v[204:207], v147 offset:1024
	ds_read_b128 v[208:211], v147 offset:2048
	ds_read_b128 v[228:231], v147 offset:3072
	ds_read_b128 v[232:235], v147 offset:4096
	ds_read_b128 v[236:239], v147 offset:5120
	ds_read_b128 v[240:243], v147 offset:6144
	ds_read_b128 v[244:247], v147 offset:7168
	global_load_lds_dwordx4 v[160:161], off
	v_lshl_add_u64 v[160:161], s[6:7], 0, v[136:137]
	s_add_i32 m0, s15, 0xe000
	s_nop 0
	global_load_lds_dwordx4 v[160:161], off
	s_waitcnt vmcnt(8)
	s_waitcnt lgkmcnt(0)
	s_barrier
	s_setprio 1
	v_mfma_f32_16x16x32_bf16 v[126:129], v[148:151], v[200:203], v[126:129]
	v_mfma_f32_16x16x32_bf16 v[122:125], v[156:159], v[200:203], v[122:125]
	v_mfma_f32_16x16x32_bf16 v[118:121], v[148:151], v[208:211], v[118:121]
	v_mfma_f32_16x16x32_bf16 v[110:113], v[156:159], v[208:211], v[110:113]
	v_mfma_f32_16x16x32_bf16 v[102:105], v[148:151], v[232:235], v[102:105]
	v_mfma_f32_16x16x32_bf16 v[94:97], v[156:159], v[232:235], v[94:97]
	v_mfma_f32_16x16x32_bf16 v[86:89], v[148:151], v[240:243], v[86:89]
	v_mfma_f32_16x16x32_bf16 v[78:81], v[156:159], v[240:243], v[78:81]
	v_mfma_f32_16x16x32_bf16 v[126:129], v[152:155], v[204:207], v[126:129]
	v_mfma_f32_16x16x32_bf16 v[122:125], v[180:183], v[204:207], v[122:125]
	v_mfma_f32_16x16x32_bf16 v[118:121], v[152:155], v[228:231], v[118:121]
	v_mfma_f32_16x16x32_bf16 v[110:113], v[180:183], v[228:231], v[110:113]
	v_mfma_f32_16x16x32_bf16 v[102:105], v[152:155], v[236:239], v[102:105]
	v_mfma_f32_16x16x32_bf16 v[94:97], v[180:183], v[236:239], v[94:97]
	v_mfma_f32_16x16x32_bf16 v[86:89], v[152:155], v[244:247], v[86:89]
	v_mfma_f32_16x16x32_bf16 v[78:81], v[180:183], v[244:247], v[78:81]
	v_mfma_f32_16x16x32_bf16 v[114:117], v[184:187], v[200:203], v[114:117]
	v_mfma_f32_16x16x32_bf16 v[106:109], v[192:195], v[200:203], v[106:109]
	v_mfma_f32_16x16x32_bf16 v[98:101], v[184:187], v[208:211], v[98:101]
	v_mfma_f32_16x16x32_bf16 v[90:93], v[192:195], v[208:211], v[90:93]
	v_mfma_f32_16x16x32_bf16 v[82:85], v[184:187], v[232:235], v[82:85]
	v_mfma_f32_16x16x32_bf16 v[74:77], v[192:195], v[232:235], v[74:77]
	v_mfma_f32_16x16x32_bf16 v[70:73], v[184:187], v[240:243], v[70:73]
	v_mfma_f32_16x16x32_bf16 v[66:69], v[192:195], v[240:243], v[66:69]
	v_mfma_f32_16x16x32_bf16 v[114:117], v[188:191], v[204:207], v[114:117]
	v_mfma_f32_16x16x32_bf16 v[106:109], v[196:199], v[204:207], v[106:109]
	v_mfma_f32_16x16x32_bf16 v[98:101], v[188:191], v[228:231], v[98:101]
	v_mfma_f32_16x16x32_bf16 v[90:93], v[196:199], v[228:231], v[90:93]
	v_mfma_f32_16x16x32_bf16 v[82:85], v[188:191], v[236:239], v[82:85]
	v_mfma_f32_16x16x32_bf16 v[74:77], v[196:199], v[236:239], v[74:77]
	v_mfma_f32_16x16x32_bf16 v[70:73], v[188:191], v[244:247], v[70:73]
	v_mfma_f32_16x16x32_bf16 v[66:69], v[196:199], v[244:247], v[66:69]
	s_setprio 0
	s_barrier
	s_add_i32 s47, s37, s2
	v_lshl_add_u64 v[160:161], s[24:25], 0, v[132:133]
	s_mov_b32 m0, s47
	ds_read_b128 v[200:203], v147 offset:16384
	ds_read_b128 v[204:207], v147 offset:17408
	ds_read_b128 v[208:211], v147 offset:18432
	ds_read_b128 v[228:231], v147 offset:19456
	ds_read_b128 v[232:235], v147 offset:20480
	ds_read_b128 v[236:239], v147 offset:21504
	ds_read_b128 v[240:243], v147 offset:22528
	ds_read_b128 v[244:247], v147 offset:23552
	global_load_lds_dwordx4 v[160:161], off
	s_add_i32 m0, s47, 0x2000
	s_add_u32 s54, s24, 0x20000
	v_lshl_add_u64 v[212:213], s[24:25], 0, v[130:131]
	s_addc_u32 s55, s25, 0
	s_add_i32 s47, s38, s2
	global_load_lds_dwordx4 v[212:213], off
	v_lshl_add_u64 v[222:223], s[54:55], 0, v[132:133]
	s_mov_b32 m0, s47
	v_lshl_add_u64 v[248:249], s[26:27], 0, v[130:131]
	global_load_lds_dwordx4 v[222:223], off
	v_lshl_add_u64 v[222:223], s[54:55], 0, v[130:131]
	s_add_i32 m0, s47, 0x2000
	s_nop 0
	global_load_lds_dwordx4 v[222:223], off
	v_lshl_add_u64 v[222:223], s[26:27], 0, v[132:133]
	s_mov_b32 m0, s15
	s_nop 0
	global_load_lds_dwordx4 v[222:223], off
	s_mov_b32 m0, s29
	s_nop 0
	global_load_lds_dwordx4 v[248:249], off
	s_waitcnt vmcnt(8)
	s_waitcnt lgkmcnt(0)
	s_barrier
; #define PG8_STAGE(bufoff, gbase, voff) do { _Pragma("unroll") for (int _i = 0; _i < 2; ++_i) \
;         __builtin_amdgcn_global_load_lds((const unsigned*)((const char*)(gbase) + (voff)[_i]), (PG8_LAS unsigned*)(lds + (bufoff) + ldsw + _i * 8192), 16, 0, 0); } while (0)
; #define PG8_LDA(dst, b, h) do { _Pragma("unroll") for (int m = 0; m < 4; ++m) _Pragma("unroll") for (int k = 0; k < 2; ++k) dst[m][k] = *(const PG8_LAS bf16x8*)(lds + PG8_SA(b, h) + aoff + m * 2048 + k * 1024); } while (0)
; #define PG8_LDB(dst, b, h) do { _Pragma("unroll") for (int n = 0; n < 2; ++n) _Pragma("unroll") for (int k = 0; k < 2; ++k) dst[n][k] = *(const PG8_LAS bf16x8*)(lds + PG8_SB(b, h) + boff + n * 2048 + k * 1024); } while (0)
; #define PG8_MMA(ai, bj, At, Bt) do { __builtin_amdgcn_s_setprio(1); _Pragma("unroll") for (int m = 0; m < 4; ++m) _Pragma("unroll") for (int n = 0; n < 2; ++n) _Pragma("unroll") for (int k = 0; k < 2; ++k) \
;         acc[ai][bj][m][n] = __builtin_amdgcn_mfma_f32_16x16x32_bf16(Bt[n][k], At[m][k], acc[ai][bj][m][n], 0, 0, 0); __builtin_amdgcn_s_setprio(0); } while (0)
; #define PG8_WAIT_V(n) asm volatile("s_waitcnt vmcnt(" #n ")" ::: "memory")
; #define PG8_WAIT_L(n) asm volatile("s_waitcnt lgkmcnt(" #n ")" ::: "memory")
; #define PG8_BAR __builtin_amdgcn_s_barrier()
; #define PG8_SCHED __builtin_amdgcn_sched_barrier(0)
; template <class Epi, class Sched, bool ALIGN_EPI = false, bool SP2 = false>
; __device__ __forceinline__ void gemm_phase(PG8_LAS unsigned char* lds, const Gemm g, const Sched& S, const Epi& E) {
;     ...
;             PG8_WAIT_V(8); PG8_WAIT_L(0); PG8_BAR; PG8_MMA(1, 0, At, B0); PG8_MMA(1, 1, At, B1); PG8_BAR; PG8_SCHED;
;             PG8_LDB(B0, 1, 0); PG8_LDB(B1, 1, 1); PG8_SCHED; PG8_LDA(At, 1, 0); PG8_STAGE(PG8_SA(0, 1), a2 + hstep, voffA);
;             PG8_WAIT_V(8); PG8_WAIT_L(0); PG8_BAR; PG8_MMA(0, 0, At, B0); PG8_MMA(0, 1, At, B1); PG8_BAR; PG8_SCHED;
	s_setprio 1
	v_mfma_f32_16x16x32_bf16 v[62:65], v[148:151], v[200:203], v[62:65]
	v_mfma_f32_16x16x32_bf16 v[58:61], v[156:159], v[200:203], v[58:61]
	v_mfma_f32_16x16x32_bf16 v[54:57], v[148:151], v[208:211], v[54:57]
	v_mfma_f32_16x16x32_bf16 v[46:49], v[156:159], v[208:211], v[46:49]
	v_mfma_f32_16x16x32_bf16 v[38:41], v[148:151], v[232:235], v[38:41]
	v_mfma_f32_16x16x32_bf16 v[30:33], v[156:159], v[232:235], v[30:33]
	v_mfma_f32_16x16x32_bf16 v[22:25], v[148:151], v[240:243], v[22:25]
	v_mfma_f32_16x16x32_bf16 v[14:17], v[156:159], v[240:243], v[14:17]
	v_mfma_f32_16x16x32_bf16 v[62:65], v[152:155], v[204:207], v[62:65]
	v_mfma_f32_16x16x32_bf16 v[58:61], v[180:183], v[204:207], v[58:61]
	v_mfma_f32_16x16x32_bf16 v[54:57], v[152:155], v[228:231], v[54:57]
	v_mfma_f32_16x16x32_bf16 v[46:49], v[180:183], v[228:231], v[46:49]
	v_mfma_f32_16x16x32_bf16 v[38:41], v[152:155], v[236:239], v[38:41]
	v_mfma_f32_16x16x32_bf16 v[30:33], v[180:183], v[236:239], v[30:33]
	v_mfma_f32_16x16x32_bf16 v[22:25], v[152:155], v[244:247], v[22:25]
	v_mfma_f32_16x16x32_bf16 v[14:17], v[180:183], v[244:247], v[14:17]
	v_mfma_f32_16x16x32_bf16 v[50:53], v[184:187], v[200:203], v[50:53]
	v_mfma_f32_16x16x32_bf16 v[42:45], v[192:195], v[200:203], v[42:45]
	v_mfma_f32_16x16x32_bf16 v[34:37], v[184:187], v[208:211], v[34:37]
	v_mfma_f32_16x16x32_bf16 v[26:29], v[192:195], v[208:211], v[26:29]
	v_mfma_f32_16x16x32_bf16 v[18:21], v[184:187], v[232:235], v[18:21]
	v_mfma_f32_16x16x32_bf16 v[10:13], v[192:195], v[232:235], v[10:13]
	v_mfma_f32_16x16x32_bf16 v[6:9], v[184:187], v[240:243], v[6:9]
	v_mfma_f32_16x16x32_bf16 v[2:5], v[192:195], v[240:243], v[2:5]
	v_mfma_f32_16x16x32_bf16 v[50:53], v[188:191], v[204:207], v[50:53]
	v_mfma_f32_16x16x32_bf16 v[42:45], v[196:199], v[204:207], v[42:45]
	v_mfma_f32_16x16x32_bf16 v[34:37], v[188:191], v[228:231], v[34:37]
	v_mfma_f32_16x16x32_bf16 v[26:29], v[196:199], v[228:231], v[26:29]
	v_mfma_f32_16x16x32_bf16 v[18:21], v[188:191], v[236:239], v[18:21]
	v_mfma_f32_16x16x32_bf16 v[10:13], v[196:199], v[236:239], v[10:13]
	v_mfma_f32_16x16x32_bf16 v[6:9], v[188:191], v[244:247], v[6:9]
	v_mfma_f32_16x16x32_bf16 v[2:5], v[196:199], v[244:247], v[2:5]
	s_setprio 0
	s_barrier
	s_add_i32 s47, 0, 0x18000
	v_add_u32_e32 v167, s47, v143
	s_add_i32 s49, 0, 0x1c000
	ds_read_b128 v[148:151], v167
	ds_read_b128 v[152:155], v167 offset:1024
	ds_read_b128 v[156:159], v167 offset:2048
	ds_read_b128 v[180:183], v167 offset:3072
	v_add_u32_e32 v167, s49, v143
	ds_read_b128 v[184:187], v167
	ds_read_b128 v[188:191], v167 offset:1024
	ds_read_b128 v[192:195], v167 offset:2048
	ds_read_b128 v[196:199], v167 offset:3072
	s_add_u32 s26, s26, 0x20000
	s_addc_u32 s27, s27, 0
	s_mov_b32 m0, s30
	v_lshl_add_u64 v[250:251], s[26:27], 0, v[132:133]
	ds_read_b128 v[200:203], v147 offset:32768
	ds_read_b128 v[204:207], v147 offset:33792
	ds_read_b128 v[208:211], v147 offset:34816
	ds_read_b128 v[228:231], v147 offset:35840
	ds_read_b128 v[232:235], v147 offset:36864
	ds_read_b128 v[236:239], v147 offset:37888
	ds_read_b128 v[240:243], v147 offset:38912
	ds_read_b128 v[244:247], v147 offset:39936
	global_load_lds_dwordx4 v[250:251], off
	v_lshl_add_u64 v[250:251], s[26:27], 0, v[130:131]
	s_mov_b32 m0, s31
	s_nop 0
	global_load_lds_dwordx4 v[250:251], off
	s_waitcnt vmcnt(8)
	s_waitcnt lgkmcnt(0)
	s_barrier
	s_setprio 1
	v_mfma_f32_16x16x32_bf16 v[126:129], v[148:151], v[200:203], v[126:129]
	v_mfma_f32_16x16x32_bf16 v[122:125], v[156:159], v[200:203], v[122:125]
	v_mfma_f32_16x16x32_bf16 v[118:121], v[148:151], v[208:211], v[118:121]
	v_mfma_f32_16x16x32_bf16 v[110:113], v[156:159], v[208:211], v[110:113]
	v_mfma_f32_16x16x32_bf16 v[102:105], v[148:151], v[232:235], v[102:105]
	v_mfma_f32_16x16x32_bf16 v[94:97], v[156:159], v[232:235], v[94:97]
	v_mfma_f32_16x16x32_bf16 v[86:89], v[148:151], v[240:243], v[86:89]
	v_mfma_f32_16x16x32_bf16 v[78:81], v[156:159], v[240:243], v[78:81]
	v_mfma_f32_16x16x32_bf16 v[126:129], v[152:155], v[204:207], v[126:129]
	v_mfma_f32_16x16x32_bf16 v[122:125], v[180:183], v[204:207], v[122:125]
	v_mfma_f32_16x16x32_bf16 v[118:121], v[152:155], v[228:231], v[118:121]
	v_mfma_f32_16x16x32_bf16 v[110:113], v[180:183], v[228:231], v[110:113]
	v_mfma_f32_16x16x32_bf16 v[102:105], v[152:155], v[236:239], v[102:105]
	v_mfma_f32_16x16x32_bf16 v[94:97], v[180:183], v[236:239], v[94:97]
	v_mfma_f32_16x16x32_bf16 v[86:89], v[152:155], v[244:247], v[86:89]
	v_mfma_f32_16x16x32_bf16 v[78:81], v[180:183], v[244:247], v[78:81]
	v_mfma_f32_16x16x32_bf16 v[114:117], v[184:187], v[200:203], v[114:117]
	v_mfma_f32_16x16x32_bf16 v[106:109], v[192:195], v[200:203], v[106:109]
	v_mfma_f32_16x16x32_bf16 v[98:101], v[184:187], v[208:211], v[98:101]
	v_mfma_f32_16x16x32_bf16 v[90:93], v[192:195], v[208:211], v[90:93]
	v_mfma_f32_16x16x32_bf16 v[82:85], v[184:187], v[232:235], v[82:85]
	v_mfma_f32_16x16x32_bf16 v[74:77], v[192:195], v[232:235], v[74:77]
	v_mfma_f32_16x16x32_bf16 v[70:73], v[184:187], v[240:243], v[70:73]
	v_mfma_f32_16x16x32_bf16 v[66:69], v[192:195], v[240:243], v[66:69]
	v_mfma_f32_16x16x32_bf16 v[114:117], v[188:191], v[204:207], v[114:117]
	v_mfma_f32_16x16x32_bf16 v[106:109], v[196:199], v[204:207], v[106:109]
	v_mfma_f32_16x16x32_bf16 v[98:101], v[188:191], v[228:231], v[98:101]
	v_mfma_f32_16x16x32_bf16 v[90:93], v[196:199], v[228:231], v[90:93]
	v_mfma_f32_16x16x32_bf16 v[82:85], v[188:191], v[236:239], v[82:85]
	v_mfma_f32_16x16x32_bf16 v[74:77], v[196:199], v[236:239], v[74:77]
	v_mfma_f32_16x16x32_bf16 v[70:73], v[188:191], v[244:247], v[70:73]
	v_mfma_f32_16x16x32_bf16 v[66:69], v[196:199], v[244:247], v[66:69]
	s_setprio 0
	s_barrier
; #define PG8_STAGE(bufoff, gbase, voff) do { _Pragma("unroll") for (int _i = 0; _i < 2; ++_i) \
;         __builtin_amdgcn_global_load_lds((const unsigned*)((const char*)(gbase) + (voff)[_i]), (PG8_LAS unsigned*)(lds + (bufoff) + ldsw + _i * 8192), 16, 0, 0); } while (0)
; #define PG8_LDA(dst, b, h) do { _Pragma("unroll") for (int m = 0; m < 4; ++m) _Pragma("unroll") for (int k = 0; k < 2; ++k) dst[m][k] = *(const PG8_LAS bf16x8*)(lds + PG8_SA(b, h) + aoff + m * 2048 + k * 1024); } while (0)
; #define PG8_WAIT_V(n) asm volatile("s_waitcnt vmcnt(" #n ")" ::: "memory")
; template <class Epi, class Sched, bool ALIGN_EPI = false, bool SP2 = false>
; __device__ __forceinline__ void gemm_phase(PG8_LAS unsigned char* lds, const Gemm g, const Sched& S, const Epi& E) {
;     ...
;             PG8_LDA(At, 1, 1); PG8_STAGE(PG8_SB(1, 0), b3, voffB); PG8_STAGE(PG8_SB(1, 1), b3 + hstep, voffB); PG8_STAGE(PG8_SA(1, 0), a3, voffA);
;             PG8_WAIT_V(8); PG8_WAIT_L(0); PG8_BAR; PG8_MMA(1, 0, At, B0); PG8_MMA(1, 1, At, B1); PG8_BAR; PG8_SCHED;
;             } else {
;             PG8_LDB(B0, 0, 0); PG8_SCHED; PG8_LDA(At, 0, 0); PG8_STAGE(PG8_SA(1, 1), a1 + hstep, voffA);
;             PG8_WAIT_L(8); PG8_BAR; PG8_WAIT_L(0); PG8_MMA(0, 0, At, B0); PG8_BAR; PG8_SCHED;
;             PG8_LDB(B1, 0, 1); PG8_STAGE(PG8_SB(0, 0), b2, voffB);
;             PG8_BAR; PG8_WAIT_L(0); PG8_MMA(0, 1, At, B1); PG8_BAR;
;             PG8_LDA(At, 0, 1); PG8_STAGE(PG8_SA(0, 0), a2, voffA);
;             PG8_BAR; PG8_WAIT_L(0); PG8_MMA(1, 0, At, B0); PG8_BAR; PG8_SCHED;
;             PG8_STAGE(PG8_SB(0, 1), b2 + hstep, voffB);
;             PG8_WAIT_V(6); PG8_BAR; PG8_MMA(1, 1, At, B1); PG8_BAR;
;             PG8_LDB(B0, 1, 0); PG8_SCHED; PG8_LDA(At, 1, 0); PG8_STAGE(PG8_SA(0, 1), a2 + hstep, voffA);
;             PG8_WAIT_L(8); PG8_BAR; PG8_WAIT_L(0); PG8_MMA(0, 0, At, B0); PG8_BAR; PG8_SCHED;
;             PG8_LDB(B1, 1, 1); PG8_STAGE(PG8_SB(1, 0), b3, voffB);
;             PG8_BAR; PG8_WAIT_L(0); PG8_MMA(0, 1, At, B1); PG8_BAR;
;             PG8_LDA(At, 1, 1); PG8_STAGE(PG8_SA(1, 0), a3, voffA);
;             PG8_BAR; PG8_WAIT_L(0); PG8_MMA(1, 0, At, B0); PG8_BAR; PG8_SCHED;
;             PG8_STAGE(PG8_SB(1, 1), b3 + hstep, voffB);
;             PG8_WAIT_V(6); PG8_BAR; PG8_MMA(1, 1, At, B1); PG8_BAR;
;             }
;         }
;         if constexpr (ALIGN_EPI) { if (wr == 0) PG8_BAR; }
	s_add_i32 s26, s47, s2
	v_lshl_add_u64 v[160:161], v[160:161], 0, s[8:9]
	s_mov_b32 m0, s26
	ds_read_b128 v[200:203], v147 offset:49152
	ds_read_b128 v[204:207], v147 offset:50176
	ds_read_b128 v[208:211], v147 offset:51200
	ds_read_b128 v[228:231], v147 offset:52224
	ds_read_b128 v[232:235], v147 offset:53248
	ds_read_b128 v[236:239], v147 offset:54272
	ds_read_b128 v[240:243], v147 offset:55296
	ds_read_b128 v[244:247], v147 offset:56320
	global_load_lds_dwordx4 v[160:161], off
	s_add_i32 m0, s26, 0x2000
	s_add_u32 s24, s24, 0x20080
	v_lshl_add_u64 v[160:161], v[212:213], 0, s[8:9]
	s_addc_u32 s25, s25, 0
	s_add_i32 s26, s49, s2
	global_load_lds_dwordx4 v[160:161], off
	v_lshl_add_u64 v[160:161], s[24:25], 0, v[132:133]
	s_mov_b32 m0, s26
	s_nop 0
	global_load_lds_dwordx4 v[160:161], off
	v_lshl_add_u64 v[160:161], s[24:25], 0, v[130:131]
	s_add_i32 m0, s26, 0x2000
	s_nop 0
	global_load_lds_dwordx4 v[160:161], off
	v_lshl_add_u64 v[160:161], v[222:223], 0, s[8:9]
	s_mov_b32 m0, s34
	s_nop 0
	global_load_lds_dwordx4 v[160:161], off
	v_lshl_add_u64 v[160:161], v[248:249], 0, s[8:9]
	s_mov_b32 m0, s35
	s_nop 0
	global_load_lds_dwordx4 v[160:161], off
	s_waitcnt vmcnt(8)
	s_waitcnt lgkmcnt(0)
	s_barrier
	s_setprio 1
	v_mfma_f32_16x16x32_bf16 v[62:65], v[148:151], v[200:203], v[62:65]
	v_mfma_f32_16x16x32_bf16 v[58:61], v[156:159], v[200:203], v[58:61]
	v_mfma_f32_16x16x32_bf16 v[54:57], v[148:151], v[208:211], v[54:57]
	v_mfma_f32_16x16x32_bf16 v[46:49], v[156:159], v[208:211], v[46:49]
	v_mfma_f32_16x16x32_bf16 v[38:41], v[148:151], v[232:235], v[38:41]
	v_mfma_f32_16x16x32_bf16 v[30:33], v[156:159], v[232:235], v[30:33]
	v_mfma_f32_16x16x32_bf16 v[22:25], v[148:151], v[240:243], v[22:25]
	v_mfma_f32_16x16x32_bf16 v[14:17], v[156:159], v[240:243], v[14:17]
	v_mfma_f32_16x16x32_bf16 v[62:65], v[152:155], v[204:207], v[62:65]
	v_mfma_f32_16x16x32_bf16 v[58:61], v[180:183], v[204:207], v[58:61]
	v_mfma_f32_16x16x32_bf16 v[54:57], v[152:155], v[228:231], v[54:57]
	v_mfma_f32_16x16x32_bf16 v[46:49], v[180:183], v[228:231], v[46:49]
	v_mfma_f32_16x16x32_bf16 v[38:41], v[152:155], v[236:239], v[38:41]
	v_mfma_f32_16x16x32_bf16 v[30:33], v[180:183], v[236:239], v[30:33]
	v_mfma_f32_16x16x32_bf16 v[22:25], v[152:155], v[244:247], v[22:25]
	v_mfma_f32_16x16x32_bf16 v[14:17], v[180:183], v[244:247], v[14:17]
	v_mfma_f32_16x16x32_bf16 v[50:53], v[184:187], v[200:203], v[50:53]
	v_mfma_f32_16x16x32_bf16 v[42:45], v[192:195], v[200:203], v[42:45]
	v_mfma_f32_16x16x32_bf16 v[34:37], v[184:187], v[208:211], v[34:37]
	v_mfma_f32_16x16x32_bf16 v[26:29], v[192:195], v[208:211], v[26:29]
	v_mfma_f32_16x16x32_bf16 v[18:21], v[184:187], v[232:235], v[18:21]
	v_mfma_f32_16x16x32_bf16 v[10:13], v[192:195], v[232:235], v[10:13]
	v_mfma_f32_16x16x32_bf16 v[6:9], v[184:187], v[240:243], v[6:9]
	v_mfma_f32_16x16x32_bf16 v[2:5], v[192:195], v[240:243], v[2:5]
	v_mfma_f32_16x16x32_bf16 v[50:53], v[188:191], v[204:207], v[50:53]
	v_mfma_f32_16x16x32_bf16 v[42:45], v[196:199], v[204:207], v[42:45]
	v_mfma_f32_16x16x32_bf16 v[34:37], v[188:191], v[228:231], v[34:37]
	v_mfma_f32_16x16x32_bf16 v[26:29], v[196:199], v[228:231], v[26:29]
	v_mfma_f32_16x16x32_bf16 v[18:21], v[188:191], v[236:239], v[18:21]
	v_mfma_f32_16x16x32_bf16 v[10:13], v[196:199], v[236:239], v[10:13]
	v_mfma_f32_16x16x32_bf16 v[6:9], v[188:191], v[244:247], v[6:9]
	v_mfma_f32_16x16x32_bf16 v[2:5], v[196:199], v[244:247], v[2:5]
	s_setprio 0
	s_barrier
	s_add_u32 s6, s6, 0x100
	s_addc_u32 s7, s7, 0
	s_add_u32 s45, s45, 0x100
	s_addc_u32 s46, s46, 0
	s_cmp_ge_u32 s48, s40
	s_mov_b32 s47, s48
	s_cbranch_scc0 .LBB0_1228
	s_and_b64 vcc, exec, s[10:11]
	s_cbranch_vccz .LBB0_1231
	s_barrier

; #define PG8_STAGE(bufoff, gbase, voff) do { _Pragma("unroll") for (int _i = 0; _i < 2; ++_i) \
;         __builtin_amdgcn_global_load_lds((const unsigned*)((const char*)(gbase) + (voff)[_i]), (PG8_LAS unsigned*)(lds + (bufoff) + ldsw + _i * 8192), 16, 0, 0); } while (0)
; #define PG8_LDA(dst, b, h) do { _Pragma("unroll") for (int m = 0; m < 4; ++m) _Pragma("unroll") for (int k = 0; k < 2; ++k) dst[m][k] = *(const PG8_LAS bf16x8*)(lds + PG8_SA(b, h) + aoff + m * 2048 + k * 1024); } while (0)
; #define PG8_LDB(dst, b, h) do { _Pragma("unroll") for (int n = 0; n < 2; ++n) _Pragma("unroll") for (int k = 0; k < 2; ++k) dst[n][k] = *(const PG8_LAS bf16x8*)(lds + PG8_SB(b, h) + boff + n * 2048 + k * 1024); } while (0)
; #define PG8_MMA(ai, bj, At, Bt) do { __builtin_amdgcn_s_setprio(1); _Pragma("unroll") for (int m = 0; m < 4; ++m) _Pragma("unroll") for (int n = 0; n < 2; ++n) _Pragma("unroll") for (int k = 0; k < 2; ++k) \
;         acc[ai][bj][m][n] = __builtin_amdgcn_mfma_f32_16x16x32_bf16(Bt[n][k], At[m][k], acc[ai][bj][m][n], 0, 0, 0); __builtin_amdgcn_s_setprio(0); } while (0)
; #define PG8_WAIT_V(n) asm volatile("s_waitcnt vmcnt(" #n ")" ::: "memory")
; #define PG8_BAR __builtin_amdgcn_s_barrier()
; template <class Epi, class Sched, bool ALIGN_EPI = false, bool SP2 = false>
; __device__ __forceinline__ void gemm_phase(PG8_LAS unsigned char* lds, const Gemm g, const Sched& S, const Epi& E) {
;     ...
;         for (int t = 0; t < nt; t += 2) {
;             const bool last = (t == nt - 2);
;             const char* a1 = cA + (size_t)(t + 1) * kstep;
;             const char* a2 = last ? nA : cA + (size_t)(t + 2) * kstep; const char* b2 = last ? nB : cB + (size_t)(t + 2) * kstep;
;             const char* a3 = a2 + kstep; const char* b3 = b2 + kstep;
;             if (last && has_next) S.a_ready(nxt);
;             if constexpr (SP2) {
;             PG8_LDB(B0, 0, 0); PG8_LDB(B1, 0, 1); PG8_SCHED; PG8_LDA(At, 0, 0); PG8_STAGE(PG8_SA(1, 1), a1 + hstep, voffA);
;             PG8_WAIT_V(8); PG8_WAIT_L(0); PG8_BAR; PG8_MMA(0, 0, At, B0); PG8_MMA(0, 1, At, B1); PG8_BAR; PG8_SCHED;
;             PG8_LDA(At, 0, 1); PG8_STAGE(PG8_SB(0, 0), b2, voffB); PG8_STAGE(PG8_SB(0, 1), b2 + hstep, voffB); PG8_STAGE(PG8_SA(0, 0), a2, voffA);
;             PG8_WAIT_V(8); PG8_WAIT_L(0); PG8_BAR; PG8_MMA(1, 0, At, B0); PG8_MMA(1, 1, At, B1); PG8_BAR; PG8_SCHED;
.LBB0_1373:
	ds_read_b128 v[146:149], v143
	ds_read_b128 v[150:153], v143 offset:1024
	ds_read_b128 v[154:157], v143 offset:2048
	ds_read_b128 v[158:161], v143 offset:3072
	ds_read_b128 v[178:181], v144
	ds_read_b128 v[182:185], v144 offset:1024
	ds_read_b128 v[186:189], v144 offset:2048
	ds_read_b128 v[190:193], v144 offset:3072
	s_add_i32 s47, s46, 2
	s_add_u32 s22, s0, 0xfff80080
	s_addc_u32 s23, s1, -1
	s_cmp_eq_u32 s43, s46
	s_cselect_b32 s25, s15, s23
	s_cselect_b32 s24, s41, s22
	s_cselect_b32 s23, s13, s45
	s_cselect_b32 s22, s42, s44
	v_lshl_add_u64 v[138:139], s[0:1], 0, v[130:131]
	s_add_i32 m0, s21, 0xc000
	ds_read_b128 v[194:197], v145
	ds_read_b128 v[198:201], v145 offset:1024
	ds_read_b128 v[202:205], v145 offset:2048
	ds_read_b128 v[206:209], v145 offset:3072
	ds_read_b128 v[210:213], v145 offset:4096
	ds_read_b128 v[218:221], v145 offset:5120
	ds_read_b128 v[228:231], v145 offset:6144
	ds_read_b128 v[232:235], v145 offset:7168
	global_load_lds_dwordx4 v[138:139], off
	v_lshl_add_u64 v[138:139], s[0:1], 0, v[132:133]
	s_add_i32 m0, s21, 0xe000
	s_nop 0
	global_load_lds_dwordx4 v[138:139], off
	s_waitcnt vmcnt(8)
	s_waitcnt lgkmcnt(0)
	s_barrier
	s_setprio 1
	v_mfma_f32_16x16x32_bf16 v[126:129], v[146:149], v[194:197], v[126:129]
	v_mfma_f32_16x16x32_bf16 v[122:125], v[154:157], v[194:197], v[122:125]
	v_mfma_f32_16x16x32_bf16 v[110:113], v[146:149], v[202:205], v[110:113]
	v_mfma_f32_16x16x32_bf16 v[106:109], v[154:157], v[202:205], v[106:109]
	v_mfma_f32_16x16x32_bf16 v[94:97], v[146:149], v[210:213], v[94:97]
	v_mfma_f32_16x16x32_bf16 v[90:93], v[154:157], v[210:213], v[90:93]
	v_mfma_f32_16x16x32_bf16 v[78:81], v[146:149], v[228:231], v[78:81]
	v_mfma_f32_16x16x32_bf16 v[74:77], v[154:157], v[228:231], v[74:77]
	v_mfma_f32_16x16x32_bf16 v[126:129], v[150:153], v[198:201], v[126:129]
	v_mfma_f32_16x16x32_bf16 v[122:125], v[158:161], v[198:201], v[122:125]
	v_mfma_f32_16x16x32_bf16 v[110:113], v[150:153], v[206:209], v[110:113]
	v_mfma_f32_16x16x32_bf16 v[106:109], v[158:161], v[206:209], v[106:109]
	v_mfma_f32_16x16x32_bf16 v[94:97], v[150:153], v[218:221], v[94:97]
	v_mfma_f32_16x16x32_bf16 v[90:93], v[158:161], v[218:221], v[90:93]
	v_mfma_f32_16x16x32_bf16 v[78:81], v[150:153], v[232:235], v[78:81]
	v_mfma_f32_16x16x32_bf16 v[74:77], v[158:161], v[232:235], v[74:77]
	v_mfma_f32_16x16x32_bf16 v[118:121], v[178:181], v[194:197], v[118:121]
	v_mfma_f32_16x16x32_bf16 v[114:117], v[186:189], v[194:197], v[114:117]
	v_mfma_f32_16x16x32_bf16 v[102:105], v[178:181], v[202:205], v[102:105]
	v_mfma_f32_16x16x32_bf16 v[98:101], v[186:189], v[202:205], v[98:101]
	v_mfma_f32_16x16x32_bf16 v[86:89], v[178:181], v[210:213], v[86:89]
	v_mfma_f32_16x16x32_bf16 v[82:85], v[186:189], v[210:213], v[82:85]
	v_mfma_f32_16x16x32_bf16 v[70:73], v[178:181], v[228:231], v[70:73]
	v_mfma_f32_16x16x32_bf16 v[66:69], v[186:189], v[228:231], v[66:69]
	v_mfma_f32_16x16x32_bf16 v[118:121], v[182:185], v[198:201], v[118:121]
	v_mfma_f32_16x16x32_bf16 v[114:117], v[190:193], v[198:201], v[114:117]
	v_mfma_f32_16x16x32_bf16 v[102:105], v[182:185], v[206:209], v[102:105]
	v_mfma_f32_16x16x32_bf16 v[98:101], v[190:193], v[206:209], v[98:101]
	v_mfma_f32_16x16x32_bf16 v[86:89], v[182:185], v[218:221], v[86:89]
	v_mfma_f32_16x16x32_bf16 v[82:85], v[190:193], v[218:221], v[82:85]
	v_mfma_f32_16x16x32_bf16 v[70:73], v[182:185], v[232:235], v[70:73]
	v_mfma_f32_16x16x32_bf16 v[66:69], v[190:193], v[232:235], v[66:69]
	s_setprio 0
	s_barrier
	s_add_i32 s46, s35, s2
	v_lshl_add_u64 v[138:139], s[22:23], 0, v[168:169]
	s_mov_b32 m0, s46
	ds_read_b128 v[194:197], v145 offset:16384
	ds_read_b128 v[198:201], v145 offset:17408
	ds_read_b128 v[202:205], v145 offset:18432
	ds_read_b128 v[206:209], v145 offset:19456
	ds_read_b128 v[210:213], v145 offset:20480
	ds_read_b128 v[218:221], v145 offset:21504
	ds_read_b128 v[228:231], v145 offset:22528
	ds_read_b128 v[232:235], v145 offset:23552
	global_load_lds_dwordx4 v[138:139], off
	s_add_i32 m0, s46, 0x2000
	s_add_u32 s48, s22, 0x80000
	v_lshl_add_u64 v[222:223], s[22:23], 0, v[172:173]
	s_addc_u32 s49, s23, 0
	s_add_i32 s46, s36, s2
	global_load_lds_dwordx4 v[222:223], off
	v_lshl_add_u64 v[236:237], s[48:49], 0, v[168:169]
	s_mov_b32 m0, s46
	v_lshl_add_u64 v[238:239], s[24:25], 0, v[170:171]
	global_load_lds_dwordx4 v[236:237], off
	v_lshl_add_u64 v[236:237], s[48:49], 0, v[172:173]
	s_add_i32 m0, s46, 0x2000
	s_nop 0
	global_load_lds_dwordx4 v[236:237], off
	v_lshl_add_u64 v[236:237], s[24:25], 0, v[166:167]
	s_mov_b32 m0, s21
	s_nop 0
	global_load_lds_dwordx4 v[236:237], off
	s_mov_b32 m0, s27
	s_nop 0
	global_load_lds_dwordx4 v[238:239], off
	s_waitcnt vmcnt(8)
	s_waitcnt lgkmcnt(0)
	s_barrier
; #define PG8_STAGE(bufoff, gbase, voff) do { _Pragma("unroll") for (int _i = 0; _i < 2; ++_i) \
;         __builtin_amdgcn_global_load_lds((const unsigned*)((const char*)(gbase) + (voff)[_i]), (PG8_LAS unsigned*)(lds + (bufoff) + ldsw + _i * 8192), 16, 0, 0); } while (0)
; #define PG8_LDA(dst, b, h) do { _Pragma("unroll") for (int m = 0; m < 4; ++m) _Pragma("unroll") for (int k = 0; k < 2; ++k) dst[m][k] = *(const PG8_LAS bf16x8*)(lds + PG8_SA(b, h) + aoff + m * 2048 + k * 1024); } while (0)
; #define PG8_LDB(dst, b, h) do { _Pragma("unroll") for (int n = 0; n < 2; ++n) _Pragma("unroll") for (int k = 0; k < 2; ++k) dst[n][k] = *(const PG8_LAS bf16x8*)(lds + PG8_SB(b, h) + boff + n * 2048 + k * 1024); } while (0)
; #define PG8_MMA(ai, bj, At, Bt) do { __builtin_amdgcn_s_setprio(1); _Pragma("unroll") for (int m = 0; m < 4; ++m) _Pragma("unroll") for (int n = 0; n < 2; ++n) _Pragma("unroll") for (int k = 0; k < 2; ++k) \
;         acc[ai][bj][m][n] = __builtin_amdgcn_mfma_f32_16x16x32_bf16(Bt[n][k], At[m][k], acc[ai][bj][m][n], 0, 0, 0); __builtin_amdgcn_s_setprio(0); } while (0)
; #define PG8_WAIT_V(n) asm volatile("s_waitcnt vmcnt(" #n ")" ::: "memory")
; #define PG8_WAIT_L(n) asm volatile("s_waitcnt lgkmcnt(" #n ")" ::: "memory")
; #define PG8_BAR __builtin_amdgcn_s_barrier()
; #define PG8_SCHED __builtin_amdgcn_sched_barrier(0)
; template <class Epi, class Sched, bool ALIGN_EPI = false, bool SP2 = false>
; __device__ __forceinline__ void gemm_phase(PG8_LAS unsigned char* lds, const Gemm g, const Sched& S, const Epi& E) {
;     ...
;             PG8_WAIT_V(8); PG8_WAIT_L(0); PG8_BAR; PG8_MMA(1, 0, At, B0); PG8_MMA(1, 1, At, B1); PG8_BAR; PG8_SCHED;
;             PG8_LDB(B0, 1, 0); PG8_LDB(B1, 1, 1); PG8_SCHED; PG8_LDA(At, 1, 0); PG8_STAGE(PG8_SA(0, 1), a2 + hstep, voffA);
;             PG8_WAIT_V(8); PG8_WAIT_L(0); PG8_BAR; PG8_MMA(0, 0, At, B0); PG8_MMA(0, 1, At, B1); PG8_BAR; PG8_SCHED;
	s_setprio 1
	v_mfma_f32_16x16x32_bf16 v[62:65], v[146:149], v[194:197], v[62:65]
	v_mfma_f32_16x16x32_bf16 v[58:61], v[154:157], v[194:197], v[58:61]
	v_mfma_f32_16x16x32_bf16 v[46:49], v[146:149], v[202:205], v[46:49]
	v_mfma_f32_16x16x32_bf16 v[42:45], v[154:157], v[202:205], v[42:45]
	v_mfma_f32_16x16x32_bf16 v[30:33], v[146:149], v[210:213], v[30:33]
	v_mfma_f32_16x16x32_bf16 v[26:29], v[154:157], v[210:213], v[26:29]
	v_mfma_f32_16x16x32_bf16 v[14:17], v[146:149], v[228:231], v[14:17]
	v_mfma_f32_16x16x32_bf16 v[10:13], v[154:157], v[228:231], v[10:13]
	v_mfma_f32_16x16x32_bf16 v[62:65], v[150:153], v[198:201], v[62:65]
	v_mfma_f32_16x16x32_bf16 v[58:61], v[158:161], v[198:201], v[58:61]
	v_mfma_f32_16x16x32_bf16 v[46:49], v[150:153], v[206:209], v[46:49]
	v_mfma_f32_16x16x32_bf16 v[42:45], v[158:161], v[206:209], v[42:45]
	v_mfma_f32_16x16x32_bf16 v[30:33], v[150:153], v[218:221], v[30:33]
	v_mfma_f32_16x16x32_bf16 v[26:29], v[158:161], v[218:221], v[26:29]
	v_mfma_f32_16x16x32_bf16 v[14:17], v[150:153], v[232:235], v[14:17]
	v_mfma_f32_16x16x32_bf16 v[10:13], v[158:161], v[232:235], v[10:13]
	v_mfma_f32_16x16x32_bf16 v[54:57], v[178:181], v[194:197], v[54:57]
	v_mfma_f32_16x16x32_bf16 v[50:53], v[186:189], v[194:197], v[50:53]
	v_mfma_f32_16x16x32_bf16 v[38:41], v[178:181], v[202:205], v[38:41]
	v_mfma_f32_16x16x32_bf16 v[34:37], v[186:189], v[202:205], v[34:37]
	v_mfma_f32_16x16x32_bf16 v[22:25], v[178:181], v[210:213], v[22:25]
	v_mfma_f32_16x16x32_bf16 v[18:21], v[186:189], v[210:213], v[18:21]
	v_mfma_f32_16x16x32_bf16 v[6:9], v[178:181], v[228:231], v[6:9]
	v_mfma_f32_16x16x32_bf16 v[2:5], v[186:189], v[228:231], v[2:5]
	v_mfma_f32_16x16x32_bf16 v[54:57], v[182:185], v[198:201], v[54:57]
	v_mfma_f32_16x16x32_bf16 v[50:53], v[190:193], v[198:201], v[50:53]
	v_mfma_f32_16x16x32_bf16 v[38:41], v[182:185], v[206:209], v[38:41]
	v_mfma_f32_16x16x32_bf16 v[34:37], v[190:193], v[206:209], v[34:37]
	v_mfma_f32_16x16x32_bf16 v[22:25], v[182:185], v[218:221], v[22:25]
	v_mfma_f32_16x16x32_bf16 v[18:21], v[190:193], v[218:221], v[18:21]
	v_mfma_f32_16x16x32_bf16 v[6:9], v[182:185], v[232:235], v[6:9]
	v_mfma_f32_16x16x32_bf16 v[2:5], v[190:193], v[232:235], v[2:5]
	s_setprio 0
	s_barrier
	s_add_i32 s46, 0, 0x18000
	s_add_i32 s48, 0, 0x1c000
	v_add_u32_e32 v158, s46, v141
	v_add_u32_e32 v175, s48, v141
	ds_read_b128 v[146:149], v158
	ds_read_b128 v[150:153], v158 offset:1024
	ds_read_b128 v[154:157], v158 offset:2048
	ds_read_b128 v[158:161], v158 offset:3072
	ds_read_b128 v[178:181], v175
	ds_read_b128 v[182:185], v175 offset:1024
	ds_read_b128 v[186:189], v175 offset:2048
	ds_read_b128 v[190:193], v175 offset:3072
	s_add_u32 s24, s24, 0x80000
	s_addc_u32 s25, s25, 0
	s_mov_b32 m0, s28
	v_lshl_add_u64 v[240:241], s[24:25], 0, v[166:167]
	ds_read_b128 v[194:197], v145 offset:32768
	ds_read_b128 v[198:201], v145 offset:33792
	ds_read_b128 v[202:205], v145 offset:34816
	ds_read_b128 v[206:209], v145 offset:35840
	ds_read_b128 v[210:213], v145 offset:36864
	ds_read_b128 v[218:221], v145 offset:37888
	ds_read_b128 v[228:231], v145 offset:38912
	ds_read_b128 v[232:235], v145 offset:39936
	global_load_lds_dwordx4 v[240:241], off
	v_lshl_add_u64 v[240:241], s[24:25], 0, v[170:171]
	s_mov_b32 m0, s29
	s_nop 0
	global_load_lds_dwordx4 v[240:241], off
	s_waitcnt vmcnt(8)
	s_waitcnt lgkmcnt(0)
	s_barrier
	s_setprio 1
	v_mfma_f32_16x16x32_bf16 v[126:129], v[146:149], v[194:197], v[126:129]
	v_mfma_f32_16x16x32_bf16 v[122:125], v[154:157], v[194:197], v[122:125]
	v_mfma_f32_16x16x32_bf16 v[110:113], v[146:149], v[202:205], v[110:113]
	v_mfma_f32_16x16x32_bf16 v[106:109], v[154:157], v[202:205], v[106:109]
	v_mfma_f32_16x16x32_bf16 v[94:97], v[146:149], v[210:213], v[94:97]
	v_mfma_f32_16x16x32_bf16 v[90:93], v[154:157], v[210:213], v[90:93]
	v_mfma_f32_16x16x32_bf16 v[78:81], v[146:149], v[228:231], v[78:81]
	v_mfma_f32_16x16x32_bf16 v[74:77], v[154:157], v[228:231], v[74:77]
	v_mfma_f32_16x16x32_bf16 v[126:129], v[150:153], v[198:201], v[126:129]
	v_mfma_f32_16x16x32_bf16 v[122:125], v[158:161], v[198:201], v[122:125]
	v_mfma_f32_16x16x32_bf16 v[110:113], v[150:153], v[206:209], v[110:113]
	v_mfma_f32_16x16x32_bf16 v[106:109], v[158:161], v[206:209], v[106:109]
	v_mfma_f32_16x16x32_bf16 v[94:97], v[150:153], v[218:221], v[94:97]
	v_mfma_f32_16x16x32_bf16 v[90:93], v[158:161], v[218:221], v[90:93]
	v_mfma_f32_16x16x32_bf16 v[78:81], v[150:153], v[232:235], v[78:81]
	v_mfma_f32_16x16x32_bf16 v[74:77], v[158:161], v[232:235], v[74:77]
	v_mfma_f32_16x16x32_bf16 v[118:121], v[178:181], v[194:197], v[118:121]
	v_mfma_f32_16x16x32_bf16 v[114:117], v[186:189], v[194:197], v[114:117]
	v_mfma_f32_16x16x32_bf16 v[102:105], v[178:181], v[202:205], v[102:105]
	v_mfma_f32_16x16x32_bf16 v[98:101], v[186:189], v[202:205], v[98:101]
	v_mfma_f32_16x16x32_bf16 v[86:89], v[178:181], v[210:213], v[86:89]
	v_mfma_f32_16x16x32_bf16 v[82:85], v[186:189], v[210:213], v[82:85]
	v_mfma_f32_16x16x32_bf16 v[70:73], v[178:181], v[228:231], v[70:73]
	v_mfma_f32_16x16x32_bf16 v[66:69], v[186:189], v[228:231], v[66:69]
	v_mfma_f32_16x16x32_bf16 v[118:121], v[182:185], v[198:201], v[118:121]
	v_mfma_f32_16x16x32_bf16 v[114:117], v[190:193], v[198:201], v[114:117]
	v_mfma_f32_16x16x32_bf16 v[102:105], v[182:185], v[206:209], v[102:105]
	v_mfma_f32_16x16x32_bf16 v[98:101], v[190:193], v[206:209], v[98:101]
	v_mfma_f32_16x16x32_bf16 v[86:89], v[182:185], v[218:221], v[86:89]
	v_mfma_f32_16x16x32_bf16 v[82:85], v[190:193], v[218:221], v[82:85]
	v_mfma_f32_16x16x32_bf16 v[70:73], v[182:185], v[232:235], v[70:73]
	v_mfma_f32_16x16x32_bf16 v[66:69], v[190:193], v[232:235], v[66:69]
	s_setprio 0
	s_barrier
; #define PG8_STAGE(bufoff, gbase, voff) do { _Pragma("unroll") for (int _i = 0; _i < 2; ++_i) \
;         __builtin_amdgcn_global_load_lds((const unsigned*)((const char*)(gbase) + (voff)[_i]), (PG8_LAS unsigned*)(lds + (bufoff) + ldsw + _i * 8192), 16, 0, 0); } while (0)
; #define PG8_LDA(dst, b, h) do { _Pragma("unroll") for (int m = 0; m < 4; ++m) _Pragma("unroll") for (int k = 0; k < 2; ++k) dst[m][k] = *(const PG8_LAS bf16x8*)(lds + PG8_SA(b, h) + aoff + m * 2048 + k * 1024); } while (0)
; #define PG8_WAIT_V(n) asm volatile("s_waitcnt vmcnt(" #n ")" ::: "memory")
; template <class Epi, class Sched, bool ALIGN_EPI = false, bool SP2 = false>
; __device__ __forceinline__ void gemm_phase(PG8_LAS unsigned char* lds, const Gemm g, const Sched& S, const Epi& E) {
;     ...
;             PG8_LDA(At, 1, 1); PG8_STAGE(PG8_SB(1, 0), b3, voffB); PG8_STAGE(PG8_SB(1, 1), b3 + hstep, voffB); PG8_STAGE(PG8_SA(1, 0), a3, voffA);
;             PG8_WAIT_V(8); PG8_WAIT_L(0); PG8_BAR; PG8_MMA(1, 0, At, B0); PG8_MMA(1, 1, At, B1); PG8_BAR; PG8_SCHED;
;             } else {
;             PG8_LDB(B0, 0, 0); PG8_SCHED; PG8_LDA(At, 0, 0); PG8_STAGE(PG8_SA(1, 1), a1 + hstep, voffA);
;             PG8_WAIT_L(8); PG8_BAR; PG8_WAIT_L(0); PG8_MMA(0, 0, At, B0); PG8_BAR; PG8_SCHED;
;             PG8_LDB(B1, 0, 1); PG8_STAGE(PG8_SB(0, 0), b2, voffB);
;             PG8_BAR; PG8_WAIT_L(0); PG8_MMA(0, 1, At, B1); PG8_BAR;
;             PG8_LDA(At, 0, 1); PG8_STAGE(PG8_SA(0, 0), a2, voffA);
;             PG8_BAR; PG8_WAIT_L(0); PG8_MMA(1, 0, At, B0); PG8_BAR; PG8_SCHED;
;             PG8_STAGE(PG8_SB(0, 1), b2 + hstep, voffB);
;             PG8_WAIT_V(6); PG8_BAR; PG8_MMA(1, 1, At, B1); PG8_BAR;
;             PG8_LDB(B0, 1, 0); PG8_SCHED; PG8_LDA(At, 1, 0); PG8_STAGE(PG8_SA(0, 1), a2 + hstep, voffA);
;             PG8_WAIT_L(8); PG8_BAR; PG8_WAIT_L(0); PG8_MMA(0, 0, At, B0); PG8_BAR; PG8_SCHED;
;             PG8_LDB(B1, 1, 1); PG8_STAGE(PG8_SB(1, 0), b3, voffB);
;             PG8_BAR; PG8_WAIT_L(0); PG8_MMA(0, 1, At, B1); PG8_BAR;
;             PG8_LDA(At, 1, 1); PG8_STAGE(PG8_SA(1, 0), a3, voffA);
;             PG8_BAR; PG8_WAIT_L(0); PG8_MMA(1, 0, At, B0); PG8_BAR; PG8_SCHED;
;             PG8_STAGE(PG8_SB(1, 1), b3 + hstep, voffB);
;             PG8_WAIT_V(6); PG8_BAR; PG8_MMA(1, 1, At, B1); PG8_BAR;
;             }
;         }
;         if constexpr (ALIGN_EPI) { if (wr == 0) PG8_BAR; }
	s_add_i32 s24, s46, s2
	v_lshl_add_u64 v[138:139], v[138:139], 0, s[8:9]
	s_mov_b32 m0, s24
	ds_read_b128 v[194:197], v145 offset:49152
	ds_read_b128 v[198:201], v145 offset:50176
	ds_read_b128 v[202:205], v145 offset:51200
	ds_read_b128 v[206:209], v145 offset:52224
	ds_read_b128 v[210:213], v145 offset:53248
	ds_read_b128 v[218:221], v145 offset:54272
	ds_read_b128 v[228:231], v145 offset:55296
	ds_read_b128 v[232:235], v145 offset:56320
	global_load_lds_dwordx4 v[138:139], off
	s_add_i32 m0, s24, 0x2000
	s_add_u32 s22, s22, 0x80080
	v_lshl_add_u64 v[138:139], v[222:223], 0, s[8:9]
	s_addc_u32 s23, s23, 0
	s_add_i32 s24, s48, s2
	global_load_lds_dwordx4 v[138:139], off
	v_lshl_add_u64 v[138:139], s[22:23], 0, v[168:169]
	s_mov_b32 m0, s24
	s_nop 0
	global_load_lds_dwordx4 v[138:139], off
	v_lshl_add_u64 v[138:139], s[22:23], 0, v[172:173]
	s_add_i32 m0, s24, 0x2000
	s_nop 0
	global_load_lds_dwordx4 v[138:139], off
	v_lshl_add_u64 v[138:139], v[236:237], 0, s[8:9]
	s_mov_b32 m0, s31
	s_nop 0
	global_load_lds_dwordx4 v[138:139], off
	v_lshl_add_u64 v[138:139], v[238:239], 0, s[8:9]
	s_mov_b32 m0, s33
	s_nop 0
	global_load_lds_dwordx4 v[138:139], off
	s_waitcnt vmcnt(8)
	s_waitcnt lgkmcnt(0)
	s_barrier
	s_setprio 1
	v_mfma_f32_16x16x32_bf16 v[62:65], v[146:149], v[194:197], v[62:65]
	v_mfma_f32_16x16x32_bf16 v[58:61], v[154:157], v[194:197], v[58:61]
	v_mfma_f32_16x16x32_bf16 v[46:49], v[146:149], v[202:205], v[46:49]
	v_mfma_f32_16x16x32_bf16 v[42:45], v[154:157], v[202:205], v[42:45]
	v_mfma_f32_16x16x32_bf16 v[30:33], v[146:149], v[210:213], v[30:33]
	v_mfma_f32_16x16x32_bf16 v[26:29], v[154:157], v[210:213], v[26:29]
	v_mfma_f32_16x16x32_bf16 v[14:17], v[146:149], v[228:231], v[14:17]
	v_mfma_f32_16x16x32_bf16 v[10:13], v[154:157], v[228:231], v[10:13]
	v_mfma_f32_16x16x32_bf16 v[62:65], v[150:153], v[198:201], v[62:65]
	v_mfma_f32_16x16x32_bf16 v[58:61], v[158:161], v[198:201], v[58:61]
	v_mfma_f32_16x16x32_bf16 v[46:49], v[150:153], v[206:209], v[46:49]
	v_mfma_f32_16x16x32_bf16 v[42:45], v[158:161], v[206:209], v[42:45]
	v_mfma_f32_16x16x32_bf16 v[30:33], v[150:153], v[218:221], v[30:33]
	v_mfma_f32_16x16x32_bf16 v[26:29], v[158:161], v[218:221], v[26:29]
	v_mfma_f32_16x16x32_bf16 v[14:17], v[150:153], v[232:235], v[14:17]
	v_mfma_f32_16x16x32_bf16 v[10:13], v[158:161], v[232:235], v[10:13]
	v_mfma_f32_16x16x32_bf16 v[54:57], v[178:181], v[194:197], v[54:57]
	v_mfma_f32_16x16x32_bf16 v[50:53], v[186:189], v[194:197], v[50:53]
	v_mfma_f32_16x16x32_bf16 v[38:41], v[178:181], v[202:205], v[38:41]
	v_mfma_f32_16x16x32_bf16 v[34:37], v[186:189], v[202:205], v[34:37]
	v_mfma_f32_16x16x32_bf16 v[22:25], v[178:181], v[210:213], v[22:25]
	v_mfma_f32_16x16x32_bf16 v[18:21], v[186:189], v[210:213], v[18:21]
	v_mfma_f32_16x16x32_bf16 v[6:9], v[178:181], v[228:231], v[6:9]
	v_mfma_f32_16x16x32_bf16 v[2:5], v[186:189], v[228:231], v[2:5]
	v_mfma_f32_16x16x32_bf16 v[54:57], v[182:185], v[198:201], v[54:57]
	v_mfma_f32_16x16x32_bf16 v[50:53], v[190:193], v[198:201], v[50:53]
	v_mfma_f32_16x16x32_bf16 v[38:41], v[182:185], v[206:209], v[38:41]
	v_mfma_f32_16x16x32_bf16 v[34:37], v[190:193], v[206:209], v[34:37]
	v_mfma_f32_16x16x32_bf16 v[22:25], v[182:185], v[218:221], v[22:25]
	v_mfma_f32_16x16x32_bf16 v[18:21], v[190:193], v[218:221], v[18:21]
	v_mfma_f32_16x16x32_bf16 v[6:9], v[182:185], v[232:235], v[6:9]
	v_mfma_f32_16x16x32_bf16 v[2:5], v[190:193], v[232:235], v[2:5]
	s_setprio 0
	s_barrier
	s_add_u32 s0, s0, 0x100
	s_addc_u32 s1, s1, 0
	s_add_u32 s44, s44, 0x100
	s_addc_u32 s45, s45, 0
	s_cmp_ge_u32 s47, s40
	s_mov_b32 s46, s47
	s_cbranch_scc0 .LBB0_1373
	s_and_b64 vcc, exec, s[10:11]
	s_cbranch_vccz .LBB0_1376
	s_barrier

; #define PG8_STAGE(bufoff, gbase, voff) do { _Pragma("unroll") for (int _i = 0; _i < 2; ++_i) \
;         __builtin_amdgcn_global_load_lds((const unsigned*)((const char*)(gbase) + (voff)[_i]), (PG8_LAS unsigned*)(lds + (bufoff) + ldsw + _i * 8192), 16, 0, 0); } while (0)
; #define PG8_LDA(dst, b, h) do { _Pragma("unroll") for (int m = 0; m < 4; ++m) _Pragma("unroll") for (int k = 0; k < 2; ++k) dst[m][k] = *(const PG8_LAS bf16x8*)(lds + PG8_SA(b, h) + aoff + m * 2048 + k * 1024); } while (0)
; #define PG8_LDB(dst, b, h) do { _Pragma("unroll") for (int n = 0; n < 2; ++n) _Pragma("unroll") for (int k = 0; k < 2; ++k) dst[n][k] = *(const PG8_LAS bf16x8*)(lds + PG8_SB(b, h) + boff + n * 2048 + k * 1024); } while (0)
; #define PG8_MMA(ai, bj, At, Bt) do { __builtin_amdgcn_s_setprio(1); _Pragma("unroll") for (int m = 0; m < 4; ++m) _Pragma("unroll") for (int n = 0; n < 2; ++n) _Pragma("unroll") for (int k = 0; k < 2; ++k) \
;         acc[ai][bj][m][n] = __builtin_amdgcn_mfma_f32_16x16x32_bf16(Bt[n][k], At[m][k], acc[ai][bj][m][n], 0, 0, 0); __builtin_amdgcn_s_setprio(0); } while (0)
; #define PG8_WAIT_V(n) asm volatile("s_waitcnt vmcnt(" #n ")" ::: "memory")
; #define PG8_BAR __builtin_amdgcn_s_barrier()
; template <class Epi, class Sched, bool ALIGN_EPI = false, bool SP2 = false>
; __device__ __forceinline__ void gemm_phase(PG8_LAS unsigned char* lds, const Gemm g, const Sched& S, const Epi& E) {
;     ...
;         for (int t = 0; t < nt; t += 2) {
;             const bool last = (t == nt - 2);
;             const char* a1 = cA + (size_t)(t + 1) * kstep;
;             const char* a2 = last ? nA : cA + (size_t)(t + 2) * kstep; const char* b2 = last ? nB : cB + (size_t)(t + 2) * kstep;
;             const char* a3 = a2 + kstep; const char* b3 = b2 + kstep;
;             if (last && has_next) S.a_ready(nxt);
;             if constexpr (SP2) {
;             PG8_LDB(B0, 0, 0); PG8_LDB(B1, 0, 1); PG8_SCHED; PG8_LDA(At, 0, 0); PG8_STAGE(PG8_SA(1, 1), a1 + hstep, voffA);
;             PG8_WAIT_V(8); PG8_WAIT_L(0); PG8_BAR; PG8_MMA(0, 0, At, B0); PG8_MMA(0, 1, At, B1); PG8_BAR; PG8_SCHED;
;             PG8_LDA(At, 0, 1); PG8_STAGE(PG8_SB(0, 0), b2, voffB); PG8_STAGE(PG8_SB(0, 1), b2 + hstep, voffB); PG8_STAGE(PG8_SA(0, 0), a2, voffA);
;             PG8_WAIT_V(8); PG8_WAIT_L(0); PG8_BAR; PG8_MMA(1, 0, At, B0); PG8_MMA(1, 1, At, B1); PG8_BAR; PG8_SCHED;
.LBB0_1532:
	ds_read_b128 v[136:139], v143
	ds_read_b128 v[146:149], v143 offset:1024
	ds_read_b128 v[150:153], v143 offset:2048
	ds_read_b128 v[154:157], v143 offset:3072
	ds_read_b128 v[158:161], v144
	ds_read_b128 v[166:169], v144 offset:1024
	ds_read_b128 v[170:173], v144 offset:2048
	ds_read_b128 v[178:181], v144 offset:3072
	s_add_i32 s67, s34, 2
	s_add_u32 s35, s30, 0xffea0080
	s_addc_u32 s36, s31, -1
	s_cmp_eq_u32 s64, s34
	s_cselect_b32 s34, s28, s65
	s_cselect_b32 s37, s27, s36
	s_cselect_b32 s36, s26, s35
	s_cselect_b32 s35, s29, s66
	v_lshl_add_u64 v[216:217], s[30:31], 0, v[130:131]
	s_add_i32 m0, s3, 0xc000
	ds_read_b128 v[182:185], v145
	ds_read_b128 v[186:189], v145 offset:1024
	ds_read_b128 v[190:193], v145 offset:2048
	ds_read_b128 v[194:197], v145 offset:3072
	ds_read_b128 v[198:201], v145 offset:4096
	ds_read_b128 v[202:205], v145 offset:5120
	ds_read_b128 v[206:209], v145 offset:6144
	ds_read_b128 v[210:213], v145 offset:7168
	global_load_lds_dwordx4 v[216:217], off
	v_lshl_add_u64 v[216:217], s[30:31], 0, v[132:133]
	s_add_i32 m0, s3, 0xe000
	s_nop 0
	global_load_lds_dwordx4 v[216:217], off
	s_waitcnt vmcnt(8)
	s_waitcnt lgkmcnt(0)
	s_barrier
	s_setprio 1
	v_mfma_f32_16x16x32_bf16 v[126:129], v[136:139], v[182:185], v[126:129]
	v_mfma_f32_16x16x32_bf16 v[122:125], v[150:153], v[182:185], v[122:125]
	v_mfma_f32_16x16x32_bf16 v[118:121], v[136:139], v[190:193], v[118:121]
	v_mfma_f32_16x16x32_bf16 v[114:117], v[150:153], v[190:193], v[114:117]
	v_mfma_f32_16x16x32_bf16 v[102:105], v[136:139], v[198:201], v[102:105]
	v_mfma_f32_16x16x32_bf16 v[98:101], v[150:153], v[198:201], v[98:101]
	v_mfma_f32_16x16x32_bf16 v[90:93], v[136:139], v[206:209], v[90:93]
	v_mfma_f32_16x16x32_bf16 v[82:85], v[150:153], v[206:209], v[82:85]
	v_mfma_f32_16x16x32_bf16 v[126:129], v[146:149], v[186:189], v[126:129]
	v_mfma_f32_16x16x32_bf16 v[122:125], v[154:157], v[186:189], v[122:125]
	v_mfma_f32_16x16x32_bf16 v[118:121], v[146:149], v[194:197], v[118:121]
	v_mfma_f32_16x16x32_bf16 v[114:117], v[154:157], v[194:197], v[114:117]
	v_mfma_f32_16x16x32_bf16 v[102:105], v[146:149], v[202:205], v[102:105]
	v_mfma_f32_16x16x32_bf16 v[98:101], v[154:157], v[202:205], v[98:101]
	v_mfma_f32_16x16x32_bf16 v[90:93], v[146:149], v[210:213], v[90:93]
	v_mfma_f32_16x16x32_bf16 v[82:85], v[154:157], v[210:213], v[82:85]
	v_mfma_f32_16x16x32_bf16 v[110:113], v[158:161], v[182:185], v[110:113]
	v_mfma_f32_16x16x32_bf16 v[106:109], v[170:173], v[182:185], v[106:109]
	v_mfma_f32_16x16x32_bf16 v[94:97], v[158:161], v[190:193], v[94:97]
	v_mfma_f32_16x16x32_bf16 v[86:89], v[170:173], v[190:193], v[86:89]
	v_mfma_f32_16x16x32_bf16 v[78:81], v[158:161], v[198:201], v[78:81]
	v_mfma_f32_16x16x32_bf16 v[74:77], v[170:173], v[198:201], v[74:77]
	v_mfma_f32_16x16x32_bf16 v[70:73], v[158:161], v[206:209], v[70:73]
	v_mfma_f32_16x16x32_bf16 v[66:69], v[170:173], v[206:209], v[66:69]
	v_mfma_f32_16x16x32_bf16 v[110:113], v[166:169], v[186:189], v[110:113]
	v_mfma_f32_16x16x32_bf16 v[106:109], v[178:181], v[186:189], v[106:109]
	v_mfma_f32_16x16x32_bf16 v[94:97], v[166:169], v[194:197], v[94:97]
	v_mfma_f32_16x16x32_bf16 v[86:89], v[178:181], v[194:197], v[86:89]
	v_mfma_f32_16x16x32_bf16 v[78:81], v[166:169], v[202:205], v[78:81]
	v_mfma_f32_16x16x32_bf16 v[74:77], v[178:181], v[202:205], v[74:77]
	v_mfma_f32_16x16x32_bf16 v[70:73], v[166:169], v[210:213], v[70:73]
	v_mfma_f32_16x16x32_bf16 v[66:69], v[178:181], v[210:213], v[66:69]
	s_setprio 0
	s_barrier
	s_add_i32 s68, s48, s2
	v_lshl_add_u64 v[216:217], s[34:35], 0, v[174:175]
	s_mov_b32 m0, s68
	ds_read_b128 v[182:185], v145 offset:16384
	ds_read_b128 v[186:189], v145 offset:17408
	ds_read_b128 v[190:193], v145 offset:18432
	ds_read_b128 v[194:197], v145 offset:19456
	ds_read_b128 v[198:201], v145 offset:20480
	ds_read_b128 v[202:205], v145 offset:21504
	ds_read_b128 v[206:209], v145 offset:22528
	ds_read_b128 v[210:213], v145 offset:23552
	global_load_lds_dwordx4 v[216:217], off
	s_add_i32 m0, s68, 0x2000
	s_add_u32 s68, s34, 0x160000
	v_lshl_add_u64 v[218:219], s[34:35], 0, v[176:177]
	s_addc_u32 s69, s35, 0
	s_add_i32 s70, s49, s2
	global_load_lds_dwordx4 v[218:219], off
	v_lshl_add_u64 v[220:221], s[68:69], 0, v[174:175]
	s_mov_b32 m0, s70
	v_lshl_add_u64 v[222:223], s[36:37], 0, v[176:177]
	global_load_lds_dwordx4 v[220:221], off
	v_lshl_add_u64 v[220:221], s[68:69], 0, v[176:177]
	s_add_i32 m0, s70, 0x2000
	s_nop 0
	global_load_lds_dwordx4 v[220:221], off
	v_lshl_add_u64 v[220:221], s[36:37], 0, v[174:175]
	s_mov_b32 m0, s3
	s_nop 0
	global_load_lds_dwordx4 v[220:221], off
	s_mov_b32 m0, s33
	s_nop 0
	global_load_lds_dwordx4 v[222:223], off
	s_waitcnt vmcnt(8)
	s_waitcnt lgkmcnt(0)
	s_barrier
; #define PG8_STAGE(bufoff, gbase, voff) do { _Pragma("unroll") for (int _i = 0; _i < 2; ++_i) \
;         __builtin_amdgcn_global_load_lds((const unsigned*)((const char*)(gbase) + (voff)[_i]), (PG8_LAS unsigned*)(lds + (bufoff) + ldsw + _i * 8192), 16, 0, 0); } while (0)
; #define PG8_LDA(dst, b, h) do { _Pragma("unroll") for (int m = 0; m < 4; ++m) _Pragma("unroll") for (int k = 0; k < 2; ++k) dst[m][k] = *(const PG8_LAS bf16x8*)(lds + PG8_SA(b, h) + aoff + m * 2048 + k * 1024); } while (0)
; #define PG8_LDB(dst, b, h) do { _Pragma("unroll") for (int n = 0; n < 2; ++n) _Pragma("unroll") for (int k = 0; k < 2; ++k) dst[n][k] = *(const PG8_LAS bf16x8*)(lds + PG8_SB(b, h) + boff + n * 2048 + k * 1024); } while (0)
; #define PG8_MMA(ai, bj, At, Bt) do { __builtin_amdgcn_s_setprio(1); _Pragma("unroll") for (int m = 0; m < 4; ++m) _Pragma("unroll") for (int n = 0; n < 2; ++n) _Pragma("unroll") for (int k = 0; k < 2; ++k) \
;         acc[ai][bj][m][n] = __builtin_amdgcn_mfma_f32_16x16x32_bf16(Bt[n][k], At[m][k], acc[ai][bj][m][n], 0, 0, 0); __builtin_amdgcn_s_setprio(0); } while (0)
; #define PG8_WAIT_V(n) asm volatile("s_waitcnt vmcnt(" #n ")" ::: "memory")
; #define PG8_WAIT_L(n) asm volatile("s_waitcnt lgkmcnt(" #n ")" ::: "memory")
; #define PG8_BAR __builtin_amdgcn_s_barrier()
; #define PG8_SCHED __builtin_amdgcn_sched_barrier(0)
; template <class Epi, class Sched, bool ALIGN_EPI = false, bool SP2 = false>
; __device__ __forceinline__ void gemm_phase(PG8_LAS unsigned char* lds, const Gemm g, const Sched& S, const Epi& E) {
;     ...
;             PG8_WAIT_V(8); PG8_WAIT_L(0); PG8_BAR; PG8_MMA(1, 0, At, B0); PG8_MMA(1, 1, At, B1); PG8_BAR; PG8_SCHED;
;             PG8_LDB(B0, 1, 0); PG8_LDB(B1, 1, 1); PG8_SCHED; PG8_LDA(At, 1, 0); PG8_STAGE(PG8_SA(0, 1), a2 + hstep, voffA);
;             PG8_WAIT_V(8); PG8_WAIT_L(0); PG8_BAR; PG8_MMA(0, 0, At, B0); PG8_MMA(0, 1, At, B1); PG8_BAR; PG8_SCHED;
	s_setprio 1
	v_mfma_f32_16x16x32_bf16 v[62:65], v[136:139], v[182:185], v[62:65]
	v_mfma_f32_16x16x32_bf16 v[58:61], v[150:153], v[182:185], v[58:61]
	v_mfma_f32_16x16x32_bf16 v[54:57], v[136:139], v[190:193], v[54:57]
	v_mfma_f32_16x16x32_bf16 v[50:53], v[150:153], v[190:193], v[50:53]
	v_mfma_f32_16x16x32_bf16 v[42:45], v[136:139], v[198:201], v[42:45]
	v_mfma_f32_16x16x32_bf16 v[34:37], v[150:153], v[198:201], v[34:37]
	v_mfma_f32_16x16x32_bf16 v[26:29], v[136:139], v[206:209], v[26:29]
	v_mfma_f32_16x16x32_bf16 v[18:21], v[150:153], v[206:209], v[18:21]
	v_mfma_f32_16x16x32_bf16 v[62:65], v[146:149], v[186:189], v[62:65]
	v_mfma_f32_16x16x32_bf16 v[58:61], v[154:157], v[186:189], v[58:61]
	v_mfma_f32_16x16x32_bf16 v[54:57], v[146:149], v[194:197], v[54:57]
	v_mfma_f32_16x16x32_bf16 v[50:53], v[154:157], v[194:197], v[50:53]
	v_mfma_f32_16x16x32_bf16 v[42:45], v[146:149], v[202:205], v[42:45]
	v_mfma_f32_16x16x32_bf16 v[34:37], v[154:157], v[202:205], v[34:37]
	v_mfma_f32_16x16x32_bf16 v[26:29], v[146:149], v[210:213], v[26:29]
	v_mfma_f32_16x16x32_bf16 v[18:21], v[154:157], v[210:213], v[18:21]
	v_mfma_f32_16x16x32_bf16 v[46:49], v[158:161], v[182:185], v[46:49]
	v_mfma_f32_16x16x32_bf16 v[38:41], v[170:173], v[182:185], v[38:41]
	v_mfma_f32_16x16x32_bf16 v[30:33], v[158:161], v[190:193], v[30:33]
	v_mfma_f32_16x16x32_bf16 v[22:25], v[170:173], v[190:193], v[22:25]
	v_mfma_f32_16x16x32_bf16 v[14:17], v[158:161], v[198:201], v[14:17]
	v_mfma_f32_16x16x32_bf16 v[10:13], v[170:173], v[198:201], v[10:13]
	v_mfma_f32_16x16x32_bf16 v[6:9], v[158:161], v[206:209], v[6:9]
	v_mfma_f32_16x16x32_bf16 v[2:5], v[170:173], v[206:209], v[2:5]
	v_mfma_f32_16x16x32_bf16 v[46:49], v[166:169], v[186:189], v[46:49]
	v_mfma_f32_16x16x32_bf16 v[38:41], v[178:181], v[186:189], v[38:41]
	v_mfma_f32_16x16x32_bf16 v[30:33], v[166:169], v[194:197], v[30:33]
	v_mfma_f32_16x16x32_bf16 v[22:25], v[178:181], v[194:197], v[22:25]
	v_mfma_f32_16x16x32_bf16 v[14:17], v[166:169], v[202:205], v[14:17]
	v_mfma_f32_16x16x32_bf16 v[10:13], v[178:181], v[202:205], v[10:13]
	v_mfma_f32_16x16x32_bf16 v[6:9], v[166:169], v[210:213], v[6:9]
	v_mfma_f32_16x16x32_bf16 v[2:5], v[178:181], v[210:213], v[2:5]
	s_setprio 0
	s_barrier
	s_add_i32 s68, 0, 0x18000
	s_add_i32 s69, 0, 0x1c000
	v_add_u32_e32 v154, s68, v141
	v_add_u32_e32 v178, s69, v141
	ds_read_b128 v[136:139], v154
	ds_read_b128 v[146:149], v154 offset:1024
	ds_read_b128 v[150:153], v154 offset:2048
	ds_read_b128 v[154:157], v154 offset:3072
	ds_read_b128 v[158:161], v178
	ds_read_b128 v[166:169], v178 offset:1024
	ds_read_b128 v[170:173], v178 offset:2048
	ds_read_b128 v[178:181], v178 offset:3072
	s_add_u32 s36, s36, 0x160000
	s_addc_u32 s37, s37, 0
	s_mov_b32 m0, s38
	v_lshl_add_u64 v[224:225], s[36:37], 0, v[174:175]
	ds_read_b128 v[182:185], v145 offset:32768
	ds_read_b128 v[186:189], v145 offset:33792
	ds_read_b128 v[190:193], v145 offset:34816
	ds_read_b128 v[194:197], v145 offset:35840
	ds_read_b128 v[198:201], v145 offset:36864
	ds_read_b128 v[202:205], v145 offset:37888
	ds_read_b128 v[206:209], v145 offset:38912
	ds_read_b128 v[210:213], v145 offset:39936
	global_load_lds_dwordx4 v[224:225], off
	v_lshl_add_u64 v[224:225], s[36:37], 0, v[176:177]
	s_mov_b32 m0, s39
	s_nop 0
	global_load_lds_dwordx4 v[224:225], off
	s_waitcnt vmcnt(8)
	s_waitcnt lgkmcnt(0)
	s_barrier
	s_setprio 1
	v_mfma_f32_16x16x32_bf16 v[126:129], v[136:139], v[182:185], v[126:129]
	v_mfma_f32_16x16x32_bf16 v[122:125], v[150:153], v[182:185], v[122:125]
	v_mfma_f32_16x16x32_bf16 v[118:121], v[136:139], v[190:193], v[118:121]
	v_mfma_f32_16x16x32_bf16 v[114:117], v[150:153], v[190:193], v[114:117]
	v_mfma_f32_16x16x32_bf16 v[102:105], v[136:139], v[198:201], v[102:105]
	v_mfma_f32_16x16x32_bf16 v[98:101], v[150:153], v[198:201], v[98:101]
	v_mfma_f32_16x16x32_bf16 v[90:93], v[136:139], v[206:209], v[90:93]
	v_mfma_f32_16x16x32_bf16 v[82:85], v[150:153], v[206:209], v[82:85]
	v_mfma_f32_16x16x32_bf16 v[126:129], v[146:149], v[186:189], v[126:129]
	v_mfma_f32_16x16x32_bf16 v[122:125], v[154:157], v[186:189], v[122:125]
	v_mfma_f32_16x16x32_bf16 v[118:121], v[146:149], v[194:197], v[118:121]
	v_mfma_f32_16x16x32_bf16 v[114:117], v[154:157], v[194:197], v[114:117]
	v_mfma_f32_16x16x32_bf16 v[102:105], v[146:149], v[202:205], v[102:105]
	v_mfma_f32_16x16x32_bf16 v[98:101], v[154:157], v[202:205], v[98:101]
	v_mfma_f32_16x16x32_bf16 v[90:93], v[146:149], v[210:213], v[90:93]
	v_mfma_f32_16x16x32_bf16 v[82:85], v[154:157], v[210:213], v[82:85]
	v_mfma_f32_16x16x32_bf16 v[110:113], v[158:161], v[182:185], v[110:113]
	v_mfma_f32_16x16x32_bf16 v[106:109], v[170:173], v[182:185], v[106:109]
	v_mfma_f32_16x16x32_bf16 v[94:97], v[158:161], v[190:193], v[94:97]
	v_mfma_f32_16x16x32_bf16 v[86:89], v[170:173], v[190:193], v[86:89]
	v_mfma_f32_16x16x32_bf16 v[78:81], v[158:161], v[198:201], v[78:81]
	v_mfma_f32_16x16x32_bf16 v[74:77], v[170:173], v[198:201], v[74:77]
	v_mfma_f32_16x16x32_bf16 v[70:73], v[158:161], v[206:209], v[70:73]
	v_mfma_f32_16x16x32_bf16 v[66:69], v[170:173], v[206:209], v[66:69]
	v_mfma_f32_16x16x32_bf16 v[110:113], v[166:169], v[186:189], v[110:113]
	v_mfma_f32_16x16x32_bf16 v[106:109], v[178:181], v[186:189], v[106:109]
	v_mfma_f32_16x16x32_bf16 v[94:97], v[166:169], v[194:197], v[94:97]
	v_mfma_f32_16x16x32_bf16 v[86:89], v[178:181], v[194:197], v[86:89]
	v_mfma_f32_16x16x32_bf16 v[78:81], v[166:169], v[202:205], v[78:81]
	v_mfma_f32_16x16x32_bf16 v[74:77], v[178:181], v[202:205], v[74:77]
	v_mfma_f32_16x16x32_bf16 v[70:73], v[166:169], v[210:213], v[70:73]
	v_mfma_f32_16x16x32_bf16 v[66:69], v[178:181], v[210:213], v[66:69]
	s_setprio 0
	s_barrier
; #define PG8_STAGE(bufoff, gbase, voff) do { _Pragma("unroll") for (int _i = 0; _i < 2; ++_i) \
;         __builtin_amdgcn_global_load_lds((const unsigned*)((const char*)(gbase) + (voff)[_i]), (PG8_LAS unsigned*)(lds + (bufoff) + ldsw + _i * 8192), 16, 0, 0); } while (0)
; #define PG8_LDA(dst, b, h) do { _Pragma("unroll") for (int m = 0; m < 4; ++m) _Pragma("unroll") for (int k = 0; k < 2; ++k) dst[m][k] = *(const PG8_LAS bf16x8*)(lds + PG8_SA(b, h) + aoff + m * 2048 + k * 1024); } while (0)
; #define PG8_WAIT_V(n) asm volatile("s_waitcnt vmcnt(" #n ")" ::: "memory")
; template <class Epi, class Sched, bool ALIGN_EPI = false, bool SP2 = false>
; __device__ __forceinline__ void gemm_phase(PG8_LAS unsigned char* lds, const Gemm g, const Sched& S, const Epi& E) {
;     ...
;             PG8_LDA(At, 1, 1); PG8_STAGE(PG8_SB(1, 0), b3, voffB); PG8_STAGE(PG8_SB(1, 1), b3 + hstep, voffB); PG8_STAGE(PG8_SA(1, 0), a3, voffA);
;             PG8_WAIT_V(8); PG8_WAIT_L(0); PG8_BAR; PG8_MMA(1, 0, At, B0); PG8_MMA(1, 1, At, B1); PG8_BAR; PG8_SCHED;
;             } else {
;             PG8_LDB(B0, 0, 0); PG8_SCHED; PG8_LDA(At, 0, 0); PG8_STAGE(PG8_SA(1, 1), a1 + hstep, voffA);
;             PG8_WAIT_L(8); PG8_BAR; PG8_WAIT_L(0); PG8_MMA(0, 0, At, B0); PG8_BAR; PG8_SCHED;
;             PG8_LDB(B1, 0, 1); PG8_STAGE(PG8_SB(0, 0), b2, voffB);
;             PG8_BAR; PG8_WAIT_L(0); PG8_MMA(0, 1, At, B1); PG8_BAR;
;             PG8_LDA(At, 0, 1); PG8_STAGE(PG8_SA(0, 0), a2, voffA);
;             PG8_BAR; PG8_WAIT_L(0); PG8_MMA(1, 0, At, B0); PG8_BAR; PG8_SCHED;
;             PG8_STAGE(PG8_SB(0, 1), b2 + hstep, voffB);
;             PG8_WAIT_V(6); PG8_BAR; PG8_MMA(1, 1, At, B1); PG8_BAR;
;             PG8_LDB(B0, 1, 0); PG8_SCHED; PG8_LDA(At, 1, 0); PG8_STAGE(PG8_SA(0, 1), a2 + hstep, voffA);
;             PG8_WAIT_L(8); PG8_BAR; PG8_WAIT_L(0); PG8_MMA(0, 0, At, B0); PG8_BAR; PG8_SCHED;
;             PG8_LDB(B1, 1, 1); PG8_STAGE(PG8_SB(1, 0), b3, voffB);
;             PG8_BAR; PG8_WAIT_L(0); PG8_MMA(0, 1, At, B1); PG8_BAR;
;             PG8_LDA(At, 1, 1); PG8_STAGE(PG8_SA(1, 0), a3, voffA);
;             PG8_BAR; PG8_WAIT_L(0); PG8_MMA(1, 0, At, B0); PG8_BAR; PG8_SCHED;
;             PG8_STAGE(PG8_SB(1, 1), b3 + hstep, voffB);
;             PG8_WAIT_V(6); PG8_BAR; PG8_MMA(1, 1, At, B1); PG8_BAR;
;             }
;         }
;         if constexpr (ALIGN_EPI) { if (wr == 0) PG8_BAR; }
	s_add_i32 s36, s68, s2
	v_lshl_add_u64 v[216:217], v[216:217], 0, s[8:9]
	s_mov_b32 m0, s36
	ds_read_b128 v[182:185], v145 offset:49152
	ds_read_b128 v[186:189], v145 offset:50176
	ds_read_b128 v[190:193], v145 offset:51200
	ds_read_b128 v[194:197], v145 offset:52224
	ds_read_b128 v[198:201], v145 offset:53248
	ds_read_b128 v[202:205], v145 offset:54272
	ds_read_b128 v[206:209], v145 offset:55296
	ds_read_b128 v[210:213], v145 offset:56320
	global_load_lds_dwordx4 v[216:217], off
	s_add_i32 m0, s36, 0x2000
	s_add_u32 s34, s34, 0x160080
	v_lshl_add_u64 v[216:217], v[218:219], 0, s[8:9]
	s_addc_u32 s35, s35, 0
	s_add_i32 s36, s69, s2
	global_load_lds_dwordx4 v[216:217], off
	v_lshl_add_u64 v[216:217], s[34:35], 0, v[174:175]
	s_mov_b32 m0, s36
	s_nop 0
	global_load_lds_dwordx4 v[216:217], off
	v_lshl_add_u64 v[216:217], s[34:35], 0, v[176:177]
	s_add_i32 m0, s36, 0x2000
	s_nop 0
	global_load_lds_dwordx4 v[216:217], off
	v_lshl_add_u64 v[216:217], v[220:221], 0, s[8:9]
	s_mov_b32 m0, s40
	s_nop 0
	global_load_lds_dwordx4 v[216:217], off
	v_lshl_add_u64 v[216:217], v[222:223], 0, s[8:9]
	s_mov_b32 m0, s41
	s_nop 0
	global_load_lds_dwordx4 v[216:217], off
	s_waitcnt vmcnt(8)
	s_waitcnt lgkmcnt(0)
	s_barrier
	s_setprio 1
	v_mfma_f32_16x16x32_bf16 v[62:65], v[136:139], v[182:185], v[62:65]
	v_mfma_f32_16x16x32_bf16 v[58:61], v[150:153], v[182:185], v[58:61]
	v_mfma_f32_16x16x32_bf16 v[54:57], v[136:139], v[190:193], v[54:57]
	v_mfma_f32_16x16x32_bf16 v[50:53], v[150:153], v[190:193], v[50:53]
	v_mfma_f32_16x16x32_bf16 v[42:45], v[136:139], v[198:201], v[42:45]
	v_mfma_f32_16x16x32_bf16 v[34:37], v[150:153], v[198:201], v[34:37]
	v_mfma_f32_16x16x32_bf16 v[26:29], v[136:139], v[206:209], v[26:29]
	v_mfma_f32_16x16x32_bf16 v[18:21], v[150:153], v[206:209], v[18:21]
	v_mfma_f32_16x16x32_bf16 v[62:65], v[146:149], v[186:189], v[62:65]
	v_mfma_f32_16x16x32_bf16 v[58:61], v[154:157], v[186:189], v[58:61]
	v_mfma_f32_16x16x32_bf16 v[54:57], v[146:149], v[194:197], v[54:57]
	v_mfma_f32_16x16x32_bf16 v[50:53], v[154:157], v[194:197], v[50:53]
	v_mfma_f32_16x16x32_bf16 v[42:45], v[146:149], v[202:205], v[42:45]
	v_mfma_f32_16x16x32_bf16 v[34:37], v[154:157], v[202:205], v[34:37]
	v_mfma_f32_16x16x32_bf16 v[26:29], v[146:149], v[210:213], v[26:29]
	v_mfma_f32_16x16x32_bf16 v[18:21], v[154:157], v[210:213], v[18:21]
	v_mfma_f32_16x16x32_bf16 v[46:49], v[158:161], v[182:185], v[46:49]
	v_mfma_f32_16x16x32_bf16 v[38:41], v[170:173], v[182:185], v[38:41]
	v_mfma_f32_16x16x32_bf16 v[30:33], v[158:161], v[190:193], v[30:33]
	v_mfma_f32_16x16x32_bf16 v[22:25], v[170:173], v[190:193], v[22:25]
	v_mfma_f32_16x16x32_bf16 v[14:17], v[158:161], v[198:201], v[14:17]
	v_mfma_f32_16x16x32_bf16 v[10:13], v[170:173], v[198:201], v[10:13]
	v_mfma_f32_16x16x32_bf16 v[6:9], v[158:161], v[206:209], v[6:9]
	v_mfma_f32_16x16x32_bf16 v[2:5], v[170:173], v[206:209], v[2:5]
	v_mfma_f32_16x16x32_bf16 v[46:49], v[166:169], v[186:189], v[46:49]
	v_mfma_f32_16x16x32_bf16 v[38:41], v[178:181], v[186:189], v[38:41]
	v_mfma_f32_16x16x32_bf16 v[30:33], v[166:169], v[194:197], v[30:33]
	v_mfma_f32_16x16x32_bf16 v[22:25], v[178:181], v[194:197], v[22:25]
	v_mfma_f32_16x16x32_bf16 v[14:17], v[166:169], v[202:205], v[14:17]
	v_mfma_f32_16x16x32_bf16 v[10:13], v[178:181], v[202:205], v[10:13]
	v_mfma_f32_16x16x32_bf16 v[6:9], v[166:169], v[210:213], v[6:9]
	v_mfma_f32_16x16x32_bf16 v[2:5], v[178:181], v[210:213], v[2:5]
	s_setprio 0
	s_barrier
	s_add_u32 s30, s30, 0x100
	s_addc_u32 s31, s31, 0
	s_add_u32 s65, s65, 0x100
	s_addc_u32 s66, s66, 0
	s_cmp_ge_u32 s67, s59
	s_mov_b32 s34, s67
	s_cbranch_scc0 .LBB0_1532
	s_and_b64 vcc, exec, s[10:11]
	s_cbranch_vccz .LBB0_1535
	s_barrier
